# K-loop load-phase exits: s_waitcnt vmcnt(N) and s_waitcnt lgkmcnt(0) merged into one s_waitcnt (one fewer instruction before each phase barrier)
# speedup vs baseline: 1.0016x; 1.0016x over previous
.LBB0_444:
	s_lshl_b32 s100, s24, 3
	s_or_b32 s100, s100, s70
	s_ashr_i32 s101, s100, 31
	s_lshl_b64 s[100:101], s[100:101], 2
	s_add_u32 s100, s26, s100
	s_addc_u32 s101, s69, s101
	global_load_dword v232, v1, s[100:101] sc1
	global_load_dword v233, v1, s[100:101] offset:16 sc1
	s_add_u32 s48, s46, 0x20080
	s_addc_u32 s49, s47, 0
	s_add_u32 s25, s50, 0x100
	s_addc_u32 s64, s51, 0
	s_mov_b32 s65, -2
	s_add_u32 s46, s48, 0xfffe0080
	s_addc_u32 s47, s49, -1
	s_add_i32 s84, 0, 0x10000
	s_cmp_eq_u32 s65, 4
	s_cselect_b32 s47, s15, s47
	s_cselect_b32 s46, s14, s46
	v_add_u32_e32 v0, s84, v147
	s_cselect_b32 s51, s17, s64
	s_cselect_b32 s50, s16, s25
	s_add_i32 s86, 0, 0x14000
	ds_read_b128 v[150:153], v0
	ds_read_b128 v[154:157], v0 offset:1024
	ds_read_b128 v[158:161], v0 offset:2048
	ds_read_b128 v[162:165], v0 offset:3072
	ds_read_b128 v[166:169], v0 offset:16384
	ds_read_b128 v[170:173], v0 offset:17408
	ds_read_b128 v[174:177], v0 offset:18432
	ds_read_b128 v[178:181], v0 offset:19456
	ds_read_b128 v[182:185], v148
	ds_read_b128 v[186:189], v148 offset:1024
	ds_read_b128 v[190:193], v148 offset:2048
	ds_read_b128 v[194:197], v148 offset:3072
	ds_read_b128 v[198:201], v148 offset:4096
	ds_read_b128 v[202:205], v148 offset:5120
	ds_read_b128 v[206:209], v148 offset:6144
	ds_read_b128 v[210:213], v148 offset:7168
	s_add_i32 m0, s59, 0xc000
	s_nop 0
	global_load_lds_dwordx4 v132, s[48:49]
	s_add_i32 m0, s59, 0xe000
	s_nop 0
	global_load_lds_dwordx4 v133, s[48:49]
	s_waitcnt vmcnt(8) lgkmcnt(0)
	s_setprio 1
	s_barrier
	v_mfma_i32_16x16x64_i8 v[126:129], v[150:153], v[182:185], 0
	v_mfma_i32_16x16x64_i8 v[122:125], v[158:161], v[182:185], 0
	v_mfma_i32_16x16x64_i8 v[110:113], v[150:153], v[190:193], 0
	v_mfma_i32_16x16x64_i8 v[106:109], v[158:161], v[190:193], 0
	v_mfma_i32_16x16x64_i8 v[94:97], v[150:153], v[198:201], 0
	v_mfma_i32_16x16x64_i8 v[90:93], v[158:161], v[198:201], 0
	v_mfma_i32_16x16x64_i8 v[78:81], v[150:153], v[206:209], 0
	v_mfma_i32_16x16x64_i8 v[74:77], v[158:161], v[206:209], 0
	v_mfma_i32_16x16x64_i8 v[126:129], v[154:157], v[186:189], v[126:129]
	v_mfma_i32_16x16x64_i8 v[122:125], v[162:165], v[186:189], v[122:125]
	v_mfma_i32_16x16x64_i8 v[110:113], v[154:157], v[194:197], v[110:113]
	v_mfma_i32_16x16x64_i8 v[106:109], v[162:165], v[194:197], v[106:109]
	v_mfma_i32_16x16x64_i8 v[94:97], v[154:157], v[202:205], v[94:97]
	v_mfma_i32_16x16x64_i8 v[90:93], v[162:165], v[202:205], v[90:93]
	v_mfma_i32_16x16x64_i8 v[78:81], v[154:157], v[210:213], v[78:81]
	v_mfma_i32_16x16x64_i8 v[74:77], v[162:165], v[210:213], v[74:77]
	s_setprio 0
	s_setprio 1
	v_mfma_i32_16x16x64_i8 v[118:121], v[166:169], v[182:185], 0
	v_mfma_i32_16x16x64_i8 v[114:117], v[174:177], v[182:185], 0
	v_mfma_i32_16x16x64_i8 v[102:105], v[166:169], v[190:193], 0
	v_mfma_i32_16x16x64_i8 v[98:101], v[174:177], v[190:193], 0
	v_mfma_i32_16x16x64_i8 v[86:89], v[166:169], v[198:201], 0
	v_mfma_i32_16x16x64_i8 v[82:85], v[174:177], v[198:201], 0
	v_mfma_i32_16x16x64_i8 v[70:73], v[166:169], v[206:209], 0
	v_mfma_i32_16x16x64_i8 v[66:69], v[174:177], v[206:209], 0
	v_mfma_i32_16x16x64_i8 v[118:121], v[170:173], v[186:189], v[118:121]
	v_mfma_i32_16x16x64_i8 v[114:117], v[178:181], v[186:189], v[114:117]
	v_mfma_i32_16x16x64_i8 v[102:105], v[170:173], v[194:197], v[102:105]
	v_mfma_i32_16x16x64_i8 v[98:101], v[178:181], v[194:197], v[98:101]
	v_mfma_i32_16x16x64_i8 v[86:89], v[170:173], v[202:205], v[86:89]
	v_mfma_i32_16x16x64_i8 v[82:85], v[178:181], v[202:205], v[82:85]
	v_mfma_i32_16x16x64_i8 v[70:73], v[170:173], v[210:213], v[70:73]
	v_mfma_i32_16x16x64_i8 v[66:69], v[178:181], v[210:213], v[66:69]
	s_setprio 0
	s_barrier
	s_add_i32 s84, s84, s40
	ds_read_b128 v[182:185], v148 offset:16384
	ds_read_b128 v[186:189], v148 offset:17408
	ds_read_b128 v[190:193], v148 offset:18432
	ds_read_b128 v[194:197], v148 offset:19456
	ds_read_b128 v[198:201], v148 offset:20480
	ds_read_b128 v[202:205], v148 offset:21504
	ds_read_b128 v[206:209], v148 offset:22528
	ds_read_b128 v[210:213], v148 offset:23552
	s_mov_b32 m0, s84
	s_nop 0
	global_load_lds_dwordx4 v143, s[50:51]
	s_add_i32 m0, s84, 0x2000
	s_add_u32 s84, s50, 0x20000
	global_load_lds_dwordx4 v144, s[50:51]
	s_addc_u32 s85, s51, 0
	s_add_i32 s86, s86, s40
	s_mov_b32 m0, s86
	s_nop 0
	global_load_lds_dwordx4 v143, s[84:85]
	s_add_i32 m0, s86, 0x2000
	s_nop 0
	global_load_lds_dwordx4 v144, s[84:85]
	s_mov_b32 m0, s59
	s_nop 0
	global_load_lds_dwordx4 v132, s[46:47]
	s_mov_b32 m0, s60
	s_nop 0
	global_load_lds_dwordx4 v133, s[46:47]
	s_waitcnt vmcnt(8) lgkmcnt(0)
	s_setprio 1
	s_barrier
	v_mfma_i32_16x16x64_i8 v[62:65], v[150:153], v[182:185], 0
	v_mfma_i32_16x16x64_i8 v[58:61], v[158:161], v[182:185], 0
	v_mfma_i32_16x16x64_i8 v[46:49], v[150:153], v[190:193], 0
	v_mfma_i32_16x16x64_i8 v[42:45], v[158:161], v[190:193], 0
	v_mfma_i32_16x16x64_i8 v[30:33], v[150:153], v[198:201], 0
	v_mfma_i32_16x16x64_i8 v[26:29], v[158:161], v[198:201], 0
	v_mfma_i32_16x16x64_i8 v[14:17], v[150:153], v[206:209], 0
	v_mfma_i32_16x16x64_i8 v[10:13], v[158:161], v[206:209], 0
	v_mfma_i32_16x16x64_i8 v[62:65], v[154:157], v[186:189], v[62:65]
	v_mfma_i32_16x16x64_i8 v[58:61], v[162:165], v[186:189], v[58:61]
	v_mfma_i32_16x16x64_i8 v[46:49], v[154:157], v[194:197], v[46:49]
	v_mfma_i32_16x16x64_i8 v[42:45], v[162:165], v[194:197], v[42:45]
	v_mfma_i32_16x16x64_i8 v[30:33], v[154:157], v[202:205], v[30:33]
	v_mfma_i32_16x16x64_i8 v[26:29], v[162:165], v[202:205], v[26:29]
	v_mfma_i32_16x16x64_i8 v[14:17], v[154:157], v[210:213], v[14:17]
	v_mfma_i32_16x16x64_i8 v[10:13], v[162:165], v[210:213], v[10:13]
	s_setprio 0
	s_setprio 1
	v_mfma_i32_16x16x64_i8 v[54:57], v[166:169], v[182:185], 0
	v_mfma_i32_16x16x64_i8 v[50:53], v[174:177], v[182:185], 0
	v_mfma_i32_16x16x64_i8 v[38:41], v[166:169], v[190:193], 0
	v_mfma_i32_16x16x64_i8 v[34:37], v[174:177], v[190:193], 0
	v_mfma_i32_16x16x64_i8 v[22:25], v[166:169], v[198:201], 0
	v_mfma_i32_16x16x64_i8 v[18:21], v[174:177], v[198:201], 0
	v_mfma_i32_16x16x64_i8 v[6:9], v[166:169], v[206:209], 0
	v_mfma_i32_16x16x64_i8 v[2:5], v[174:177], v[206:209], 0
	v_mfma_i32_16x16x64_i8 v[54:57], v[170:173], v[186:189], v[54:57]
	v_mfma_i32_16x16x64_i8 v[50:53], v[178:181], v[186:189], v[50:53]
	v_mfma_i32_16x16x64_i8 v[38:41], v[170:173], v[194:197], v[38:41]
	v_mfma_i32_16x16x64_i8 v[34:37], v[178:181], v[194:197], v[34:37]
	v_mfma_i32_16x16x64_i8 v[22:25], v[170:173], v[202:205], v[22:25]
	v_mfma_i32_16x16x64_i8 v[18:21], v[178:181], v[202:205], v[18:21]
	v_mfma_i32_16x16x64_i8 v[6:9], v[170:173], v[210:213], v[6:9]
	v_mfma_i32_16x16x64_i8 v[2:5], v[178:181], v[210:213], v[2:5]
	s_setprio 0
	s_barrier
	s_add_i32 s86, 0, 0x18000
	s_add_i32 s87, 0, 0x1c000
	ds_read_b128 v[150:153], v0 offset:32768
	ds_read_b128 v[154:157], v0 offset:33792
	ds_read_b128 v[158:161], v0 offset:34816
	ds_read_b128 v[162:165], v0 offset:35840
	ds_read_b128 v[166:169], v0 offset:49152
	ds_read_b128 v[170:173], v0 offset:50176
	ds_read_b128 v[174:177], v0 offset:51200
	ds_read_b128 v[178:181], v0 offset:52224
	s_add_u32 s84, s46, 0x20000
	s_mov_b32 m0, s61
	ds_read_b128 v[182:185], v148 offset:32768
	ds_read_b128 v[186:189], v148 offset:33792
	ds_read_b128 v[190:193], v148 offset:34816
	ds_read_b128 v[194:197], v148 offset:35840
	ds_read_b128 v[198:201], v148 offset:36864
	ds_read_b128 v[202:205], v148 offset:37888
	ds_read_b128 v[206:209], v148 offset:38912
	ds_read_b128 v[210:213], v148 offset:39936
	s_addc_u32 s85, s47, 0
	s_nop 0
	global_load_lds_dwordx4 v132, s[84:85]
	s_mov_b32 m0, s66
	s_nop 0
	global_load_lds_dwordx4 v133, s[84:85]
	s_waitcnt vmcnt(8) lgkmcnt(0)
	s_setprio 1
	s_barrier
	v_mfma_i32_16x16x64_i8 v[126:129], v[150:153], v[182:185], v[126:129]
	v_mfma_i32_16x16x64_i8 v[122:125], v[158:161], v[182:185], v[122:125]
	v_mfma_i32_16x16x64_i8 v[110:113], v[150:153], v[190:193], v[110:113]
	v_mfma_i32_16x16x64_i8 v[106:109], v[158:161], v[190:193], v[106:109]
	v_mfma_i32_16x16x64_i8 v[94:97], v[150:153], v[198:201], v[94:97]
	v_mfma_i32_16x16x64_i8 v[90:93], v[158:161], v[198:201], v[90:93]
	v_mfma_i32_16x16x64_i8 v[78:81], v[150:153], v[206:209], v[78:81]
	v_mfma_i32_16x16x64_i8 v[74:77], v[158:161], v[206:209], v[74:77]
	v_mfma_i32_16x16x64_i8 v[126:129], v[154:157], v[186:189], v[126:129]
	v_mfma_i32_16x16x64_i8 v[122:125], v[162:165], v[186:189], v[122:125]
	v_mfma_i32_16x16x64_i8 v[110:113], v[154:157], v[194:197], v[110:113]
	v_mfma_i32_16x16x64_i8 v[106:109], v[162:165], v[194:197], v[106:109]
	v_mfma_i32_16x16x64_i8 v[94:97], v[154:157], v[202:205], v[94:97]
	v_mfma_i32_16x16x64_i8 v[90:93], v[162:165], v[202:205], v[90:93]
	v_mfma_i32_16x16x64_i8 v[78:81], v[154:157], v[210:213], v[78:81]
	v_mfma_i32_16x16x64_i8 v[74:77], v[162:165], v[210:213], v[74:77]
	s_setprio 0
	s_setprio 1
	v_mfma_i32_16x16x64_i8 v[118:121], v[166:169], v[182:185], v[118:121]
	v_mfma_i32_16x16x64_i8 v[114:117], v[174:177], v[182:185], v[114:117]
	v_mfma_i32_16x16x64_i8 v[102:105], v[166:169], v[190:193], v[102:105]
	v_mfma_i32_16x16x64_i8 v[98:101], v[174:177], v[190:193], v[98:101]
	v_mfma_i32_16x16x64_i8 v[86:89], v[166:169], v[198:201], v[86:89]
	v_mfma_i32_16x16x64_i8 v[82:85], v[174:177], v[198:201], v[82:85]
	v_mfma_i32_16x16x64_i8 v[70:73], v[166:169], v[206:209], v[70:73]
	v_mfma_i32_16x16x64_i8 v[66:69], v[174:177], v[206:209], v[66:69]
	v_mfma_i32_16x16x64_i8 v[118:121], v[170:173], v[186:189], v[118:121]
	v_mfma_i32_16x16x64_i8 v[114:117], v[178:181], v[186:189], v[114:117]
	v_mfma_i32_16x16x64_i8 v[102:105], v[170:173], v[194:197], v[102:105]
	v_mfma_i32_16x16x64_i8 v[98:101], v[178:181], v[194:197], v[98:101]
	v_mfma_i32_16x16x64_i8 v[86:89], v[170:173], v[202:205], v[86:89]
	v_mfma_i32_16x16x64_i8 v[82:85], v[178:181], v[202:205], v[82:85]
	v_mfma_i32_16x16x64_i8 v[70:73], v[170:173], v[210:213], v[70:73]
	v_mfma_i32_16x16x64_i8 v[66:69], v[178:181], v[210:213], v[66:69]
	s_setprio 0
	s_barrier
	ds_read_b128 v[182:185], v148 offset:49152
	ds_read_b128 v[186:189], v148 offset:50176
	ds_read_b128 v[190:193], v148 offset:51200
	ds_read_b128 v[194:197], v148 offset:52224
	ds_read_b128 v[198:201], v148 offset:53248
	ds_read_b128 v[202:205], v148 offset:54272
	ds_read_b128 v[206:209], v148 offset:55296
	ds_read_b128 v[210:213], v148 offset:56320
	s_add_i32 s84, s86, s40
	s_add_u32 s100, s50, s38
	s_addc_u32 s101, s51, s39
	s_mov_b32 m0, s84
	s_nop 0
	global_load_lds_dwordx4 v143, s[100:101]
	s_add_i32 m0, s84, 0x2000
	s_nop 0
	s_add_u32 s50, s50, 0x20080
	s_addc_u32 s51, s51, 0
	s_add_i32 s84, s87, s40
	global_load_lds_dwordx4 v144, s[100:101]
	s_mov_b32 m0, s84
	s_nop 0
	global_load_lds_dwordx4 v143, s[50:51]
	s_add_i32 m0, s84, 0x2000
	s_nop 0
	global_load_lds_dwordx4 v144, s[50:51]
	s_mov_b32 m0, s75
	s_add_u32 s100, s46, s38
	s_addc_u32 s101, s47, s39
	v_mov_b32_e32 v0, v133
	global_load_lds_dwordx4 v132, s[100:101]
	s_mov_b32 m0, s78
	s_nop 0
	global_load_lds_dwordx4 v133, s[100:101]
	s_waitcnt vmcnt(8) lgkmcnt(0)
	s_setprio 1
	s_barrier
	v_mfma_i32_16x16x64_i8 v[62:65], v[150:153], v[182:185], v[62:65]
	v_mfma_i32_16x16x64_i8 v[58:61], v[158:161], v[182:185], v[58:61]
	v_mfma_i32_16x16x64_i8 v[46:49], v[150:153], v[190:193], v[46:49]
	v_mfma_i32_16x16x64_i8 v[42:45], v[158:161], v[190:193], v[42:45]
	v_mfma_i32_16x16x64_i8 v[30:33], v[150:153], v[198:201], v[30:33]
	v_mfma_i32_16x16x64_i8 v[26:29], v[158:161], v[198:201], v[26:29]
	v_mfma_i32_16x16x64_i8 v[14:17], v[150:153], v[206:209], v[14:17]
	v_mfma_i32_16x16x64_i8 v[10:13], v[158:161], v[206:209], v[10:13]
	v_mfma_i32_16x16x64_i8 v[62:65], v[154:157], v[186:189], v[62:65]
	v_mfma_i32_16x16x64_i8 v[58:61], v[162:165], v[186:189], v[58:61]
	v_mfma_i32_16x16x64_i8 v[46:49], v[154:157], v[194:197], v[46:49]
	v_mfma_i32_16x16x64_i8 v[42:45], v[162:165], v[194:197], v[42:45]
	v_mfma_i32_16x16x64_i8 v[30:33], v[154:157], v[202:205], v[30:33]
	v_mfma_i32_16x16x64_i8 v[26:29], v[162:165], v[202:205], v[26:29]
	v_mfma_i32_16x16x64_i8 v[14:17], v[154:157], v[210:213], v[14:17]
	v_mfma_i32_16x16x64_i8 v[10:13], v[162:165], v[210:213], v[10:13]
	s_setprio 0
	s_setprio 1
	v_mfma_i32_16x16x64_i8 v[54:57], v[166:169], v[182:185], v[54:57]
	v_mfma_i32_16x16x64_i8 v[50:53], v[174:177], v[182:185], v[50:53]
	v_mfma_i32_16x16x64_i8 v[38:41], v[166:169], v[190:193], v[38:41]
	v_mfma_i32_16x16x64_i8 v[34:37], v[174:177], v[190:193], v[34:37]
	v_mfma_i32_16x16x64_i8 v[22:25], v[166:169], v[198:201], v[22:25]
	v_mfma_i32_16x16x64_i8 v[18:21], v[174:177], v[198:201], v[18:21]
	v_mfma_i32_16x16x64_i8 v[6:9], v[166:169], v[206:209], v[6:9]
	v_mfma_i32_16x16x64_i8 v[2:5], v[174:177], v[206:209], v[2:5]
	v_mfma_i32_16x16x64_i8 v[54:57], v[170:173], v[186:189], v[54:57]
	v_mfma_i32_16x16x64_i8 v[50:53], v[178:181], v[186:189], v[50:53]
	v_mfma_i32_16x16x64_i8 v[38:41], v[170:173], v[194:197], v[38:41]
	v_mfma_i32_16x16x64_i8 v[34:37], v[178:181], v[194:197], v[34:37]
	v_mfma_i32_16x16x64_i8 v[22:25], v[170:173], v[202:205], v[22:25]
	v_mfma_i32_16x16x64_i8 v[18:21], v[178:181], v[202:205], v[18:21]
	v_mfma_i32_16x16x64_i8 v[6:9], v[170:173], v[210:213], v[6:9]
	v_mfma_i32_16x16x64_i8 v[2:5], v[178:181], v[210:213], v[2:5]
	s_setprio 0
	s_barrier
	s_add_i32 s65, s65, 2
	s_add_u32 s48, s48, 0x100
	s_addc_u32 s49, s49, 0
	s_add_u32 s25, s25, 0x100
	s_addc_u32 s64, s64, 0
	s_cmp_gt_u32 s65, 5
	s_cbranch_scc0 .LBB0_445
	s_branch .Lpeel_exit_445
	.p2align	6
.LBB0_445:
	s_add_u32 s46, s48, 0xfffe0080
	s_addc_u32 s47, s49, -1
	s_add_i32 s84, 0, 0x10000
	s_cmp_eq_u32 s65, 4
	s_cselect_b32 s47, s15, s47
	s_cselect_b32 s46, s14, s46
	v_add_u32_e32 v0, s84, v147
	s_cselect_b32 s51, s17, s64
	s_cselect_b32 s50, s16, s25
	s_add_i32 s86, 0, 0x14000
	ds_read_b128 v[150:153], v0
	ds_read_b128 v[154:157], v0 offset:1024
	ds_read_b128 v[158:161], v0 offset:2048
	ds_read_b128 v[162:165], v0 offset:3072
	ds_read_b128 v[166:169], v0 offset:16384
	ds_read_b128 v[170:173], v0 offset:17408
	ds_read_b128 v[174:177], v0 offset:18432
	ds_read_b128 v[178:181], v0 offset:19456
	ds_read_b128 v[182:185], v148
	ds_read_b128 v[186:189], v148 offset:1024
	ds_read_b128 v[190:193], v148 offset:2048
	ds_read_b128 v[194:197], v148 offset:3072
	ds_read_b128 v[198:201], v148 offset:4096
	ds_read_b128 v[202:205], v148 offset:5120
	ds_read_b128 v[206:209], v148 offset:6144
	ds_read_b128 v[210:213], v148 offset:7168
	s_add_i32 m0, s59, 0xc000
	s_nop 0
	global_load_lds_dwordx4 v132, s[48:49]
	s_add_i32 m0, s59, 0xe000
	s_nop 0
	global_load_lds_dwordx4 v133, s[48:49]
	s_waitcnt vmcnt(8) lgkmcnt(0)
	s_setprio 1
	s_barrier
	v_mfma_i32_16x16x64_i8 v[126:129], v[150:153], v[182:185], v[126:129]
	v_mfma_i32_16x16x64_i8 v[122:125], v[158:161], v[182:185], v[122:125]
	v_mfma_i32_16x16x64_i8 v[110:113], v[150:153], v[190:193], v[110:113]
	v_mfma_i32_16x16x64_i8 v[106:109], v[158:161], v[190:193], v[106:109]
	v_mfma_i32_16x16x64_i8 v[94:97], v[150:153], v[198:201], v[94:97]
	v_mfma_i32_16x16x64_i8 v[90:93], v[158:161], v[198:201], v[90:93]
	v_mfma_i32_16x16x64_i8 v[78:81], v[150:153], v[206:209], v[78:81]
	v_mfma_i32_16x16x64_i8 v[74:77], v[158:161], v[206:209], v[74:77]
	v_mfma_i32_16x16x64_i8 v[126:129], v[154:157], v[186:189], v[126:129]
	v_mfma_i32_16x16x64_i8 v[122:125], v[162:165], v[186:189], v[122:125]
	v_mfma_i32_16x16x64_i8 v[110:113], v[154:157], v[194:197], v[110:113]
	v_mfma_i32_16x16x64_i8 v[106:109], v[162:165], v[194:197], v[106:109]
	v_mfma_i32_16x16x64_i8 v[94:97], v[154:157], v[202:205], v[94:97]
	v_mfma_i32_16x16x64_i8 v[90:93], v[162:165], v[202:205], v[90:93]
	v_mfma_i32_16x16x64_i8 v[78:81], v[154:157], v[210:213], v[78:81]
	v_mfma_i32_16x16x64_i8 v[74:77], v[162:165], v[210:213], v[74:77]
	s_setprio 0
	s_setprio 1
	v_mfma_i32_16x16x64_i8 v[118:121], v[166:169], v[182:185], v[118:121]
	v_mfma_i32_16x16x64_i8 v[114:117], v[174:177], v[182:185], v[114:117]
	v_mfma_i32_16x16x64_i8 v[102:105], v[166:169], v[190:193], v[102:105]
	v_mfma_i32_16x16x64_i8 v[98:101], v[174:177], v[190:193], v[98:101]
	v_mfma_i32_16x16x64_i8 v[86:89], v[166:169], v[198:201], v[86:89]
	v_mfma_i32_16x16x64_i8 v[82:85], v[174:177], v[198:201], v[82:85]
	v_mfma_i32_16x16x64_i8 v[70:73], v[166:169], v[206:209], v[70:73]
	v_mfma_i32_16x16x64_i8 v[66:69], v[174:177], v[206:209], v[66:69]
	v_mfma_i32_16x16x64_i8 v[118:121], v[170:173], v[186:189], v[118:121]
	v_mfma_i32_16x16x64_i8 v[114:117], v[178:181], v[186:189], v[114:117]
	v_mfma_i32_16x16x64_i8 v[102:105], v[170:173], v[194:197], v[102:105]
	v_mfma_i32_16x16x64_i8 v[98:101], v[178:181], v[194:197], v[98:101]
	v_mfma_i32_16x16x64_i8 v[86:89], v[170:173], v[202:205], v[86:89]
	v_mfma_i32_16x16x64_i8 v[82:85], v[178:181], v[202:205], v[82:85]
	v_mfma_i32_16x16x64_i8 v[70:73], v[170:173], v[210:213], v[70:73]
	v_mfma_i32_16x16x64_i8 v[66:69], v[178:181], v[210:213], v[66:69]
	s_setprio 0
	s_barrier
	s_add_i32 s84, s84, s40
	ds_read_b128 v[182:185], v148 offset:16384
	ds_read_b128 v[186:189], v148 offset:17408
	ds_read_b128 v[190:193], v148 offset:18432
	ds_read_b128 v[194:197], v148 offset:19456
	ds_read_b128 v[198:201], v148 offset:20480
	ds_read_b128 v[202:205], v148 offset:21504
	ds_read_b128 v[206:209], v148 offset:22528
	ds_read_b128 v[210:213], v148 offset:23552
	s_mov_b32 m0, s84
	s_nop 0
	global_load_lds_dwordx4 v143, s[50:51]
	s_add_i32 m0, s84, 0x2000
	s_add_u32 s84, s50, 0x20000
	global_load_lds_dwordx4 v144, s[50:51]
	s_addc_u32 s85, s51, 0
	s_add_i32 s86, s86, s40
	s_mov_b32 m0, s86
	s_nop 0
	global_load_lds_dwordx4 v143, s[84:85]
	s_add_i32 m0, s86, 0x2000
	s_nop 0
	global_load_lds_dwordx4 v144, s[84:85]
	s_mov_b32 m0, s59
	s_nop 0
	global_load_lds_dwordx4 v132, s[46:47]
	s_mov_b32 m0, s60
	s_nop 0
	global_load_lds_dwordx4 v133, s[46:47]
	s_waitcnt vmcnt(8) lgkmcnt(0)
	s_setprio 1
	s_barrier
	v_mfma_i32_16x16x64_i8 v[62:65], v[150:153], v[182:185], v[62:65]
	v_mfma_i32_16x16x64_i8 v[58:61], v[158:161], v[182:185], v[58:61]
	v_mfma_i32_16x16x64_i8 v[46:49], v[150:153], v[190:193], v[46:49]
	v_mfma_i32_16x16x64_i8 v[42:45], v[158:161], v[190:193], v[42:45]
	v_mfma_i32_16x16x64_i8 v[30:33], v[150:153], v[198:201], v[30:33]
	v_mfma_i32_16x16x64_i8 v[26:29], v[158:161], v[198:201], v[26:29]
	v_mfma_i32_16x16x64_i8 v[14:17], v[150:153], v[206:209], v[14:17]
	v_mfma_i32_16x16x64_i8 v[10:13], v[158:161], v[206:209], v[10:13]
	v_mfma_i32_16x16x64_i8 v[62:65], v[154:157], v[186:189], v[62:65]
	v_mfma_i32_16x16x64_i8 v[58:61], v[162:165], v[186:189], v[58:61]
	v_mfma_i32_16x16x64_i8 v[46:49], v[154:157], v[194:197], v[46:49]
	v_mfma_i32_16x16x64_i8 v[42:45], v[162:165], v[194:197], v[42:45]
	v_mfma_i32_16x16x64_i8 v[30:33], v[154:157], v[202:205], v[30:33]
	v_mfma_i32_16x16x64_i8 v[26:29], v[162:165], v[202:205], v[26:29]
	v_mfma_i32_16x16x64_i8 v[14:17], v[154:157], v[210:213], v[14:17]
	v_mfma_i32_16x16x64_i8 v[10:13], v[162:165], v[210:213], v[10:13]
	s_setprio 0
	s_setprio 1
	v_mfma_i32_16x16x64_i8 v[54:57], v[166:169], v[182:185], v[54:57]
	v_mfma_i32_16x16x64_i8 v[50:53], v[174:177], v[182:185], v[50:53]
	v_mfma_i32_16x16x64_i8 v[38:41], v[166:169], v[190:193], v[38:41]
	v_mfma_i32_16x16x64_i8 v[34:37], v[174:177], v[190:193], v[34:37]
	v_mfma_i32_16x16x64_i8 v[22:25], v[166:169], v[198:201], v[22:25]
	v_mfma_i32_16x16x64_i8 v[18:21], v[174:177], v[198:201], v[18:21]
	v_mfma_i32_16x16x64_i8 v[6:9], v[166:169], v[206:209], v[6:9]
	v_mfma_i32_16x16x64_i8 v[2:5], v[174:177], v[206:209], v[2:5]
	v_mfma_i32_16x16x64_i8 v[54:57], v[170:173], v[186:189], v[54:57]
	v_mfma_i32_16x16x64_i8 v[50:53], v[178:181], v[186:189], v[50:53]
	v_mfma_i32_16x16x64_i8 v[38:41], v[170:173], v[194:197], v[38:41]
	v_mfma_i32_16x16x64_i8 v[34:37], v[178:181], v[194:197], v[34:37]
	v_mfma_i32_16x16x64_i8 v[22:25], v[170:173], v[202:205], v[22:25]
	v_mfma_i32_16x16x64_i8 v[18:21], v[178:181], v[202:205], v[18:21]
	v_mfma_i32_16x16x64_i8 v[6:9], v[170:173], v[210:213], v[6:9]
	v_mfma_i32_16x16x64_i8 v[2:5], v[178:181], v[210:213], v[2:5]
	s_setprio 0
	s_barrier
	s_add_i32 s86, 0, 0x18000
	s_add_i32 s87, 0, 0x1c000
	ds_read_b128 v[150:153], v0 offset:32768
	ds_read_b128 v[154:157], v0 offset:33792
	ds_read_b128 v[158:161], v0 offset:34816
	ds_read_b128 v[162:165], v0 offset:35840
	ds_read_b128 v[166:169], v0 offset:49152
	ds_read_b128 v[170:173], v0 offset:50176
	ds_read_b128 v[174:177], v0 offset:51200
	ds_read_b128 v[178:181], v0 offset:52224
	s_add_u32 s84, s46, 0x20000
	s_mov_b32 m0, s61
	ds_read_b128 v[182:185], v148 offset:32768
	ds_read_b128 v[186:189], v148 offset:33792
	ds_read_b128 v[190:193], v148 offset:34816
	ds_read_b128 v[194:197], v148 offset:35840
	ds_read_b128 v[198:201], v148 offset:36864
	ds_read_b128 v[202:205], v148 offset:37888
	ds_read_b128 v[206:209], v148 offset:38912
	ds_read_b128 v[210:213], v148 offset:39936
	s_addc_u32 s85, s47, 0
	s_nop 0
	global_load_lds_dwordx4 v132, s[84:85]
	s_mov_b32 m0, s66
	s_nop 0
	global_load_lds_dwordx4 v133, s[84:85]
	s_waitcnt vmcnt(8) lgkmcnt(0)
	s_setprio 1
	s_barrier
	v_mfma_i32_16x16x64_i8 v[126:129], v[150:153], v[182:185], v[126:129]
	v_mfma_i32_16x16x64_i8 v[122:125], v[158:161], v[182:185], v[122:125]
	v_mfma_i32_16x16x64_i8 v[110:113], v[150:153], v[190:193], v[110:113]
	v_mfma_i32_16x16x64_i8 v[106:109], v[158:161], v[190:193], v[106:109]
	v_mfma_i32_16x16x64_i8 v[94:97], v[150:153], v[198:201], v[94:97]
	v_mfma_i32_16x16x64_i8 v[90:93], v[158:161], v[198:201], v[90:93]
	v_mfma_i32_16x16x64_i8 v[78:81], v[150:153], v[206:209], v[78:81]
	v_mfma_i32_16x16x64_i8 v[74:77], v[158:161], v[206:209], v[74:77]
	v_mfma_i32_16x16x64_i8 v[126:129], v[154:157], v[186:189], v[126:129]
	v_mfma_i32_16x16x64_i8 v[122:125], v[162:165], v[186:189], v[122:125]
	v_mfma_i32_16x16x64_i8 v[110:113], v[154:157], v[194:197], v[110:113]
	v_mfma_i32_16x16x64_i8 v[106:109], v[162:165], v[194:197], v[106:109]
	v_mfma_i32_16x16x64_i8 v[94:97], v[154:157], v[202:205], v[94:97]
	v_mfma_i32_16x16x64_i8 v[90:93], v[162:165], v[202:205], v[90:93]
	v_mfma_i32_16x16x64_i8 v[78:81], v[154:157], v[210:213], v[78:81]
	v_mfma_i32_16x16x64_i8 v[74:77], v[162:165], v[210:213], v[74:77]
	s_setprio 0
	s_setprio 1
	v_mfma_i32_16x16x64_i8 v[118:121], v[166:169], v[182:185], v[118:121]
	v_mfma_i32_16x16x64_i8 v[114:117], v[174:177], v[182:185], v[114:117]
	v_mfma_i32_16x16x64_i8 v[102:105], v[166:169], v[190:193], v[102:105]
	v_mfma_i32_16x16x64_i8 v[98:101], v[174:177], v[190:193], v[98:101]
	v_mfma_i32_16x16x64_i8 v[86:89], v[166:169], v[198:201], v[86:89]
	v_mfma_i32_16x16x64_i8 v[82:85], v[174:177], v[198:201], v[82:85]
	v_mfma_i32_16x16x64_i8 v[70:73], v[166:169], v[206:209], v[70:73]
	v_mfma_i32_16x16x64_i8 v[66:69], v[174:177], v[206:209], v[66:69]
	v_mfma_i32_16x16x64_i8 v[118:121], v[170:173], v[186:189], v[118:121]
	v_mfma_i32_16x16x64_i8 v[114:117], v[178:181], v[186:189], v[114:117]
	v_mfma_i32_16x16x64_i8 v[102:105], v[170:173], v[194:197], v[102:105]
	v_mfma_i32_16x16x64_i8 v[98:101], v[178:181], v[194:197], v[98:101]
	v_mfma_i32_16x16x64_i8 v[86:89], v[170:173], v[202:205], v[86:89]
	v_mfma_i32_16x16x64_i8 v[82:85], v[178:181], v[202:205], v[82:85]
	v_mfma_i32_16x16x64_i8 v[70:73], v[170:173], v[210:213], v[70:73]
	v_mfma_i32_16x16x64_i8 v[66:69], v[178:181], v[210:213], v[66:69]
	s_setprio 0
	s_barrier
	ds_read_b128 v[182:185], v148 offset:49152
	ds_read_b128 v[186:189], v148 offset:50176
	ds_read_b128 v[190:193], v148 offset:51200
	ds_read_b128 v[194:197], v148 offset:52224
	ds_read_b128 v[198:201], v148 offset:53248
	ds_read_b128 v[202:205], v148 offset:54272
	ds_read_b128 v[206:209], v148 offset:55296
	ds_read_b128 v[210:213], v148 offset:56320
	s_add_i32 s84, s86, s40
	s_add_u32 s100, s50, s38
	s_addc_u32 s101, s51, s39
	s_mov_b32 m0, s84
	s_nop 0
	global_load_lds_dwordx4 v143, s[100:101]
	s_add_i32 m0, s84, 0x2000
	s_nop 0
	s_add_u32 s50, s50, 0x20080
	s_addc_u32 s51, s51, 0
	s_add_i32 s84, s87, s40
	global_load_lds_dwordx4 v144, s[100:101]
	s_mov_b32 m0, s84
	s_nop 0
	global_load_lds_dwordx4 v143, s[50:51]
	s_add_i32 m0, s84, 0x2000
	s_nop 0
	global_load_lds_dwordx4 v144, s[50:51]
	s_mov_b32 m0, s75
	s_add_u32 s100, s46, s38
	s_addc_u32 s101, s47, s39
	v_mov_b32_e32 v0, v133
	global_load_lds_dwordx4 v132, s[100:101]
	s_mov_b32 m0, s78
	s_nop 0
	global_load_lds_dwordx4 v133, s[100:101]
	s_waitcnt vmcnt(8) lgkmcnt(0)
	s_setprio 1
	s_barrier
	v_mfma_i32_16x16x64_i8 v[62:65], v[150:153], v[182:185], v[62:65]
	v_mfma_i32_16x16x64_i8 v[58:61], v[158:161], v[182:185], v[58:61]
	v_mfma_i32_16x16x64_i8 v[46:49], v[150:153], v[190:193], v[46:49]
	v_mfma_i32_16x16x64_i8 v[42:45], v[158:161], v[190:193], v[42:45]
	v_mfma_i32_16x16x64_i8 v[30:33], v[150:153], v[198:201], v[30:33]
	v_mfma_i32_16x16x64_i8 v[26:29], v[158:161], v[198:201], v[26:29]
	v_mfma_i32_16x16x64_i8 v[14:17], v[150:153], v[206:209], v[14:17]
	v_mfma_i32_16x16x64_i8 v[10:13], v[158:161], v[206:209], v[10:13]
	v_mfma_i32_16x16x64_i8 v[62:65], v[154:157], v[186:189], v[62:65]
	v_mfma_i32_16x16x64_i8 v[58:61], v[162:165], v[186:189], v[58:61]
	v_mfma_i32_16x16x64_i8 v[46:49], v[154:157], v[194:197], v[46:49]
	v_mfma_i32_16x16x64_i8 v[42:45], v[162:165], v[194:197], v[42:45]
	v_mfma_i32_16x16x64_i8 v[30:33], v[154:157], v[202:205], v[30:33]
	v_mfma_i32_16x16x64_i8 v[26:29], v[162:165], v[202:205], v[26:29]
	v_mfma_i32_16x16x64_i8 v[14:17], v[154:157], v[210:213], v[14:17]
	v_mfma_i32_16x16x64_i8 v[10:13], v[162:165], v[210:213], v[10:13]
	s_setprio 0
	s_setprio 1
	v_mfma_i32_16x16x64_i8 v[54:57], v[166:169], v[182:185], v[54:57]
	v_mfma_i32_16x16x64_i8 v[50:53], v[174:177], v[182:185], v[50:53]
	v_mfma_i32_16x16x64_i8 v[38:41], v[166:169], v[190:193], v[38:41]
	v_mfma_i32_16x16x64_i8 v[34:37], v[174:177], v[190:193], v[34:37]
	v_mfma_i32_16x16x64_i8 v[22:25], v[166:169], v[198:201], v[22:25]
	v_mfma_i32_16x16x64_i8 v[18:21], v[174:177], v[198:201], v[18:21]
	v_mfma_i32_16x16x64_i8 v[6:9], v[166:169], v[206:209], v[6:9]
	v_mfma_i32_16x16x64_i8 v[2:5], v[174:177], v[206:209], v[2:5]
	v_mfma_i32_16x16x64_i8 v[54:57], v[170:173], v[186:189], v[54:57]
	v_mfma_i32_16x16x64_i8 v[50:53], v[178:181], v[186:189], v[50:53]
	v_mfma_i32_16x16x64_i8 v[38:41], v[170:173], v[194:197], v[38:41]
	v_mfma_i32_16x16x64_i8 v[34:37], v[178:181], v[194:197], v[34:37]
	v_mfma_i32_16x16x64_i8 v[22:25], v[170:173], v[202:205], v[22:25]
	v_mfma_i32_16x16x64_i8 v[18:21], v[178:181], v[202:205], v[18:21]
	v_mfma_i32_16x16x64_i8 v[6:9], v[170:173], v[210:213], v[6:9]
	v_mfma_i32_16x16x64_i8 v[2:5], v[178:181], v[210:213], v[2:5]
	s_setprio 0
	s_barrier
	s_add_i32 s65, s65, 2
	s_add_u32 s48, s48, 0x100
	s_addc_u32 s49, s49, 0
	s_add_u32 s25, s25, 0x100
	s_addc_u32 s64, s64, 0
	s_cmp_gt_u32 s65, 5
	s_cbranch_scc0 .LBB0_445

.LBB0_626:
	s_add_u32 s58, s14, s50
	s_addc_u32 s59, s15, s51
	s_add_u32 s46, s58, 0x100
	s_addc_u32 s47, s59, 0
	s_and_b64 s[4:5], s[48:49], exec
	s_cselect_b32 s47, s15, s47
	s_cselect_b32 s46, s14, s46
	s_add_u32 s4, s16, s50
	s_addc_u32 s5, s17, s51
	s_add_u32 s50, s4, 0x100
	s_addc_u32 s51, s5, 0
	s_add_i32 s78, 0, 0x10000
	s_and_b64 s[4:5], s[48:49], exec
	s_cselect_b32 s49, s17, s51
	s_cselect_b32 s48, s16, s50
	s_add_i32 s4, 0, 0x14000
	s_add_u32 s96, s58, 0x80080
	s_addc_u32 s97, s59, 0
	s_add_i32 s82, s78, s42
	s_add_i32 m0, s43, 0xc000
	s_add_i32 s5, s43, 0xe000
	s_add_i32 s76, s82, 0x2000
	v_add_u32_e32 v0, s78, v136
	s_add_u32 s94, s48, 0x40000
	ds_read_b128 v[138:141], v0
	ds_read_b128 v[142:145], v0 offset:1024
	ds_read_b128 v[146:149], v0 offset:2048
	ds_read_b128 v[150:153], v0 offset:3072
	s_addc_u32 s95, s49, 0
	s_add_i32 s77, s4, s42
	ds_read_b128 v[154:157], v0 offset:16384
	ds_read_b128 v[158:161], v0 offset:17408
	ds_read_b128 v[162:165], v0 offset:18432
	ds_read_b128 v[166:169], v0 offset:19456
	s_add_i32 s75, s77, 0x2000
	s_add_i32 s74, 0, 0x18000
	s_add_i32 s71, 0, 0x1c000
	s_add_u32 s58, s46, 0x80000
	s_addc_u32 s59, s47, 0
	s_add_i32 s70, s74, s42
	s_add_i32 s69, s70, 0x2000
	s_add_u32 s50, s48, 0x40080
	s_addc_u32 s51, s49, 0
	s_add_i32 s79, s71, s42
	s_add_i32 s78, s79, 0x2000
	ds_read_b128 v[170:173], v137
	ds_read_b128 v[174:177], v137 offset:1024
	ds_read_b128 v[178:181], v137 offset:2048
	ds_read_b128 v[182:185], v137 offset:3072
	ds_read_b128 v[186:189], v137 offset:4096
	ds_read_b128 v[190:193], v137 offset:5120
	ds_read_b128 v[194:197], v137 offset:6144
	ds_read_b128 v[198:201], v137 offset:7168
	s_nop 0
	global_load_lds_dwordx4 v130, s[96:97]
	s_mov_b32 m0, s5
	s_nop 0
	global_load_lds_dwordx4 v132, s[96:97]
	s_waitcnt vmcnt(8) lgkmcnt(0)
	s_setprio 1
	s_barrier
	v_mfma_f32_16x16x32_bf16 v[126:129], v[138:141], v[170:173], v[126:129]
	v_mfma_f32_16x16x32_bf16 v[122:125], v[146:149], v[170:173], v[122:125]
	v_mfma_f32_16x16x32_bf16 v[118:121], v[138:141], v[178:181], v[118:121]
	v_mfma_f32_16x16x32_bf16 v[110:113], v[146:149], v[178:181], v[110:113]
	v_mfma_f32_16x16x32_bf16 v[102:105], v[138:141], v[186:189], v[102:105]
	v_mfma_f32_16x16x32_bf16 v[94:97], v[146:149], v[186:189], v[94:97]
	v_mfma_f32_16x16x32_bf16 v[86:89], v[138:141], v[194:197], v[86:89]
	v_mfma_f32_16x16x32_bf16 v[78:81], v[146:149], v[194:197], v[78:81]
	v_mfma_f32_16x16x32_bf16 v[126:129], v[142:145], v[174:177], v[126:129]
	v_mfma_f32_16x16x32_bf16 v[122:125], v[150:153], v[174:177], v[122:125]
	v_mfma_f32_16x16x32_bf16 v[118:121], v[142:145], v[182:185], v[118:121]
	v_mfma_f32_16x16x32_bf16 v[110:113], v[150:153], v[182:185], v[110:113]
	v_mfma_f32_16x16x32_bf16 v[102:105], v[142:145], v[190:193], v[102:105]
	v_mfma_f32_16x16x32_bf16 v[94:97], v[150:153], v[190:193], v[94:97]
	v_mfma_f32_16x16x32_bf16 v[86:89], v[142:145], v[198:201], v[86:89]
	v_mfma_f32_16x16x32_bf16 v[78:81], v[150:153], v[198:201], v[78:81]
	s_setprio 0
	s_setprio 1
	v_mfma_f32_16x16x32_bf16 v[114:117], v[154:157], v[170:173], v[114:117]
	v_mfma_f32_16x16x32_bf16 v[106:109], v[162:165], v[170:173], v[106:109]
	v_mfma_f32_16x16x32_bf16 v[98:101], v[154:157], v[178:181], v[98:101]
	v_mfma_f32_16x16x32_bf16 v[90:93], v[162:165], v[178:181], v[90:93]
	v_mfma_f32_16x16x32_bf16 v[82:85], v[154:157], v[186:189], v[82:85]
	v_mfma_f32_16x16x32_bf16 v[74:77], v[162:165], v[186:189], v[74:77]
	v_mfma_f32_16x16x32_bf16 v[70:73], v[154:157], v[194:197], v[70:73]
	v_mfma_f32_16x16x32_bf16 v[62:65], v[162:165], v[194:197], v[62:65]
	v_mfma_f32_16x16x32_bf16 v[114:117], v[158:161], v[174:177], v[114:117]
	v_mfma_f32_16x16x32_bf16 v[106:109], v[166:169], v[174:177], v[106:109]
	v_mfma_f32_16x16x32_bf16 v[98:101], v[158:161], v[182:185], v[98:101]
	v_mfma_f32_16x16x32_bf16 v[90:93], v[166:169], v[182:185], v[90:93]
	v_mfma_f32_16x16x32_bf16 v[82:85], v[158:161], v[190:193], v[82:85]
	v_mfma_f32_16x16x32_bf16 v[74:77], v[166:169], v[190:193], v[74:77]
	v_mfma_f32_16x16x32_bf16 v[70:73], v[158:161], v[198:201], v[70:73]
	v_mfma_f32_16x16x32_bf16 v[62:65], v[166:169], v[198:201], v[62:65]
	s_setprio 0
	s_barrier
	s_mov_b32 m0, s82
	ds_read_b128 v[170:173], v137 offset:16384
	ds_read_b128 v[174:177], v137 offset:17408
	ds_read_b128 v[178:181], v137 offset:18432
	ds_read_b128 v[182:185], v137 offset:19456
	ds_read_b128 v[186:189], v137 offset:20480
	ds_read_b128 v[190:193], v137 offset:21504
	ds_read_b128 v[194:197], v137 offset:22528
	ds_read_b128 v[198:201], v137 offset:23552
	s_nop 0
	global_load_lds_dwordx4 v131, s[48:49]
	s_mov_b32 m0, s76
	s_nop 0
	global_load_lds_dwordx4 v133, s[48:49]
	s_mov_b32 m0, s77
	s_nop 0
	global_load_lds_dwordx4 v131, s[94:95]
	s_mov_b32 m0, s75
	s_nop 0
	global_load_lds_dwordx4 v133, s[94:95]
	s_mov_b32 m0, s43
	s_nop 0
	global_load_lds_dwordx4 v130, s[46:47]
	s_mov_b32 m0, s60
	s_nop 0
	global_load_lds_dwordx4 v132, s[46:47]
	s_waitcnt vmcnt(8) lgkmcnt(0)
	s_setprio 1
	s_barrier
	v_mfma_f32_16x16x32_bf16 v[66:69], v[138:141], v[170:173], v[66:69]
	v_mfma_f32_16x16x32_bf16 v[58:61], v[146:149], v[170:173], v[58:61]
	v_mfma_f32_16x16x32_bf16 v[54:57], v[138:141], v[178:181], v[54:57]
	v_mfma_f32_16x16x32_bf16 v[46:49], v[146:149], v[178:181], v[46:49]
	v_mfma_f32_16x16x32_bf16 v[38:41], v[138:141], v[186:189], v[38:41]
	v_mfma_f32_16x16x32_bf16 v[30:33], v[146:149], v[186:189], v[30:33]
	v_mfma_f32_16x16x32_bf16 v[22:25], v[138:141], v[194:197], v[22:25]
	v_mfma_f32_16x16x32_bf16 v[14:17], v[146:149], v[194:197], v[14:17]
	v_mfma_f32_16x16x32_bf16 v[66:69], v[142:145], v[174:177], v[66:69]
	v_mfma_f32_16x16x32_bf16 v[58:61], v[150:153], v[174:177], v[58:61]
	v_mfma_f32_16x16x32_bf16 v[54:57], v[142:145], v[182:185], v[54:57]
	v_mfma_f32_16x16x32_bf16 v[46:49], v[150:153], v[182:185], v[46:49]
	v_mfma_f32_16x16x32_bf16 v[38:41], v[142:145], v[190:193], v[38:41]
	v_mfma_f32_16x16x32_bf16 v[30:33], v[150:153], v[190:193], v[30:33]
	v_mfma_f32_16x16x32_bf16 v[22:25], v[142:145], v[198:201], v[22:25]
	v_mfma_f32_16x16x32_bf16 v[14:17], v[150:153], v[198:201], v[14:17]
	s_setprio 0
	s_setprio 1
	v_mfma_f32_16x16x32_bf16 v[50:53], v[154:157], v[170:173], v[50:53]
	v_mfma_f32_16x16x32_bf16 v[42:45], v[162:165], v[170:173], v[42:45]
	v_mfma_f32_16x16x32_bf16 v[34:37], v[154:157], v[178:181], v[34:37]
	v_mfma_f32_16x16x32_bf16 v[26:29], v[162:165], v[178:181], v[26:29]
	v_mfma_f32_16x16x32_bf16 v[18:21], v[154:157], v[186:189], v[18:21]
	v_mfma_f32_16x16x32_bf16 v[10:13], v[162:165], v[186:189], v[10:13]
	v_mfma_f32_16x16x32_bf16 v[6:9], v[154:157], v[194:197], v[6:9]
	v_mfma_f32_16x16x32_bf16 v[2:5], v[162:165], v[194:197], v[2:5]
	v_mfma_f32_16x16x32_bf16 v[50:53], v[158:161], v[174:177], v[50:53]
	v_mfma_f32_16x16x32_bf16 v[42:45], v[166:169], v[174:177], v[42:45]
	v_mfma_f32_16x16x32_bf16 v[34:37], v[158:161], v[182:185], v[34:37]
	v_mfma_f32_16x16x32_bf16 v[26:29], v[166:169], v[182:185], v[26:29]
	v_mfma_f32_16x16x32_bf16 v[18:21], v[158:161], v[190:193], v[18:21]
	v_mfma_f32_16x16x32_bf16 v[10:13], v[166:169], v[190:193], v[10:13]
	v_mfma_f32_16x16x32_bf16 v[6:9], v[158:161], v[198:201], v[6:9]
	v_mfma_f32_16x16x32_bf16 v[2:5], v[166:169], v[198:201], v[2:5]
	s_setprio 0
	s_barrier
	ds_read_b128 v[138:141], v0 offset:32768
	ds_read_b128 v[142:145], v0 offset:33792
	ds_read_b128 v[146:149], v0 offset:34816
	ds_read_b128 v[150:153], v0 offset:35840
	ds_read_b128 v[154:157], v0 offset:49152
	ds_read_b128 v[158:161], v0 offset:50176
	ds_read_b128 v[162:165], v0 offset:51200
	ds_read_b128 v[166:169], v0 offset:52224
	s_mov_b32 m0, s65
	ds_read_b128 v[170:173], v137 offset:32768
	ds_read_b128 v[174:177], v137 offset:33792
	ds_read_b128 v[178:181], v137 offset:34816
	ds_read_b128 v[182:185], v137 offset:35840
	ds_read_b128 v[186:189], v137 offset:36864
	ds_read_b128 v[190:193], v137 offset:37888
	ds_read_b128 v[194:197], v137 offset:38912
	ds_read_b128 v[198:201], v137 offset:39936
	s_nop 0
	global_load_lds_dwordx4 v130, s[58:59]
	s_mov_b32 m0, s66
	s_nop 0
	global_load_lds_dwordx4 v132, s[58:59]
	s_waitcnt vmcnt(8) lgkmcnt(0)
	s_setprio 1
	s_barrier
	v_mfma_f32_16x16x32_bf16 v[126:129], v[138:141], v[170:173], v[126:129]
	v_mfma_f32_16x16x32_bf16 v[122:125], v[146:149], v[170:173], v[122:125]
	v_mfma_f32_16x16x32_bf16 v[118:121], v[138:141], v[178:181], v[118:121]
	v_mfma_f32_16x16x32_bf16 v[110:113], v[146:149], v[178:181], v[110:113]
	v_mfma_f32_16x16x32_bf16 v[102:105], v[138:141], v[186:189], v[102:105]
	v_mfma_f32_16x16x32_bf16 v[94:97], v[146:149], v[186:189], v[94:97]
	v_mfma_f32_16x16x32_bf16 v[86:89], v[138:141], v[194:197], v[86:89]
	v_mfma_f32_16x16x32_bf16 v[78:81], v[146:149], v[194:197], v[78:81]
	v_mfma_f32_16x16x32_bf16 v[126:129], v[142:145], v[174:177], v[126:129]
	v_mfma_f32_16x16x32_bf16 v[122:125], v[150:153], v[174:177], v[122:125]
	v_mfma_f32_16x16x32_bf16 v[118:121], v[142:145], v[182:185], v[118:121]
	v_mfma_f32_16x16x32_bf16 v[110:113], v[150:153], v[182:185], v[110:113]
	v_mfma_f32_16x16x32_bf16 v[102:105], v[142:145], v[190:193], v[102:105]
	v_mfma_f32_16x16x32_bf16 v[94:97], v[150:153], v[190:193], v[94:97]
	v_mfma_f32_16x16x32_bf16 v[86:89], v[142:145], v[198:201], v[86:89]
	v_mfma_f32_16x16x32_bf16 v[78:81], v[150:153], v[198:201], v[78:81]
	s_setprio 0
	s_setprio 1
	v_mfma_f32_16x16x32_bf16 v[114:117], v[154:157], v[170:173], v[114:117]
	v_mfma_f32_16x16x32_bf16 v[106:109], v[162:165], v[170:173], v[106:109]
	v_mfma_f32_16x16x32_bf16 v[98:101], v[154:157], v[178:181], v[98:101]
	v_mfma_f32_16x16x32_bf16 v[90:93], v[162:165], v[178:181], v[90:93]
	v_mfma_f32_16x16x32_bf16 v[82:85], v[154:157], v[186:189], v[82:85]
	v_mfma_f32_16x16x32_bf16 v[74:77], v[162:165], v[186:189], v[74:77]
	v_mfma_f32_16x16x32_bf16 v[70:73], v[154:157], v[194:197], v[70:73]
	v_mfma_f32_16x16x32_bf16 v[62:65], v[162:165], v[194:197], v[62:65]
	v_mfma_f32_16x16x32_bf16 v[114:117], v[158:161], v[174:177], v[114:117]
	v_mfma_f32_16x16x32_bf16 v[106:109], v[166:169], v[174:177], v[106:109]
	v_mfma_f32_16x16x32_bf16 v[98:101], v[158:161], v[182:185], v[98:101]
	v_mfma_f32_16x16x32_bf16 v[90:93], v[166:169], v[182:185], v[90:93]
	v_mfma_f32_16x16x32_bf16 v[82:85], v[158:161], v[190:193], v[82:85]
	v_mfma_f32_16x16x32_bf16 v[74:77], v[166:169], v[190:193], v[74:77]
	v_mfma_f32_16x16x32_bf16 v[70:73], v[158:161], v[198:201], v[70:73]
	v_mfma_f32_16x16x32_bf16 v[62:65], v[166:169], v[198:201], v[62:65]
	s_setprio 0
	s_barrier
	ds_read_b128 v[170:173], v137 offset:49152
	ds_read_b128 v[174:177], v137 offset:50176
	ds_read_b128 v[178:181], v137 offset:51200
	ds_read_b128 v[182:185], v137 offset:52224
	ds_read_b128 v[186:189], v137 offset:53248
	ds_read_b128 v[190:193], v137 offset:54272
	ds_read_b128 v[194:197], v137 offset:55296
	ds_read_b128 v[198:201], v137 offset:56320
	s_mov_b32 m0, s70
	s_add_u32 s100, s48, s38
	s_addc_u32 s101, s49, s39
	global_load_lds_dwordx4 v131, s[100:101]
	s_mov_b32 m0, s69
	s_nop 0
	global_load_lds_dwordx4 v133, s[100:101]
	s_mov_b32 m0, s79
	s_nop 0
	global_load_lds_dwordx4 v131, s[50:51]
	s_mov_b32 m0, s78
	s_nop 0
	global_load_lds_dwordx4 v133, s[50:51]
	s_mov_b32 m0, s67
	s_add_u32 s100, s46, s38
	s_addc_u32 s101, s47, s39
	v_mov_b32_e32 v0, v132
	global_load_lds_dwordx4 v130, s[100:101]
	s_mov_b32 m0, s68
	s_nop 0
	global_load_lds_dwordx4 v132, s[100:101]
	s_waitcnt vmcnt(8) lgkmcnt(0)
	s_setprio 1
	s_barrier
	v_mfma_f32_16x16x32_bf16 v[66:69], v[138:141], v[170:173], v[66:69]
	v_mfma_f32_16x16x32_bf16 v[58:61], v[146:149], v[170:173], v[58:61]
	v_mfma_f32_16x16x32_bf16 v[54:57], v[138:141], v[178:181], v[54:57]
	v_mfma_f32_16x16x32_bf16 v[46:49], v[146:149], v[178:181], v[46:49]
	v_mfma_f32_16x16x32_bf16 v[38:41], v[138:141], v[186:189], v[38:41]
	v_mfma_f32_16x16x32_bf16 v[30:33], v[146:149], v[186:189], v[30:33]
	v_mfma_f32_16x16x32_bf16 v[22:25], v[138:141], v[194:197], v[22:25]
	v_mfma_f32_16x16x32_bf16 v[14:17], v[146:149], v[194:197], v[14:17]
	v_mfma_f32_16x16x32_bf16 v[66:69], v[142:145], v[174:177], v[66:69]
	v_mfma_f32_16x16x32_bf16 v[58:61], v[150:153], v[174:177], v[58:61]
	v_mfma_f32_16x16x32_bf16 v[54:57], v[142:145], v[182:185], v[54:57]
	v_mfma_f32_16x16x32_bf16 v[46:49], v[150:153], v[182:185], v[46:49]
	v_mfma_f32_16x16x32_bf16 v[38:41], v[142:145], v[190:193], v[38:41]
	v_mfma_f32_16x16x32_bf16 v[30:33], v[150:153], v[190:193], v[30:33]
	v_mfma_f32_16x16x32_bf16 v[22:25], v[142:145], v[198:201], v[22:25]
	v_mfma_f32_16x16x32_bf16 v[14:17], v[150:153], v[198:201], v[14:17]
	s_setprio 0
	s_setprio 1
	v_mfma_f32_16x16x32_bf16 v[50:53], v[154:157], v[170:173], v[50:53]
	v_mfma_f32_16x16x32_bf16 v[42:45], v[162:165], v[170:173], v[42:45]
	v_mfma_f32_16x16x32_bf16 v[34:37], v[154:157], v[178:181], v[34:37]
	v_mfma_f32_16x16x32_bf16 v[26:29], v[162:165], v[178:181], v[26:29]
	v_mfma_f32_16x16x32_bf16 v[18:21], v[154:157], v[186:189], v[18:21]
	v_mfma_f32_16x16x32_bf16 v[10:13], v[162:165], v[186:189], v[10:13]
	v_mfma_f32_16x16x32_bf16 v[6:9], v[154:157], v[194:197], v[6:9]
	v_mfma_f32_16x16x32_bf16 v[2:5], v[162:165], v[194:197], v[2:5]
	v_mfma_f32_16x16x32_bf16 v[50:53], v[158:161], v[174:177], v[50:53]
	v_mfma_f32_16x16x32_bf16 v[42:45], v[166:169], v[174:177], v[42:45]
	v_mfma_f32_16x16x32_bf16 v[34:37], v[158:161], v[182:185], v[34:37]
	v_mfma_f32_16x16x32_bf16 v[26:29], v[166:169], v[182:185], v[26:29]
	v_mfma_f32_16x16x32_bf16 v[18:21], v[158:161], v[190:193], v[18:21]
	v_mfma_f32_16x16x32_bf16 v[10:13], v[166:169], v[190:193], v[10:13]
	v_mfma_f32_16x16x32_bf16 v[6:9], v[158:161], v[198:201], v[6:9]
	v_mfma_f32_16x16x32_bf16 v[2:5], v[166:169], v[198:201], v[2:5]
	s_setprio 0
	s_barrier
	s_andn2_b64 vcc, exec, s[22:23]
	s_mov_b64 s[48:49], -1
	s_mov_b64 s[22:23], 0
	s_mov_b64 s[50:51], 0x100
	s_cbranch_vccz .LBB0_626
	s_cmpk_lt_u32 s25, 0x100
	s_cbranch_scc0 .LBB0_629
	s_barrier

.LBB0_634:
	s_add_u32 s50, s2, s48
	s_addc_u32 s51, s3, s49
	s_add_u32 s22, s50, 0x100
	s_addc_u32 s23, s51, 0
	s_and_b64 s[4:5], s[46:47], exec
	s_cselect_b32 s23, s3, s23
	s_cselect_b32 s22, s2, s22
	s_add_u32 s4, s14, s48
	s_addc_u32 s5, s15, s49
	s_add_u32 s48, s4, 0x900
	s_addc_u32 s49, s5, 0
	s_add_i32 s78, 0, 0x10000
	s_and_b64 s[4:5], s[46:47], exec
	s_cselect_b32 s47, s66, s49
	s_cselect_b32 s46, s65, s48
	s_add_i32 s4, 0, 0x14000
	s_add_u32 s94, s50, 0x40080
	s_addc_u32 s95, s51, 0
	s_add_i32 s82, s78, s40
	s_add_i32 m0, s41, 0xc000
	s_add_i32 s5, s41, 0xe000
	s_add_i32 s76, s82, 0x2000
	v_add_u32_e32 v0, s78, v136
	s_add_u32 s58, s46, 0x80000
	ds_read_b128 v[138:141], v0
	ds_read_b128 v[142:145], v0 offset:1024
	ds_read_b128 v[146:149], v0 offset:2048
	ds_read_b128 v[150:153], v0 offset:3072
	s_addc_u32 s59, s47, 0
	s_add_i32 s77, s4, s40
	ds_read_b128 v[154:157], v0 offset:16384
	ds_read_b128 v[158:161], v0 offset:17408
	ds_read_b128 v[162:165], v0 offset:18432
	ds_read_b128 v[166:169], v0 offset:19456
	s_add_i32 s75, s77, 0x2000
	s_add_i32 s74, 0, 0x18000
	s_add_i32 s71, 0, 0x1c000
	s_add_u32 s50, s22, 0x40000
	s_addc_u32 s51, s23, 0
	s_add_i32 s70, s74, s40
	s_add_i32 s69, s70, 0x2000
	s_add_u32 s48, s46, 0x80080
	s_addc_u32 s49, s47, 0
	s_add_i32 s79, s71, s40
	s_add_i32 s78, s79, 0x2000
	ds_read_b128 v[170:173], v137
	ds_read_b128 v[174:177], v137 offset:1024
	ds_read_b128 v[178:181], v137 offset:2048
	ds_read_b128 v[182:185], v137 offset:3072
	ds_read_b128 v[186:189], v137 offset:4096
	ds_read_b128 v[190:193], v137 offset:5120
	ds_read_b128 v[194:197], v137 offset:6144
	ds_read_b128 v[198:201], v137 offset:7168
	s_nop 0
	global_load_lds_dwordx4 v130, s[94:95]
	s_mov_b32 m0, s5
	s_nop 0
	global_load_lds_dwordx4 v132, s[94:95]
	s_waitcnt vmcnt(8) lgkmcnt(0)
	s_setprio 1
	s_barrier
	v_mfma_f32_16x16x32_bf16 v[126:129], v[138:141], v[170:173], v[126:129]
	v_mfma_f32_16x16x32_bf16 v[122:125], v[146:149], v[170:173], v[122:125]
	v_mfma_f32_16x16x32_bf16 v[118:121], v[138:141], v[178:181], v[118:121]
	v_mfma_f32_16x16x32_bf16 v[110:113], v[146:149], v[178:181], v[110:113]
	v_mfma_f32_16x16x32_bf16 v[102:105], v[138:141], v[186:189], v[102:105]
	v_mfma_f32_16x16x32_bf16 v[94:97], v[146:149], v[186:189], v[94:97]
	v_mfma_f32_16x16x32_bf16 v[86:89], v[138:141], v[194:197], v[86:89]
	v_mfma_f32_16x16x32_bf16 v[78:81], v[146:149], v[194:197], v[78:81]
	v_mfma_f32_16x16x32_bf16 v[126:129], v[142:145], v[174:177], v[126:129]
	v_mfma_f32_16x16x32_bf16 v[122:125], v[150:153], v[174:177], v[122:125]
	v_mfma_f32_16x16x32_bf16 v[118:121], v[142:145], v[182:185], v[118:121]
	v_mfma_f32_16x16x32_bf16 v[110:113], v[150:153], v[182:185], v[110:113]
	v_mfma_f32_16x16x32_bf16 v[102:105], v[142:145], v[190:193], v[102:105]
	v_mfma_f32_16x16x32_bf16 v[94:97], v[150:153], v[190:193], v[94:97]
	v_mfma_f32_16x16x32_bf16 v[86:89], v[142:145], v[198:201], v[86:89]
	v_mfma_f32_16x16x32_bf16 v[78:81], v[150:153], v[198:201], v[78:81]
	s_setprio 0
	s_setprio 1
	v_mfma_f32_16x16x32_bf16 v[114:117], v[154:157], v[170:173], v[114:117]
	v_mfma_f32_16x16x32_bf16 v[106:109], v[162:165], v[170:173], v[106:109]
	v_mfma_f32_16x16x32_bf16 v[98:101], v[154:157], v[178:181], v[98:101]
	v_mfma_f32_16x16x32_bf16 v[90:93], v[162:165], v[178:181], v[90:93]
	v_mfma_f32_16x16x32_bf16 v[82:85], v[154:157], v[186:189], v[82:85]
	v_mfma_f32_16x16x32_bf16 v[74:77], v[162:165], v[186:189], v[74:77]
	v_mfma_f32_16x16x32_bf16 v[70:73], v[154:157], v[194:197], v[70:73]
	v_mfma_f32_16x16x32_bf16 v[62:65], v[162:165], v[194:197], v[62:65]
	v_mfma_f32_16x16x32_bf16 v[114:117], v[158:161], v[174:177], v[114:117]
	v_mfma_f32_16x16x32_bf16 v[106:109], v[166:169], v[174:177], v[106:109]
	v_mfma_f32_16x16x32_bf16 v[98:101], v[158:161], v[182:185], v[98:101]
	v_mfma_f32_16x16x32_bf16 v[90:93], v[166:169], v[182:185], v[90:93]
	v_mfma_f32_16x16x32_bf16 v[82:85], v[158:161], v[190:193], v[82:85]
	v_mfma_f32_16x16x32_bf16 v[74:77], v[166:169], v[190:193], v[74:77]
	v_mfma_f32_16x16x32_bf16 v[70:73], v[158:161], v[198:201], v[70:73]
	v_mfma_f32_16x16x32_bf16 v[62:65], v[166:169], v[198:201], v[62:65]
	s_setprio 0
	s_barrier
	s_mov_b32 m0, s82
	ds_read_b128 v[170:173], v137 offset:16384
	ds_read_b128 v[174:177], v137 offset:17408
	ds_read_b128 v[178:181], v137 offset:18432
	ds_read_b128 v[182:185], v137 offset:19456
	ds_read_b128 v[186:189], v137 offset:20480
	ds_read_b128 v[190:193], v137 offset:21504
	ds_read_b128 v[194:197], v137 offset:22528
	ds_read_b128 v[198:201], v137 offset:23552
	s_nop 0
	global_load_lds_dwordx4 v131, s[46:47]
	s_mov_b32 m0, s76
	s_nop 0
	global_load_lds_dwordx4 v133, s[46:47]
	s_mov_b32 m0, s77
	s_nop 0
	global_load_lds_dwordx4 v131, s[58:59]
	s_mov_b32 m0, s75
	s_nop 0
	global_load_lds_dwordx4 v133, s[58:59]
	s_mov_b32 m0, s41
	s_nop 0
	global_load_lds_dwordx4 v130, s[22:23]
	s_mov_b32 m0, s42
	s_nop 0
	global_load_lds_dwordx4 v132, s[22:23]
	s_waitcnt vmcnt(8) lgkmcnt(0)
	s_setprio 1
	s_barrier
	v_mfma_f32_16x16x32_bf16 v[66:69], v[138:141], v[170:173], v[66:69]
	v_mfma_f32_16x16x32_bf16 v[58:61], v[146:149], v[170:173], v[58:61]
	v_mfma_f32_16x16x32_bf16 v[54:57], v[138:141], v[178:181], v[54:57]
	v_mfma_f32_16x16x32_bf16 v[46:49], v[146:149], v[178:181], v[46:49]
	v_mfma_f32_16x16x32_bf16 v[38:41], v[138:141], v[186:189], v[38:41]
	v_mfma_f32_16x16x32_bf16 v[30:33], v[146:149], v[186:189], v[30:33]
	v_mfma_f32_16x16x32_bf16 v[22:25], v[138:141], v[194:197], v[22:25]
	v_mfma_f32_16x16x32_bf16 v[14:17], v[146:149], v[194:197], v[14:17]
	v_mfma_f32_16x16x32_bf16 v[66:69], v[142:145], v[174:177], v[66:69]
	v_mfma_f32_16x16x32_bf16 v[58:61], v[150:153], v[174:177], v[58:61]
	v_mfma_f32_16x16x32_bf16 v[54:57], v[142:145], v[182:185], v[54:57]
	v_mfma_f32_16x16x32_bf16 v[46:49], v[150:153], v[182:185], v[46:49]
	v_mfma_f32_16x16x32_bf16 v[38:41], v[142:145], v[190:193], v[38:41]
	v_mfma_f32_16x16x32_bf16 v[30:33], v[150:153], v[190:193], v[30:33]
	v_mfma_f32_16x16x32_bf16 v[22:25], v[142:145], v[198:201], v[22:25]
	v_mfma_f32_16x16x32_bf16 v[14:17], v[150:153], v[198:201], v[14:17]
	s_setprio 0
	s_setprio 1
	v_mfma_f32_16x16x32_bf16 v[50:53], v[154:157], v[170:173], v[50:53]
	v_mfma_f32_16x16x32_bf16 v[42:45], v[162:165], v[170:173], v[42:45]
	v_mfma_f32_16x16x32_bf16 v[34:37], v[154:157], v[178:181], v[34:37]
	v_mfma_f32_16x16x32_bf16 v[26:29], v[162:165], v[178:181], v[26:29]
	v_mfma_f32_16x16x32_bf16 v[18:21], v[154:157], v[186:189], v[18:21]
	v_mfma_f32_16x16x32_bf16 v[10:13], v[162:165], v[186:189], v[10:13]
	v_mfma_f32_16x16x32_bf16 v[6:9], v[154:157], v[194:197], v[6:9]
	v_mfma_f32_16x16x32_bf16 v[2:5], v[162:165], v[194:197], v[2:5]
	v_mfma_f32_16x16x32_bf16 v[50:53], v[158:161], v[174:177], v[50:53]
	v_mfma_f32_16x16x32_bf16 v[42:45], v[166:169], v[174:177], v[42:45]
	v_mfma_f32_16x16x32_bf16 v[34:37], v[158:161], v[182:185], v[34:37]
	v_mfma_f32_16x16x32_bf16 v[26:29], v[166:169], v[182:185], v[26:29]
	v_mfma_f32_16x16x32_bf16 v[18:21], v[158:161], v[190:193], v[18:21]
	v_mfma_f32_16x16x32_bf16 v[10:13], v[166:169], v[190:193], v[10:13]
	v_mfma_f32_16x16x32_bf16 v[6:9], v[158:161], v[198:201], v[6:9]
	v_mfma_f32_16x16x32_bf16 v[2:5], v[166:169], v[198:201], v[2:5]
	s_setprio 0
	s_barrier
	ds_read_b128 v[138:141], v0 offset:32768
	ds_read_b128 v[142:145], v0 offset:33792
	ds_read_b128 v[146:149], v0 offset:34816
	ds_read_b128 v[150:153], v0 offset:35840
	ds_read_b128 v[154:157], v0 offset:49152
	ds_read_b128 v[158:161], v0 offset:50176
	ds_read_b128 v[162:165], v0 offset:51200
	ds_read_b128 v[166:169], v0 offset:52224
	s_mov_b32 m0, s43
	ds_read_b128 v[170:173], v137 offset:32768
	ds_read_b128 v[174:177], v137 offset:33792
	ds_read_b128 v[178:181], v137 offset:34816
	ds_read_b128 v[182:185], v137 offset:35840
	ds_read_b128 v[186:189], v137 offset:36864
	ds_read_b128 v[190:193], v137 offset:37888
	ds_read_b128 v[194:197], v137 offset:38912
	ds_read_b128 v[198:201], v137 offset:39936
	s_nop 0
	global_load_lds_dwordx4 v130, s[50:51]
	s_mov_b32 m0, s64
	s_nop 0
	global_load_lds_dwordx4 v132, s[50:51]
	s_waitcnt vmcnt(8) lgkmcnt(0)
	s_setprio 1
	s_barrier
	v_mfma_f32_16x16x32_bf16 v[126:129], v[138:141], v[170:173], v[126:129]
	v_mfma_f32_16x16x32_bf16 v[122:125], v[146:149], v[170:173], v[122:125]
	v_mfma_f32_16x16x32_bf16 v[118:121], v[138:141], v[178:181], v[118:121]
	v_mfma_f32_16x16x32_bf16 v[110:113], v[146:149], v[178:181], v[110:113]
	v_mfma_f32_16x16x32_bf16 v[102:105], v[138:141], v[186:189], v[102:105]
	v_mfma_f32_16x16x32_bf16 v[94:97], v[146:149], v[186:189], v[94:97]
	v_mfma_f32_16x16x32_bf16 v[86:89], v[138:141], v[194:197], v[86:89]
	v_mfma_f32_16x16x32_bf16 v[78:81], v[146:149], v[194:197], v[78:81]
	v_mfma_f32_16x16x32_bf16 v[126:129], v[142:145], v[174:177], v[126:129]
	v_mfma_f32_16x16x32_bf16 v[122:125], v[150:153], v[174:177], v[122:125]
	v_mfma_f32_16x16x32_bf16 v[118:121], v[142:145], v[182:185], v[118:121]
	v_mfma_f32_16x16x32_bf16 v[110:113], v[150:153], v[182:185], v[110:113]
	v_mfma_f32_16x16x32_bf16 v[102:105], v[142:145], v[190:193], v[102:105]
	v_mfma_f32_16x16x32_bf16 v[94:97], v[150:153], v[190:193], v[94:97]
	v_mfma_f32_16x16x32_bf16 v[86:89], v[142:145], v[198:201], v[86:89]
	v_mfma_f32_16x16x32_bf16 v[78:81], v[150:153], v[198:201], v[78:81]
	s_setprio 0
	s_setprio 1
	v_mfma_f32_16x16x32_bf16 v[114:117], v[154:157], v[170:173], v[114:117]
	v_mfma_f32_16x16x32_bf16 v[106:109], v[162:165], v[170:173], v[106:109]
	v_mfma_f32_16x16x32_bf16 v[98:101], v[154:157], v[178:181], v[98:101]
	v_mfma_f32_16x16x32_bf16 v[90:93], v[162:165], v[178:181], v[90:93]
	v_mfma_f32_16x16x32_bf16 v[82:85], v[154:157], v[186:189], v[82:85]
	v_mfma_f32_16x16x32_bf16 v[74:77], v[162:165], v[186:189], v[74:77]
	v_mfma_f32_16x16x32_bf16 v[70:73], v[154:157], v[194:197], v[70:73]
	v_mfma_f32_16x16x32_bf16 v[62:65], v[162:165], v[194:197], v[62:65]
	v_mfma_f32_16x16x32_bf16 v[114:117], v[158:161], v[174:177], v[114:117]
	v_mfma_f32_16x16x32_bf16 v[106:109], v[166:169], v[174:177], v[106:109]
	v_mfma_f32_16x16x32_bf16 v[98:101], v[158:161], v[182:185], v[98:101]
	v_mfma_f32_16x16x32_bf16 v[90:93], v[166:169], v[182:185], v[90:93]
	v_mfma_f32_16x16x32_bf16 v[82:85], v[158:161], v[190:193], v[82:85]
	v_mfma_f32_16x16x32_bf16 v[74:77], v[166:169], v[190:193], v[74:77]
	v_mfma_f32_16x16x32_bf16 v[70:73], v[158:161], v[198:201], v[70:73]
	v_mfma_f32_16x16x32_bf16 v[62:65], v[166:169], v[198:201], v[62:65]
	s_setprio 0
	s_barrier
	ds_read_b128 v[170:173], v137 offset:49152
	ds_read_b128 v[174:177], v137 offset:50176
	ds_read_b128 v[178:181], v137 offset:51200
	ds_read_b128 v[182:185], v137 offset:52224
	ds_read_b128 v[186:189], v137 offset:53248
	ds_read_b128 v[190:193], v137 offset:54272
	ds_read_b128 v[194:197], v137 offset:55296
	ds_read_b128 v[198:201], v137 offset:56320
	s_mov_b32 m0, s70
	s_add_u32 s100, s46, s38
	s_addc_u32 s101, s47, s39
	global_load_lds_dwordx4 v131, s[100:101]
	s_mov_b32 m0, s69
	s_nop 0
	global_load_lds_dwordx4 v133, s[100:101]
	s_mov_b32 m0, s79
	s_nop 0
	global_load_lds_dwordx4 v131, s[48:49]
	s_mov_b32 m0, s78
	s_nop 0
	global_load_lds_dwordx4 v133, s[48:49]
	s_mov_b32 m0, s67
	s_add_u32 s100, s22, s38
	s_addc_u32 s101, s23, s39
	v_mov_b32_e32 v0, v132
	global_load_lds_dwordx4 v130, s[100:101]
	s_mov_b32 m0, s68
	s_nop 0
	global_load_lds_dwordx4 v132, s[100:101]
	s_waitcnt vmcnt(8) lgkmcnt(0)
	s_setprio 1
	s_barrier
	v_mfma_f32_16x16x32_bf16 v[66:69], v[138:141], v[170:173], v[66:69]
	v_mfma_f32_16x16x32_bf16 v[58:61], v[146:149], v[170:173], v[58:61]
	v_mfma_f32_16x16x32_bf16 v[54:57], v[138:141], v[178:181], v[54:57]
	v_mfma_f32_16x16x32_bf16 v[46:49], v[146:149], v[178:181], v[46:49]
	v_mfma_f32_16x16x32_bf16 v[38:41], v[138:141], v[186:189], v[38:41]
	v_mfma_f32_16x16x32_bf16 v[30:33], v[146:149], v[186:189], v[30:33]
	v_mfma_f32_16x16x32_bf16 v[22:25], v[138:141], v[194:197], v[22:25]
	v_mfma_f32_16x16x32_bf16 v[14:17], v[146:149], v[194:197], v[14:17]
	v_mfma_f32_16x16x32_bf16 v[66:69], v[142:145], v[174:177], v[66:69]
	v_mfma_f32_16x16x32_bf16 v[58:61], v[150:153], v[174:177], v[58:61]
	v_mfma_f32_16x16x32_bf16 v[54:57], v[142:145], v[182:185], v[54:57]
	v_mfma_f32_16x16x32_bf16 v[46:49], v[150:153], v[182:185], v[46:49]
	v_mfma_f32_16x16x32_bf16 v[38:41], v[142:145], v[190:193], v[38:41]
	v_mfma_f32_16x16x32_bf16 v[30:33], v[150:153], v[190:193], v[30:33]
	v_mfma_f32_16x16x32_bf16 v[22:25], v[142:145], v[198:201], v[22:25]
	v_mfma_f32_16x16x32_bf16 v[14:17], v[150:153], v[198:201], v[14:17]
	s_setprio 0
	s_setprio 1
	v_mfma_f32_16x16x32_bf16 v[50:53], v[154:157], v[170:173], v[50:53]
	v_mfma_f32_16x16x32_bf16 v[42:45], v[162:165], v[170:173], v[42:45]
	v_mfma_f32_16x16x32_bf16 v[34:37], v[154:157], v[178:181], v[34:37]
	v_mfma_f32_16x16x32_bf16 v[26:29], v[162:165], v[178:181], v[26:29]
	v_mfma_f32_16x16x32_bf16 v[18:21], v[154:157], v[186:189], v[18:21]
	v_mfma_f32_16x16x32_bf16 v[10:13], v[162:165], v[186:189], v[10:13]
	v_mfma_f32_16x16x32_bf16 v[6:9], v[154:157], v[194:197], v[6:9]
	v_mfma_f32_16x16x32_bf16 v[2:5], v[162:165], v[194:197], v[2:5]
	v_mfma_f32_16x16x32_bf16 v[50:53], v[158:161], v[174:177], v[50:53]
	v_mfma_f32_16x16x32_bf16 v[42:45], v[166:169], v[174:177], v[42:45]
	v_mfma_f32_16x16x32_bf16 v[34:37], v[158:161], v[182:185], v[34:37]
	v_mfma_f32_16x16x32_bf16 v[26:29], v[166:169], v[182:185], v[26:29]
	v_mfma_f32_16x16x32_bf16 v[18:21], v[158:161], v[190:193], v[18:21]
	v_mfma_f32_16x16x32_bf16 v[10:13], v[166:169], v[190:193], v[10:13]
	v_mfma_f32_16x16x32_bf16 v[6:9], v[158:161], v[198:201], v[6:9]
	v_mfma_f32_16x16x32_bf16 v[2:5], v[166:169], v[198:201], v[2:5]
	s_setprio 0
	s_barrier
	s_andn2_b64 vcc, exec, s[16:17]
	s_mov_b64 s[46:47], -1
	s_mov_b64 s[16:17], 0
	s_mov_b64 s[48:49], 0x100
	s_cbranch_vccz .LBB0_634
	s_cmpk_lt_u32 s25, 0x100
	s_cbranch_scc0 .LBB0_637
	s_barrier

.LBB0_667:
	s_add_u32 s4, s70, s50
	s_addc_u32 s5, s71, s51
	s_add_u32 s46, s4, 0x9400100
	s_addc_u32 s47, s5, 0
	s_add_u32 s58, s74, s50
	s_addc_u32 s59, s75, s51
	s_add_i32 s77, 0, 0x10000
	s_cmpk_eq_i32 s50, 0x300
	s_cselect_b32 s47, s23, s47
	s_cselect_b32 s46, s22, s46
	v_add_u32_e32 v0, s77, v144
	s_cselect_b32 s59, s49, s59
	s_cselect_b32 s58, s48, s58
	s_add_i32 s78, 0, 0x14000
	ds_read_b128 v[146:149], v0
	ds_read_b128 v[150:153], v0 offset:1024
	ds_read_b128 v[154:157], v0 offset:2048
	ds_read_b128 v[158:161], v0 offset:3072
	ds_read_b128 v[162:165], v0 offset:16384
	ds_read_b128 v[166:169], v0 offset:17408
	ds_read_b128 v[170:173], v0 offset:18432
	ds_read_b128 v[174:177], v0 offset:19456
	ds_read_b128 v[178:181], v145
	ds_read_b128 v[182:185], v145 offset:1024
	ds_read_b128 v[186:189], v145 offset:2048
	ds_read_b128 v[190:193], v145 offset:3072
	ds_read_b128 v[194:197], v145 offset:4096
	ds_read_b128 v[198:201], v145 offset:5120
	ds_read_b128 v[202:205], v145 offset:6144
	ds_read_b128 v[206:209], v145 offset:7168
	s_add_i32 m0, s61, 0xc000
	s_add_u32 s100, s4, s54
	s_addc_u32 s101, s5, s55
	global_load_lds_dwordx4 v130, s[100:101]
	s_add_i32 m0, s61, 0xe000
	s_nop 0
	global_load_lds_dwordx4 v141, s[100:101]
	s_waitcnt vmcnt(8) lgkmcnt(0)
	s_setprio 1
	s_barrier
	v_mfma_i32_16x16x64_i8 v[126:129], v[146:149], v[178:181], v[126:129]
	v_mfma_i32_16x16x64_i8 v[122:125], v[154:157], v[178:181], v[122:125]
	v_mfma_i32_16x16x64_i8 v[110:113], v[146:149], v[186:189], v[110:113]
	v_mfma_i32_16x16x64_i8 v[106:109], v[154:157], v[186:189], v[106:109]
	v_mfma_i32_16x16x64_i8 v[94:97], v[146:149], v[194:197], v[94:97]
	v_mfma_i32_16x16x64_i8 v[90:93], v[154:157], v[194:197], v[90:93]
	v_mfma_i32_16x16x64_i8 v[78:81], v[146:149], v[202:205], v[78:81]
	v_mfma_i32_16x16x64_i8 v[74:77], v[154:157], v[202:205], v[74:77]
	v_mfma_i32_16x16x64_i8 v[126:129], v[150:153], v[182:185], v[126:129]
	v_mfma_i32_16x16x64_i8 v[122:125], v[158:161], v[182:185], v[122:125]
	v_mfma_i32_16x16x64_i8 v[110:113], v[150:153], v[190:193], v[110:113]
	v_mfma_i32_16x16x64_i8 v[106:109], v[158:161], v[190:193], v[106:109]
	v_mfma_i32_16x16x64_i8 v[94:97], v[150:153], v[198:201], v[94:97]
	v_mfma_i32_16x16x64_i8 v[90:93], v[158:161], v[198:201], v[90:93]
	v_mfma_i32_16x16x64_i8 v[78:81], v[150:153], v[206:209], v[78:81]
	v_mfma_i32_16x16x64_i8 v[74:77], v[158:161], v[206:209], v[74:77]
	s_setprio 0
	s_setprio 1
	v_mfma_i32_16x16x64_i8 v[118:121], v[162:165], v[178:181], v[118:121]
	v_mfma_i32_16x16x64_i8 v[114:117], v[170:173], v[178:181], v[114:117]
	v_mfma_i32_16x16x64_i8 v[102:105], v[162:165], v[186:189], v[102:105]
	v_mfma_i32_16x16x64_i8 v[98:101], v[170:173], v[186:189], v[98:101]
	v_mfma_i32_16x16x64_i8 v[86:89], v[162:165], v[194:197], v[86:89]
	v_mfma_i32_16x16x64_i8 v[82:85], v[170:173], v[194:197], v[82:85]
	v_mfma_i32_16x16x64_i8 v[70:73], v[162:165], v[202:205], v[70:73]
	v_mfma_i32_16x16x64_i8 v[66:69], v[170:173], v[202:205], v[66:69]
	v_mfma_i32_16x16x64_i8 v[118:121], v[166:169], v[182:185], v[118:121]
	v_mfma_i32_16x16x64_i8 v[114:117], v[174:177], v[182:185], v[114:117]
	v_mfma_i32_16x16x64_i8 v[102:105], v[166:169], v[190:193], v[102:105]
	v_mfma_i32_16x16x64_i8 v[98:101], v[174:177], v[190:193], v[98:101]
	v_mfma_i32_16x16x64_i8 v[86:89], v[166:169], v[198:201], v[86:89]
	v_mfma_i32_16x16x64_i8 v[82:85], v[174:177], v[198:201], v[82:85]
	v_mfma_i32_16x16x64_i8 v[70:73], v[166:169], v[206:209], v[70:73]
	v_mfma_i32_16x16x64_i8 v[66:69], v[174:177], v[206:209], v[66:69]
	s_setprio 0
	s_barrier
	s_add_i32 s4, s77, s60
	ds_read_b128 v[178:181], v145 offset:16384
	ds_read_b128 v[182:185], v145 offset:17408
	ds_read_b128 v[186:189], v145 offset:18432
	ds_read_b128 v[190:193], v145 offset:19456
	ds_read_b128 v[194:197], v145 offset:20480
	ds_read_b128 v[198:201], v145 offset:21504
	ds_read_b128 v[202:205], v145 offset:22528
	ds_read_b128 v[206:209], v145 offset:23552
	s_mov_b32 m0, s4
	s_nop 0
	global_load_lds_dwordx4 v131, s[58:59]
	s_add_i32 m0, s4, 0x2000
	s_add_u32 s4, s58, 0x20000
	global_load_lds_dwordx4 v142, s[58:59]
	s_addc_u32 s5, s59, 0
	s_add_i32 s77, s78, s60
	s_mov_b32 m0, s77
	s_nop 0
	global_load_lds_dwordx4 v131, s[4:5]
	s_add_i32 m0, s77, 0x2000
	s_nop 0
	global_load_lds_dwordx4 v142, s[4:5]
	s_mov_b32 m0, s61
	s_nop 0
	global_load_lds_dwordx4 v130, s[46:47]
	s_mov_b32 m0, s65
	s_nop 0
	global_load_lds_dwordx4 v141, s[46:47]
	s_waitcnt vmcnt(8) lgkmcnt(0)
	s_setprio 1
	s_barrier
	v_mfma_i32_16x16x64_i8 v[62:65], v[146:149], v[178:181], v[62:65]
	v_mfma_i32_16x16x64_i8 v[58:61], v[154:157], v[178:181], v[58:61]
	v_mfma_i32_16x16x64_i8 v[46:49], v[146:149], v[186:189], v[46:49]
	v_mfma_i32_16x16x64_i8 v[42:45], v[154:157], v[186:189], v[42:45]
	v_mfma_i32_16x16x64_i8 v[30:33], v[146:149], v[194:197], v[30:33]
	v_mfma_i32_16x16x64_i8 v[26:29], v[154:157], v[194:197], v[26:29]
	v_mfma_i32_16x16x64_i8 v[14:17], v[146:149], v[202:205], v[14:17]
	v_mfma_i32_16x16x64_i8 v[10:13], v[154:157], v[202:205], v[10:13]
	v_mfma_i32_16x16x64_i8 v[62:65], v[150:153], v[182:185], v[62:65]
	v_mfma_i32_16x16x64_i8 v[58:61], v[158:161], v[182:185], v[58:61]
	v_mfma_i32_16x16x64_i8 v[46:49], v[150:153], v[190:193], v[46:49]
	v_mfma_i32_16x16x64_i8 v[42:45], v[158:161], v[190:193], v[42:45]
	v_mfma_i32_16x16x64_i8 v[30:33], v[150:153], v[198:201], v[30:33]
	v_mfma_i32_16x16x64_i8 v[26:29], v[158:161], v[198:201], v[26:29]
	v_mfma_i32_16x16x64_i8 v[14:17], v[150:153], v[206:209], v[14:17]
	v_mfma_i32_16x16x64_i8 v[10:13], v[158:161], v[206:209], v[10:13]
	s_setprio 0
	s_setprio 1
	v_mfma_i32_16x16x64_i8 v[54:57], v[162:165], v[178:181], v[54:57]
	v_mfma_i32_16x16x64_i8 v[50:53], v[170:173], v[178:181], v[50:53]
	v_mfma_i32_16x16x64_i8 v[38:41], v[162:165], v[186:189], v[38:41]
	v_mfma_i32_16x16x64_i8 v[34:37], v[170:173], v[186:189], v[34:37]
	v_mfma_i32_16x16x64_i8 v[22:25], v[162:165], v[194:197], v[22:25]
	v_mfma_i32_16x16x64_i8 v[18:21], v[170:173], v[194:197], v[18:21]
	v_mfma_i32_16x16x64_i8 v[6:9], v[162:165], v[202:205], v[6:9]
	v_mfma_i32_16x16x64_i8 v[2:5], v[170:173], v[202:205], v[2:5]
	v_mfma_i32_16x16x64_i8 v[54:57], v[166:169], v[182:185], v[54:57]
	v_mfma_i32_16x16x64_i8 v[50:53], v[174:177], v[182:185], v[50:53]
	v_mfma_i32_16x16x64_i8 v[38:41], v[166:169], v[190:193], v[38:41]
	v_mfma_i32_16x16x64_i8 v[34:37], v[174:177], v[190:193], v[34:37]
	v_mfma_i32_16x16x64_i8 v[22:25], v[166:169], v[198:201], v[22:25]
	v_mfma_i32_16x16x64_i8 v[18:21], v[174:177], v[198:201], v[18:21]
	v_mfma_i32_16x16x64_i8 v[6:9], v[166:169], v[206:209], v[6:9]
	v_mfma_i32_16x16x64_i8 v[2:5], v[174:177], v[206:209], v[2:5]
	s_setprio 0
	s_barrier
	s_add_i32 s77, 0, 0x18000
	s_add_i32 s78, 0, 0x1c000
	ds_read_b128 v[146:149], v0 offset:32768
	ds_read_b128 v[150:153], v0 offset:33792
	ds_read_b128 v[154:157], v0 offset:34816
	ds_read_b128 v[158:161], v0 offset:35840
	ds_read_b128 v[162:165], v0 offset:49152
	ds_read_b128 v[166:169], v0 offset:50176
	ds_read_b128 v[170:173], v0 offset:51200
	ds_read_b128 v[174:177], v0 offset:52224
	s_add_u32 s4, s46, 0x20000
	s_mov_b32 m0, s66
	ds_read_b128 v[178:181], v145 offset:32768
	ds_read_b128 v[182:185], v145 offset:33792
	ds_read_b128 v[186:189], v145 offset:34816
	ds_read_b128 v[190:193], v145 offset:35840
	ds_read_b128 v[194:197], v145 offset:36864
	ds_read_b128 v[198:201], v145 offset:37888
	ds_read_b128 v[202:205], v145 offset:38912
	ds_read_b128 v[206:209], v145 offset:39936
	s_addc_u32 s5, s47, 0
	s_nop 0
	global_load_lds_dwordx4 v130, s[4:5]
	s_mov_b32 m0, s67
	s_nop 0
	global_load_lds_dwordx4 v141, s[4:5]
	s_waitcnt vmcnt(8) lgkmcnt(0)
	s_setprio 1
	s_barrier
	v_mfma_i32_16x16x64_i8 v[126:129], v[146:149], v[178:181], v[126:129]
	v_mfma_i32_16x16x64_i8 v[122:125], v[154:157], v[178:181], v[122:125]
	v_mfma_i32_16x16x64_i8 v[110:113], v[146:149], v[186:189], v[110:113]
	v_mfma_i32_16x16x64_i8 v[106:109], v[154:157], v[186:189], v[106:109]
	v_mfma_i32_16x16x64_i8 v[94:97], v[146:149], v[194:197], v[94:97]
	v_mfma_i32_16x16x64_i8 v[90:93], v[154:157], v[194:197], v[90:93]
	v_mfma_i32_16x16x64_i8 v[78:81], v[146:149], v[202:205], v[78:81]
	v_mfma_i32_16x16x64_i8 v[74:77], v[154:157], v[202:205], v[74:77]
	v_mfma_i32_16x16x64_i8 v[126:129], v[150:153], v[182:185], v[126:129]
	v_mfma_i32_16x16x64_i8 v[122:125], v[158:161], v[182:185], v[122:125]
	v_mfma_i32_16x16x64_i8 v[110:113], v[150:153], v[190:193], v[110:113]
	v_mfma_i32_16x16x64_i8 v[106:109], v[158:161], v[190:193], v[106:109]
	v_mfma_i32_16x16x64_i8 v[94:97], v[150:153], v[198:201], v[94:97]
	v_mfma_i32_16x16x64_i8 v[90:93], v[158:161], v[198:201], v[90:93]
	v_mfma_i32_16x16x64_i8 v[78:81], v[150:153], v[206:209], v[78:81]
	v_mfma_i32_16x16x64_i8 v[74:77], v[158:161], v[206:209], v[74:77]
	s_setprio 0
	s_setprio 1
	v_mfma_i32_16x16x64_i8 v[118:121], v[162:165], v[178:181], v[118:121]
	v_mfma_i32_16x16x64_i8 v[114:117], v[170:173], v[178:181], v[114:117]
	v_mfma_i32_16x16x64_i8 v[102:105], v[162:165], v[186:189], v[102:105]
	v_mfma_i32_16x16x64_i8 v[98:101], v[170:173], v[186:189], v[98:101]
	v_mfma_i32_16x16x64_i8 v[86:89], v[162:165], v[194:197], v[86:89]
	v_mfma_i32_16x16x64_i8 v[82:85], v[170:173], v[194:197], v[82:85]
	v_mfma_i32_16x16x64_i8 v[70:73], v[162:165], v[202:205], v[70:73]
	v_mfma_i32_16x16x64_i8 v[66:69], v[170:173], v[202:205], v[66:69]
	v_mfma_i32_16x16x64_i8 v[118:121], v[166:169], v[182:185], v[118:121]
	v_mfma_i32_16x16x64_i8 v[114:117], v[174:177], v[182:185], v[114:117]
	v_mfma_i32_16x16x64_i8 v[102:105], v[166:169], v[190:193], v[102:105]
	v_mfma_i32_16x16x64_i8 v[98:101], v[174:177], v[190:193], v[98:101]
	v_mfma_i32_16x16x64_i8 v[86:89], v[166:169], v[198:201], v[86:89]
	v_mfma_i32_16x16x64_i8 v[82:85], v[174:177], v[198:201], v[82:85]
	v_mfma_i32_16x16x64_i8 v[70:73], v[166:169], v[206:209], v[70:73]
	v_mfma_i32_16x16x64_i8 v[66:69], v[174:177], v[206:209], v[66:69]
	s_setprio 0
	s_barrier
	ds_read_b128 v[178:181], v145 offset:49152
	ds_read_b128 v[182:185], v145 offset:50176
	ds_read_b128 v[186:189], v145 offset:51200
	ds_read_b128 v[190:193], v145 offset:52224
	ds_read_b128 v[194:197], v145 offset:53248
	ds_read_b128 v[198:201], v145 offset:54272
	ds_read_b128 v[202:205], v145 offset:55296
	ds_read_b128 v[206:209], v145 offset:56320
	s_add_i32 s4, s77, s60
	s_add_u32 s100, s58, s38
	s_addc_u32 s101, s59, s39
	s_mov_b32 m0, s4
	s_nop 0
	global_load_lds_dwordx4 v131, s[100:101]
	s_add_i32 m0, s4, 0x2000
	s_add_u32 s4, s58, 0x20080
	s_addc_u32 s5, s59, 0
	s_add_i32 s58, s78, s60
	global_load_lds_dwordx4 v142, s[100:101]
	s_mov_b32 m0, s58
	s_nop 0
	global_load_lds_dwordx4 v131, s[4:5]
	s_add_i32 m0, s58, 0x2000
	s_nop 0
	global_load_lds_dwordx4 v142, s[4:5]
	s_mov_b32 m0, s68
	s_add_u32 s100, s46, s38
	s_addc_u32 s101, s47, s39
	v_mov_b32_e32 v0, v141
	global_load_lds_dwordx4 v130, s[100:101]
	s_mov_b32 m0, s69
	s_nop 0
	global_load_lds_dwordx4 v141, s[100:101]
	s_waitcnt vmcnt(8) lgkmcnt(0)
	s_setprio 1
	s_barrier
	v_mfma_i32_16x16x64_i8 v[62:65], v[146:149], v[178:181], v[62:65]
	v_mfma_i32_16x16x64_i8 v[58:61], v[154:157], v[178:181], v[58:61]
	v_mfma_i32_16x16x64_i8 v[46:49], v[146:149], v[186:189], v[46:49]
	v_mfma_i32_16x16x64_i8 v[42:45], v[154:157], v[186:189], v[42:45]
	v_mfma_i32_16x16x64_i8 v[30:33], v[146:149], v[194:197], v[30:33]
	v_mfma_i32_16x16x64_i8 v[26:29], v[154:157], v[194:197], v[26:29]
	v_mfma_i32_16x16x64_i8 v[14:17], v[146:149], v[202:205], v[14:17]
	v_mfma_i32_16x16x64_i8 v[10:13], v[154:157], v[202:205], v[10:13]
	v_mfma_i32_16x16x64_i8 v[62:65], v[150:153], v[182:185], v[62:65]
	v_mfma_i32_16x16x64_i8 v[58:61], v[158:161], v[182:185], v[58:61]
	v_mfma_i32_16x16x64_i8 v[46:49], v[150:153], v[190:193], v[46:49]
	v_mfma_i32_16x16x64_i8 v[42:45], v[158:161], v[190:193], v[42:45]
	v_mfma_i32_16x16x64_i8 v[30:33], v[150:153], v[198:201], v[30:33]
	v_mfma_i32_16x16x64_i8 v[26:29], v[158:161], v[198:201], v[26:29]
	v_mfma_i32_16x16x64_i8 v[14:17], v[150:153], v[206:209], v[14:17]
	v_mfma_i32_16x16x64_i8 v[10:13], v[158:161], v[206:209], v[10:13]
	s_setprio 0
	s_setprio 1
	v_mfma_i32_16x16x64_i8 v[54:57], v[162:165], v[178:181], v[54:57]
	v_mfma_i32_16x16x64_i8 v[50:53], v[170:173], v[178:181], v[50:53]
	v_mfma_i32_16x16x64_i8 v[38:41], v[162:165], v[186:189], v[38:41]
	v_mfma_i32_16x16x64_i8 v[34:37], v[170:173], v[186:189], v[34:37]
	v_mfma_i32_16x16x64_i8 v[22:25], v[162:165], v[194:197], v[22:25]
	v_mfma_i32_16x16x64_i8 v[18:21], v[170:173], v[194:197], v[18:21]
	v_mfma_i32_16x16x64_i8 v[6:9], v[162:165], v[202:205], v[6:9]
	v_mfma_i32_16x16x64_i8 v[2:5], v[170:173], v[202:205], v[2:5]
	v_mfma_i32_16x16x64_i8 v[54:57], v[166:169], v[182:185], v[54:57]
	v_mfma_i32_16x16x64_i8 v[50:53], v[174:177], v[182:185], v[50:53]
	v_mfma_i32_16x16x64_i8 v[38:41], v[166:169], v[190:193], v[38:41]
	v_mfma_i32_16x16x64_i8 v[34:37], v[174:177], v[190:193], v[34:37]
	v_mfma_i32_16x16x64_i8 v[22:25], v[166:169], v[198:201], v[22:25]
	v_mfma_i32_16x16x64_i8 v[18:21], v[174:177], v[198:201], v[18:21]
	v_mfma_i32_16x16x64_i8 v[6:9], v[166:169], v[206:209], v[6:9]
	v_mfma_i32_16x16x64_i8 v[2:5], v[174:177], v[206:209], v[2:5]
	s_setprio 0
	s_barrier
	s_add_i32 s76, s76, 2
	s_add_u32 s50, s50, 0x100
	s_addc_u32 s51, s51, 0
	s_cmp_gt_u32 s76, 5
	s_cbranch_scc0 .LBB0_667
	s_cmpk_lt_u32 s17, 0x100
	s_cbranch_scc0 .LBB0_661
	s_barrier
	s_branch .LBB0_661

.LBB0_821:
	s_add_u32 s4, s79, s50
	s_addc_u32 s5, s82, s51
	s_add_u32 s46, s4, 0x9800100
	s_addc_u32 s47, s5, 0
	s_add_u32 s58, s64, s50
	s_addc_u32 s59, s83, s51
	s_add_i32 s85, 0, 0x10000
	s_cmpk_eq_i32 s50, 0x1500
	s_cselect_b32 s47, s49, s47
	s_cselect_b32 s46, s48, s46
	v_add_u32_e32 v0, s85, v134
	s_cselect_b32 s59, s71, s59
	s_cselect_b32 s58, s70, s58
	s_add_i32 s86, 0, 0x14000
	ds_read_b128 v[136:139], v0
	ds_read_b128 v[140:143], v0 offset:1024
	ds_read_b128 v[144:147], v0 offset:2048
	ds_read_b128 v[148:151], v0 offset:3072
	ds_read_b128 v[152:155], v0 offset:16384
	ds_read_b128 v[156:159], v0 offset:17408
	ds_read_b128 v[160:163], v0 offset:18432
	ds_read_b128 v[164:167], v0 offset:19456
	ds_read_b128 v[168:171], v135
	ds_read_b128 v[172:175], v135 offset:1024
	ds_read_b128 v[176:179], v135 offset:2048
	ds_read_b128 v[180:183], v135 offset:3072
	ds_read_b128 v[184:187], v135 offset:4096
	ds_read_b128 v[188:191], v135 offset:5120
	ds_read_b128 v[192:195], v135 offset:6144
	ds_read_b128 v[198:201], v135 offset:7168
	s_add_i32 m0, s60, 0xc000
	s_add_u32 s100, s4, s88
	s_addc_u32 s101, s5, s89
	global_load_lds_dwordx4 v130, s[100:101]
	s_add_i32 m0, s60, 0xe000
	s_nop 0
	global_load_lds_dwordx4 v131, s[100:101]
	s_waitcnt vmcnt(8) lgkmcnt(0)
	s_setprio 1
	s_barrier
	v_mfma_f32_16x16x32_bf16 v[126:129], v[136:139], v[168:171], v[126:129]
	v_mfma_f32_16x16x32_bf16 v[122:125], v[144:147], v[168:171], v[122:125]
	v_mfma_f32_16x16x32_bf16 v[110:113], v[136:139], v[176:179], v[110:113]
	v_mfma_f32_16x16x32_bf16 v[106:109], v[144:147], v[176:179], v[106:109]
	v_mfma_f32_16x16x32_bf16 v[94:97], v[136:139], v[184:187], v[94:97]
	v_mfma_f32_16x16x32_bf16 v[90:93], v[144:147], v[184:187], v[90:93]
	v_mfma_f32_16x16x32_bf16 v[78:81], v[136:139], v[192:195], v[78:81]
	v_mfma_f32_16x16x32_bf16 v[74:77], v[144:147], v[192:195], v[74:77]
	v_mfma_f32_16x16x32_bf16 v[126:129], v[140:143], v[172:175], v[126:129]
	v_mfma_f32_16x16x32_bf16 v[122:125], v[148:151], v[172:175], v[122:125]
	v_mfma_f32_16x16x32_bf16 v[110:113], v[140:143], v[180:183], v[110:113]
	v_mfma_f32_16x16x32_bf16 v[106:109], v[148:151], v[180:183], v[106:109]
	v_mfma_f32_16x16x32_bf16 v[94:97], v[140:143], v[188:191], v[94:97]
	v_mfma_f32_16x16x32_bf16 v[90:93], v[148:151], v[188:191], v[90:93]
	v_mfma_f32_16x16x32_bf16 v[78:81], v[140:143], v[198:201], v[78:81]
	v_mfma_f32_16x16x32_bf16 v[74:77], v[148:151], v[198:201], v[74:77]
	s_setprio 0
	s_setprio 1
	v_mfma_f32_16x16x32_bf16 v[118:121], v[152:155], v[168:171], v[118:121]
	v_mfma_f32_16x16x32_bf16 v[114:117], v[160:163], v[168:171], v[114:117]
	v_mfma_f32_16x16x32_bf16 v[102:105], v[152:155], v[176:179], v[102:105]
	v_mfma_f32_16x16x32_bf16 v[98:101], v[160:163], v[176:179], v[98:101]
	v_mfma_f32_16x16x32_bf16 v[86:89], v[152:155], v[184:187], v[86:89]
	v_mfma_f32_16x16x32_bf16 v[82:85], v[160:163], v[184:187], v[82:85]
	v_mfma_f32_16x16x32_bf16 v[70:73], v[152:155], v[192:195], v[70:73]
	v_mfma_f32_16x16x32_bf16 v[66:69], v[160:163], v[192:195], v[66:69]
	v_mfma_f32_16x16x32_bf16 v[118:121], v[156:159], v[172:175], v[118:121]
	v_mfma_f32_16x16x32_bf16 v[114:117], v[164:167], v[172:175], v[114:117]
	v_mfma_f32_16x16x32_bf16 v[102:105], v[156:159], v[180:183], v[102:105]
	v_mfma_f32_16x16x32_bf16 v[98:101], v[164:167], v[180:183], v[98:101]
	v_mfma_f32_16x16x32_bf16 v[86:89], v[156:159], v[188:191], v[86:89]
	v_mfma_f32_16x16x32_bf16 v[82:85], v[164:167], v[188:191], v[82:85]
	v_mfma_f32_16x16x32_bf16 v[70:73], v[156:159], v[198:201], v[70:73]
	v_mfma_f32_16x16x32_bf16 v[66:69], v[164:167], v[198:201], v[66:69]
	s_setprio 0
	s_barrier
	s_add_i32 s4, s85, s26
	ds_read_b128 v[168:171], v135 offset:16384
	ds_read_b128 v[172:175], v135 offset:17408
	ds_read_b128 v[176:179], v135 offset:18432
	ds_read_b128 v[180:183], v135 offset:19456
	ds_read_b128 v[184:187], v135 offset:20480
	ds_read_b128 v[188:191], v135 offset:21504
	ds_read_b128 v[192:195], v135 offset:22528
	ds_read_b128 v[198:201], v135 offset:23552
	s_mov_b32 m0, s4
	s_nop 0
	global_load_lds_dwordx4 v132, s[58:59]
	s_add_i32 m0, s4, 0x2000
	s_add_u32 s4, s58, 0xb0000
	global_load_lds_dwordx4 v133, s[58:59]
	s_addc_u32 s5, s59, 0
	s_add_i32 s85, s86, s26
	s_mov_b32 m0, s85
	s_nop 0
	global_load_lds_dwordx4 v132, s[4:5]
	s_add_i32 m0, s85, 0x2000
	s_nop 0
	global_load_lds_dwordx4 v133, s[4:5]
	s_mov_b32 m0, s60
	s_nop 0
	global_load_lds_dwordx4 v130, s[46:47]
	s_mov_b32 m0, s65
	s_nop 0
	global_load_lds_dwordx4 v131, s[46:47]
	s_waitcnt vmcnt(8) lgkmcnt(0)
	s_setprio 1
	s_barrier
	v_mfma_f32_16x16x32_bf16 v[62:65], v[136:139], v[168:171], v[62:65]
	v_mfma_f32_16x16x32_bf16 v[58:61], v[144:147], v[168:171], v[58:61]
	v_mfma_f32_16x16x32_bf16 v[46:49], v[136:139], v[176:179], v[46:49]
	v_mfma_f32_16x16x32_bf16 v[42:45], v[144:147], v[176:179], v[42:45]
	v_mfma_f32_16x16x32_bf16 v[30:33], v[136:139], v[184:187], v[30:33]
	v_mfma_f32_16x16x32_bf16 v[26:29], v[144:147], v[184:187], v[26:29]
	v_mfma_f32_16x16x32_bf16 v[14:17], v[136:139], v[192:195], v[14:17]
	v_mfma_f32_16x16x32_bf16 v[10:13], v[144:147], v[192:195], v[10:13]
	v_mfma_f32_16x16x32_bf16 v[62:65], v[140:143], v[172:175], v[62:65]
	v_mfma_f32_16x16x32_bf16 v[58:61], v[148:151], v[172:175], v[58:61]
	v_mfma_f32_16x16x32_bf16 v[46:49], v[140:143], v[180:183], v[46:49]
	v_mfma_f32_16x16x32_bf16 v[42:45], v[148:151], v[180:183], v[42:45]
	v_mfma_f32_16x16x32_bf16 v[30:33], v[140:143], v[188:191], v[30:33]
	v_mfma_f32_16x16x32_bf16 v[26:29], v[148:151], v[188:191], v[26:29]
	v_mfma_f32_16x16x32_bf16 v[14:17], v[140:143], v[198:201], v[14:17]
	v_mfma_f32_16x16x32_bf16 v[10:13], v[148:151], v[198:201], v[10:13]
	s_setprio 0
	s_setprio 1
	v_mfma_f32_16x16x32_bf16 v[54:57], v[152:155], v[168:171], v[54:57]
	v_mfma_f32_16x16x32_bf16 v[50:53], v[160:163], v[168:171], v[50:53]
	v_mfma_f32_16x16x32_bf16 v[38:41], v[152:155], v[176:179], v[38:41]
	v_mfma_f32_16x16x32_bf16 v[34:37], v[160:163], v[176:179], v[34:37]
	v_mfma_f32_16x16x32_bf16 v[22:25], v[152:155], v[184:187], v[22:25]
	v_mfma_f32_16x16x32_bf16 v[18:21], v[160:163], v[184:187], v[18:21]
	v_mfma_f32_16x16x32_bf16 v[6:9], v[152:155], v[192:195], v[6:9]
	v_mfma_f32_16x16x32_bf16 v[2:5], v[160:163], v[192:195], v[2:5]
	v_mfma_f32_16x16x32_bf16 v[54:57], v[156:159], v[172:175], v[54:57]
	v_mfma_f32_16x16x32_bf16 v[50:53], v[164:167], v[172:175], v[50:53]
	v_mfma_f32_16x16x32_bf16 v[38:41], v[156:159], v[180:183], v[38:41]
	v_mfma_f32_16x16x32_bf16 v[34:37], v[164:167], v[180:183], v[34:37]
	v_mfma_f32_16x16x32_bf16 v[22:25], v[156:159], v[188:191], v[22:25]
	v_mfma_f32_16x16x32_bf16 v[18:21], v[164:167], v[188:191], v[18:21]
	v_mfma_f32_16x16x32_bf16 v[6:9], v[156:159], v[198:201], v[6:9]
	v_mfma_f32_16x16x32_bf16 v[2:5], v[164:167], v[198:201], v[2:5]
	s_setprio 0
	s_barrier
	s_add_i32 s85, 0, 0x18000
	s_add_i32 s86, 0, 0x1c000
	ds_read_b128 v[136:139], v0 offset:32768
	ds_read_b128 v[140:143], v0 offset:33792
	ds_read_b128 v[144:147], v0 offset:34816
	ds_read_b128 v[148:151], v0 offset:35840
	ds_read_b128 v[152:155], v0 offset:49152
	ds_read_b128 v[156:159], v0 offset:50176
	ds_read_b128 v[160:163], v0 offset:51200
	ds_read_b128 v[164:167], v0 offset:52224
	s_add_u32 s4, s46, 0xb0000
	s_mov_b32 m0, s68
	ds_read_b128 v[168:171], v135 offset:32768
	ds_read_b128 v[172:175], v135 offset:33792
	ds_read_b128 v[176:179], v135 offset:34816
	ds_read_b128 v[180:183], v135 offset:35840
	ds_read_b128 v[184:187], v135 offset:36864
	ds_read_b128 v[188:191], v135 offset:37888
	ds_read_b128 v[192:195], v135 offset:38912
	ds_read_b128 v[198:201], v135 offset:39936
	s_addc_u32 s5, s47, 0
	s_nop 0
	global_load_lds_dwordx4 v130, s[4:5]
	s_mov_b32 m0, s69
	s_nop 0
	global_load_lds_dwordx4 v131, s[4:5]
	s_waitcnt vmcnt(8) lgkmcnt(0)
	s_setprio 1
	s_barrier
	v_mfma_f32_16x16x32_bf16 v[126:129], v[136:139], v[168:171], v[126:129]
	v_mfma_f32_16x16x32_bf16 v[122:125], v[144:147], v[168:171], v[122:125]
	v_mfma_f32_16x16x32_bf16 v[110:113], v[136:139], v[176:179], v[110:113]
	v_mfma_f32_16x16x32_bf16 v[106:109], v[144:147], v[176:179], v[106:109]
	v_mfma_f32_16x16x32_bf16 v[94:97], v[136:139], v[184:187], v[94:97]
	v_mfma_f32_16x16x32_bf16 v[90:93], v[144:147], v[184:187], v[90:93]
	v_mfma_f32_16x16x32_bf16 v[78:81], v[136:139], v[192:195], v[78:81]
	v_mfma_f32_16x16x32_bf16 v[74:77], v[144:147], v[192:195], v[74:77]
	v_mfma_f32_16x16x32_bf16 v[126:129], v[140:143], v[172:175], v[126:129]
	v_mfma_f32_16x16x32_bf16 v[122:125], v[148:151], v[172:175], v[122:125]
	v_mfma_f32_16x16x32_bf16 v[110:113], v[140:143], v[180:183], v[110:113]
	v_mfma_f32_16x16x32_bf16 v[106:109], v[148:151], v[180:183], v[106:109]
	v_mfma_f32_16x16x32_bf16 v[94:97], v[140:143], v[188:191], v[94:97]
	v_mfma_f32_16x16x32_bf16 v[90:93], v[148:151], v[188:191], v[90:93]
	v_mfma_f32_16x16x32_bf16 v[78:81], v[140:143], v[198:201], v[78:81]
	v_mfma_f32_16x16x32_bf16 v[74:77], v[148:151], v[198:201], v[74:77]
	s_setprio 0
	s_setprio 1
	v_mfma_f32_16x16x32_bf16 v[118:121], v[152:155], v[168:171], v[118:121]
	v_mfma_f32_16x16x32_bf16 v[114:117], v[160:163], v[168:171], v[114:117]
	v_mfma_f32_16x16x32_bf16 v[102:105], v[152:155], v[176:179], v[102:105]
	v_mfma_f32_16x16x32_bf16 v[98:101], v[160:163], v[176:179], v[98:101]
	v_mfma_f32_16x16x32_bf16 v[86:89], v[152:155], v[184:187], v[86:89]
	v_mfma_f32_16x16x32_bf16 v[82:85], v[160:163], v[184:187], v[82:85]
	v_mfma_f32_16x16x32_bf16 v[70:73], v[152:155], v[192:195], v[70:73]
	v_mfma_f32_16x16x32_bf16 v[66:69], v[160:163], v[192:195], v[66:69]
	v_mfma_f32_16x16x32_bf16 v[118:121], v[156:159], v[172:175], v[118:121]
	v_mfma_f32_16x16x32_bf16 v[114:117], v[164:167], v[172:175], v[114:117]
	v_mfma_f32_16x16x32_bf16 v[102:105], v[156:159], v[180:183], v[102:105]
	v_mfma_f32_16x16x32_bf16 v[98:101], v[164:167], v[180:183], v[98:101]
	v_mfma_f32_16x16x32_bf16 v[86:89], v[156:159], v[188:191], v[86:89]
	v_mfma_f32_16x16x32_bf16 v[82:85], v[164:167], v[188:191], v[82:85]
	v_mfma_f32_16x16x32_bf16 v[70:73], v[156:159], v[198:201], v[70:73]
	v_mfma_f32_16x16x32_bf16 v[66:69], v[164:167], v[198:201], v[66:69]
	s_setprio 0
	s_barrier
	ds_read_b128 v[168:171], v135 offset:49152
	ds_read_b128 v[172:175], v135 offset:50176
	ds_read_b128 v[176:179], v135 offset:51200
	ds_read_b128 v[180:183], v135 offset:52224
	ds_read_b128 v[184:187], v135 offset:53248
	ds_read_b128 v[188:191], v135 offset:54272
	ds_read_b128 v[192:195], v135 offset:55296
	ds_read_b128 v[198:201], v135 offset:56320
	s_add_i32 s4, s85, s26
	s_add_u32 s100, s58, s38
	s_addc_u32 s101, s59, s39
	s_mov_b32 m0, s4
	s_nop 0
	global_load_lds_dwordx4 v132, s[100:101]
	s_add_i32 m0, s4, 0x2000
	s_add_u32 s4, s58, 0xb0080
	s_addc_u32 s5, s59, 0
	s_add_i32 s58, s86, s26
	global_load_lds_dwordx4 v133, s[100:101]
	s_mov_b32 m0, s58
	s_nop 0
	global_load_lds_dwordx4 v132, s[4:5]
	s_add_i32 m0, s58, 0x2000
	s_nop 0
	global_load_lds_dwordx4 v133, s[4:5]
	s_mov_b32 m0, s75
	s_add_u32 s100, s46, s38
	s_addc_u32 s101, s47, s39
	v_mov_b32_e32 v0, v131
	global_load_lds_dwordx4 v130, s[100:101]
	s_mov_b32 m0, s78
	s_nop 0
	global_load_lds_dwordx4 v131, s[100:101]
	s_waitcnt vmcnt(8) lgkmcnt(0)
	s_setprio 1
	s_barrier
	v_mfma_f32_16x16x32_bf16 v[62:65], v[136:139], v[168:171], v[62:65]
	v_mfma_f32_16x16x32_bf16 v[58:61], v[144:147], v[168:171], v[58:61]
	v_mfma_f32_16x16x32_bf16 v[46:49], v[136:139], v[176:179], v[46:49]
	v_mfma_f32_16x16x32_bf16 v[42:45], v[144:147], v[176:179], v[42:45]
	v_mfma_f32_16x16x32_bf16 v[30:33], v[136:139], v[184:187], v[30:33]
	v_mfma_f32_16x16x32_bf16 v[26:29], v[144:147], v[184:187], v[26:29]
	v_mfma_f32_16x16x32_bf16 v[14:17], v[136:139], v[192:195], v[14:17]
	v_mfma_f32_16x16x32_bf16 v[10:13], v[144:147], v[192:195], v[10:13]
	v_mfma_f32_16x16x32_bf16 v[62:65], v[140:143], v[172:175], v[62:65]
	v_mfma_f32_16x16x32_bf16 v[58:61], v[148:151], v[172:175], v[58:61]
	v_mfma_f32_16x16x32_bf16 v[46:49], v[140:143], v[180:183], v[46:49]
	v_mfma_f32_16x16x32_bf16 v[42:45], v[148:151], v[180:183], v[42:45]
	v_mfma_f32_16x16x32_bf16 v[30:33], v[140:143], v[188:191], v[30:33]
	v_mfma_f32_16x16x32_bf16 v[26:29], v[148:151], v[188:191], v[26:29]
	v_mfma_f32_16x16x32_bf16 v[14:17], v[140:143], v[198:201], v[14:17]
	v_mfma_f32_16x16x32_bf16 v[10:13], v[148:151], v[198:201], v[10:13]
	s_setprio 0
	s_setprio 1
	v_mfma_f32_16x16x32_bf16 v[54:57], v[152:155], v[168:171], v[54:57]
	v_mfma_f32_16x16x32_bf16 v[50:53], v[160:163], v[168:171], v[50:53]
	v_mfma_f32_16x16x32_bf16 v[38:41], v[152:155], v[176:179], v[38:41]
	v_mfma_f32_16x16x32_bf16 v[34:37], v[160:163], v[176:179], v[34:37]
	v_mfma_f32_16x16x32_bf16 v[22:25], v[152:155], v[184:187], v[22:25]
	v_mfma_f32_16x16x32_bf16 v[18:21], v[160:163], v[184:187], v[18:21]
	v_mfma_f32_16x16x32_bf16 v[6:9], v[152:155], v[192:195], v[6:9]
	v_mfma_f32_16x16x32_bf16 v[2:5], v[160:163], v[192:195], v[2:5]
	v_mfma_f32_16x16x32_bf16 v[54:57], v[156:159], v[172:175], v[54:57]
	v_mfma_f32_16x16x32_bf16 v[50:53], v[164:167], v[172:175], v[50:53]
	v_mfma_f32_16x16x32_bf16 v[38:41], v[156:159], v[180:183], v[38:41]
	v_mfma_f32_16x16x32_bf16 v[34:37], v[164:167], v[180:183], v[34:37]
	v_mfma_f32_16x16x32_bf16 v[22:25], v[156:159], v[188:191], v[22:25]
	v_mfma_f32_16x16x32_bf16 v[18:21], v[164:167], v[188:191], v[18:21]
	v_mfma_f32_16x16x32_bf16 v[6:9], v[156:159], v[198:201], v[6:9]
	v_mfma_f32_16x16x32_bf16 v[2:5], v[164:167], v[198:201], v[2:5]
	s_setprio 0
	s_barrier
	s_add_i32 s84, s84, 2
	s_add_u32 s50, s50, 0x100
	s_addc_u32 s51, s51, 0
	s_cmp_gt_u32 s84, 41
	s_cbranch_scc0 .LBB0_821

.LBB0_869:
	s_add_u32 s4, s10, s2
	s_addc_u32 s5, s11, s3
	s_add_u32 s22, s4, 0x100
	s_addc_u32 s23, s5, 0
	s_add_u32 s46, s58, s2
	s_addc_u32 s47, s59, s3
	s_add_i32 s69, 0, 0x10000
	s_cmp_eq_u32 s68, 40
	s_cselect_b32 s23, s11, s23
	s_cselect_b32 s22, s10, s22
	v_add_u32_e32 v0, s69, v126
	s_cselect_b32 s47, s17, s47
	s_cselect_b32 s46, s16, s46
	s_add_i32 s70, 0, 0x14000
	ds_read_b128 v[128:131], v0
	ds_read_b128 v[142:145], v0 offset:1024
	ds_read_b128 v[146:149], v0 offset:2048
	ds_read_b128 v[150:153], v0 offset:3072
	ds_read_b128 v[154:157], v0 offset:16384
	ds_read_b128 v[160:163], v0 offset:17408
	ds_read_b128 v[164:167], v0 offset:18432
	ds_read_b128 v[168:171], v0 offset:19456
	ds_read_b128 v[172:175], v127
	ds_read_b128 v[176:179], v127 offset:1024
	ds_read_b128 v[180:183], v127 offset:2048
	ds_read_b128 v[184:187], v127 offset:3072
	ds_read_b128 v[188:191], v127 offset:4096
	ds_read_b128 v[192:195], v127 offset:5120
	ds_read_b128 v[196:199], v127 offset:6144
	ds_read_b128 v[200:203], v127 offset:7168
	s_add_i32 m0, s41, 0xc000
	s_add_u32 s100, s4, s62
	s_addc_u32 s101, s5, s63
	global_load_lds_dwordx4 v122, s[100:101]
	s_add_i32 m0, s41, 0xe000
	s_nop 0
	global_load_lds_dwordx4 v123, s[100:101]
	s_waitcnt vmcnt(8) lgkmcnt(0)
	s_setprio 1
	s_barrier
	v_mfma_f32_16x16x32_bf16 v[138:141], v[128:131], v[172:175], v[138:141]
	v_mfma_f32_16x16x32_bf16 v[132:135], v[146:149], v[172:175], v[134:137]
	v_mfma_f32_16x16x32_bf16 v[110:113], v[128:131], v[180:183], v[110:113]
	v_mfma_f32_16x16x32_bf16 v[106:109], v[146:149], v[180:183], v[106:109]
	v_mfma_f32_16x16x32_bf16 v[94:97], v[128:131], v[188:191], v[94:97]
	v_mfma_f32_16x16x32_bf16 v[90:93], v[146:149], v[188:191], v[90:93]
	v_mfma_f32_16x16x32_bf16 v[78:81], v[128:131], v[196:199], v[78:81]
	v_mfma_f32_16x16x32_bf16 v[74:77], v[146:149], v[196:199], v[74:77]
	v_mfma_f32_16x16x32_bf16 v[138:141], v[142:145], v[176:179], v[138:141]
	v_mfma_f32_16x16x32_bf16 v[132:135], v[150:153], v[176:179], v[132:135]
	v_mfma_f32_16x16x32_bf16 v[110:113], v[142:145], v[184:187], v[110:113]
	v_mfma_f32_16x16x32_bf16 v[106:109], v[150:153], v[184:187], v[106:109]
	v_mfma_f32_16x16x32_bf16 v[94:97], v[142:145], v[192:195], v[94:97]
	v_mfma_f32_16x16x32_bf16 v[90:93], v[150:153], v[192:195], v[90:93]
	v_mfma_f32_16x16x32_bf16 v[78:81], v[142:145], v[200:203], v[78:81]
	v_mfma_f32_16x16x32_bf16 v[74:77], v[150:153], v[200:203], v[74:77]
	s_setprio 0
	s_setprio 1
	v_mfma_f32_16x16x32_bf16 v[118:121], v[154:157], v[172:175], v[118:121]
	v_mfma_f32_16x16x32_bf16 v[114:117], v[164:167], v[172:175], v[114:117]
	v_mfma_f32_16x16x32_bf16 v[102:105], v[154:157], v[180:183], v[102:105]
	v_mfma_f32_16x16x32_bf16 v[98:101], v[164:167], v[180:183], v[98:101]
	v_mfma_f32_16x16x32_bf16 v[86:89], v[154:157], v[188:191], v[86:89]
	v_mfma_f32_16x16x32_bf16 v[82:85], v[164:167], v[188:191], v[82:85]
	v_mfma_f32_16x16x32_bf16 v[70:73], v[154:157], v[196:199], v[70:73]
	v_mfma_f32_16x16x32_bf16 v[66:69], v[164:167], v[196:199], v[66:69]
	v_mfma_f32_16x16x32_bf16 v[118:121], v[160:163], v[176:179], v[118:121]
	v_mfma_f32_16x16x32_bf16 v[114:117], v[168:171], v[176:179], v[114:117]
	v_mfma_f32_16x16x32_bf16 v[102:105], v[160:163], v[184:187], v[102:105]
	v_mfma_f32_16x16x32_bf16 v[98:101], v[168:171], v[184:187], v[98:101]
	v_mfma_f32_16x16x32_bf16 v[86:89], v[160:163], v[192:195], v[86:89]
	v_mfma_f32_16x16x32_bf16 v[82:85], v[168:171], v[192:195], v[82:85]
	v_mfma_f32_16x16x32_bf16 v[70:73], v[160:163], v[200:203], v[70:73]
	v_mfma_f32_16x16x32_bf16 v[66:69], v[168:171], v[200:203], v[66:69]
	s_setprio 0
	s_barrier
	s_add_i32 s4, s69, s26
	ds_read_b128 v[172:175], v127 offset:16384
	ds_read_b128 v[176:179], v127 offset:17408
	ds_read_b128 v[180:183], v127 offset:18432
	ds_read_b128 v[184:187], v127 offset:19456
	ds_read_b128 v[188:191], v127 offset:20480
	ds_read_b128 v[192:195], v127 offset:21504
	ds_read_b128 v[196:199], v127 offset:22528
	ds_read_b128 v[200:203], v127 offset:23552
	s_mov_b32 m0, s4
	s_nop 0
	global_load_lds_dwordx4 v124, s[46:47]
	s_add_i32 m0, s4, 0x2000
	s_add_u32 s4, s46, 0xb0000
	global_load_lds_dwordx4 v125, s[46:47]
	s_addc_u32 s5, s47, 0
	s_add_i32 s69, s70, s26
	s_mov_b32 m0, s69
	s_nop 0
	global_load_lds_dwordx4 v124, s[4:5]
	s_add_i32 m0, s69, 0x2000
	s_nop 0
	global_load_lds_dwordx4 v125, s[4:5]
	s_mov_b32 m0, s41
	s_nop 0
	global_load_lds_dwordx4 v122, s[22:23]
	s_mov_b32 m0, s48
	s_nop 0
	global_load_lds_dwordx4 v123, s[22:23]
	s_waitcnt vmcnt(8) lgkmcnt(0)
	s_setprio 1
	s_barrier
	v_mfma_f32_16x16x32_bf16 v[62:65], v[128:131], v[172:175], v[62:65]
	v_mfma_f32_16x16x32_bf16 v[58:61], v[146:149], v[172:175], v[58:61]
	v_mfma_f32_16x16x32_bf16 v[46:49], v[128:131], v[180:183], v[46:49]
	v_mfma_f32_16x16x32_bf16 v[42:45], v[146:149], v[180:183], v[42:45]
	v_mfma_f32_16x16x32_bf16 v[30:33], v[128:131], v[188:191], v[30:33]
	v_mfma_f32_16x16x32_bf16 v[26:29], v[146:149], v[188:191], v[26:29]
	v_mfma_f32_16x16x32_bf16 v[14:17], v[128:131], v[196:199], v[14:17]
	v_mfma_f32_16x16x32_bf16 v[10:13], v[146:149], v[196:199], v[10:13]
	v_mfma_f32_16x16x32_bf16 v[62:65], v[142:145], v[176:179], v[62:65]
	v_mfma_f32_16x16x32_bf16 v[58:61], v[150:153], v[176:179], v[58:61]
	v_mfma_f32_16x16x32_bf16 v[46:49], v[142:145], v[184:187], v[46:49]
	v_mfma_f32_16x16x32_bf16 v[42:45], v[150:153], v[184:187], v[42:45]
	v_mfma_f32_16x16x32_bf16 v[30:33], v[142:145], v[192:195], v[30:33]
	v_mfma_f32_16x16x32_bf16 v[26:29], v[150:153], v[192:195], v[26:29]
	v_mfma_f32_16x16x32_bf16 v[14:17], v[142:145], v[200:203], v[14:17]
	v_mfma_f32_16x16x32_bf16 v[10:13], v[150:153], v[200:203], v[10:13]
	s_setprio 0
	s_setprio 1
	v_mfma_f32_16x16x32_bf16 v[54:57], v[154:157], v[172:175], v[54:57]
	v_mfma_f32_16x16x32_bf16 v[50:53], v[164:167], v[172:175], v[50:53]
	v_mfma_f32_16x16x32_bf16 v[38:41], v[154:157], v[180:183], v[38:41]
	v_mfma_f32_16x16x32_bf16 v[34:37], v[164:167], v[180:183], v[34:37]
	v_mfma_f32_16x16x32_bf16 v[22:25], v[154:157], v[188:191], v[22:25]
	v_mfma_f32_16x16x32_bf16 v[18:21], v[164:167], v[188:191], v[18:21]
	v_mfma_f32_16x16x32_bf16 v[6:9], v[154:157], v[196:199], v[6:9]
	v_mfma_f32_16x16x32_bf16 v[2:5], v[164:167], v[196:199], v[2:5]
	v_mfma_f32_16x16x32_bf16 v[54:57], v[160:163], v[176:179], v[54:57]
	v_mfma_f32_16x16x32_bf16 v[50:53], v[168:171], v[176:179], v[50:53]
	v_mfma_f32_16x16x32_bf16 v[38:41], v[160:163], v[184:187], v[38:41]
	v_mfma_f32_16x16x32_bf16 v[34:37], v[168:171], v[184:187], v[34:37]
	v_mfma_f32_16x16x32_bf16 v[22:25], v[160:163], v[192:195], v[22:25]
	v_mfma_f32_16x16x32_bf16 v[18:21], v[168:171], v[192:195], v[18:21]
	v_mfma_f32_16x16x32_bf16 v[6:9], v[160:163], v[200:203], v[6:9]
	v_mfma_f32_16x16x32_bf16 v[2:5], v[168:171], v[200:203], v[2:5]
	s_setprio 0
	s_barrier
	s_add_i32 s69, 0, 0x18000
	s_add_i32 s70, 0, 0x1c000
	ds_read_b128 v[128:131], v0 offset:32768
	ds_read_b128 v[142:145], v0 offset:33792
	ds_read_b128 v[146:149], v0 offset:34816
	ds_read_b128 v[150:153], v0 offset:35840
	ds_read_b128 v[154:157], v0 offset:49152
	ds_read_b128 v[160:163], v0 offset:50176
	ds_read_b128 v[164:167], v0 offset:51200
	ds_read_b128 v[168:171], v0 offset:52224
	s_add_u32 s4, s22, 0xb0000
	s_mov_b32 m0, s49
	ds_read_b128 v[172:175], v127 offset:32768
	ds_read_b128 v[176:179], v127 offset:33792
	ds_read_b128 v[180:183], v127 offset:34816
	ds_read_b128 v[184:187], v127 offset:35840
	ds_read_b128 v[188:191], v127 offset:36864
	ds_read_b128 v[192:195], v127 offset:37888
	ds_read_b128 v[196:199], v127 offset:38912
	ds_read_b128 v[200:203], v127 offset:39936
	s_addc_u32 s5, s23, 0
	s_nop 0
	global_load_lds_dwordx4 v122, s[4:5]
	s_mov_b32 m0, s50
	s_nop 0
	global_load_lds_dwordx4 v123, s[4:5]
	s_waitcnt vmcnt(8) lgkmcnt(0)
	s_setprio 1
	s_barrier
	v_mfma_f32_16x16x32_bf16 v[136:139], v[128:131], v[172:175], v[138:141]
	v_mfma_f32_16x16x32_bf16 v[132:135], v[146:149], v[172:175], v[132:135]
	v_mfma_f32_16x16x32_bf16 v[110:113], v[128:131], v[180:183], v[110:113]
	v_mfma_f32_16x16x32_bf16 v[106:109], v[146:149], v[180:183], v[106:109]
	v_mfma_f32_16x16x32_bf16 v[94:97], v[128:131], v[188:191], v[94:97]
	v_mfma_f32_16x16x32_bf16 v[90:93], v[146:149], v[188:191], v[90:93]
	v_mfma_f32_16x16x32_bf16 v[78:81], v[128:131], v[196:199], v[78:81]
	v_mfma_f32_16x16x32_bf16 v[74:77], v[146:149], v[196:199], v[74:77]
	v_mfma_f32_16x16x32_bf16 v[138:141], v[142:145], v[176:179], v[136:139]
	v_mfma_f32_16x16x32_bf16 v[134:137], v[150:153], v[176:179], v[132:135]
	v_mfma_f32_16x16x32_bf16 v[110:113], v[142:145], v[184:187], v[110:113]
	v_mfma_f32_16x16x32_bf16 v[106:109], v[150:153], v[184:187], v[106:109]
	v_mfma_f32_16x16x32_bf16 v[94:97], v[142:145], v[192:195], v[94:97]
	v_mfma_f32_16x16x32_bf16 v[90:93], v[150:153], v[192:195], v[90:93]
	v_mfma_f32_16x16x32_bf16 v[78:81], v[142:145], v[200:203], v[78:81]
	v_mfma_f32_16x16x32_bf16 v[74:77], v[150:153], v[200:203], v[74:77]
	s_setprio 0
	s_setprio 1
	v_mfma_f32_16x16x32_bf16 v[118:121], v[154:157], v[172:175], v[118:121]
	v_mfma_f32_16x16x32_bf16 v[114:117], v[164:167], v[172:175], v[114:117]
	v_mfma_f32_16x16x32_bf16 v[102:105], v[154:157], v[180:183], v[102:105]
	v_mfma_f32_16x16x32_bf16 v[98:101], v[164:167], v[180:183], v[98:101]
	v_mfma_f32_16x16x32_bf16 v[86:89], v[154:157], v[188:191], v[86:89]
	v_mfma_f32_16x16x32_bf16 v[82:85], v[164:167], v[188:191], v[82:85]
	v_mfma_f32_16x16x32_bf16 v[70:73], v[154:157], v[196:199], v[70:73]
	v_mfma_f32_16x16x32_bf16 v[66:69], v[164:167], v[196:199], v[66:69]
	v_mfma_f32_16x16x32_bf16 v[118:121], v[160:163], v[176:179], v[118:121]
	v_mfma_f32_16x16x32_bf16 v[114:117], v[168:171], v[176:179], v[114:117]
	v_mfma_f32_16x16x32_bf16 v[102:105], v[160:163], v[184:187], v[102:105]
	v_mfma_f32_16x16x32_bf16 v[98:101], v[168:171], v[184:187], v[98:101]
	v_mfma_f32_16x16x32_bf16 v[86:89], v[160:163], v[192:195], v[86:89]
	v_mfma_f32_16x16x32_bf16 v[82:85], v[168:171], v[192:195], v[82:85]
	v_mfma_f32_16x16x32_bf16 v[70:73], v[160:163], v[200:203], v[70:73]
	v_mfma_f32_16x16x32_bf16 v[66:69], v[168:171], v[200:203], v[66:69]
	s_setprio 0
	s_barrier
	ds_read_b128 v[172:175], v127 offset:49152
	ds_read_b128 v[176:179], v127 offset:50176
	ds_read_b128 v[180:183], v127 offset:51200
	ds_read_b128 v[184:187], v127 offset:52224
	ds_read_b128 v[188:191], v127 offset:53248
	ds_read_b128 v[192:195], v127 offset:54272
	ds_read_b128 v[196:199], v127 offset:55296
	ds_read_b128 v[200:203], v127 offset:56320
	s_add_i32 s4, s69, s26
	s_add_u32 s100, s46, s38
	s_addc_u32 s101, s47, s39
	s_mov_b32 m0, s4
	s_nop 0
	global_load_lds_dwordx4 v124, s[100:101]
	s_add_i32 m0, s4, 0x2000
	s_add_u32 s4, s46, 0xb0080
	s_addc_u32 s5, s47, 0
	s_add_i32 s46, s70, s26
	global_load_lds_dwordx4 v125, s[100:101]
	s_mov_b32 m0, s46
	s_nop 0
	global_load_lds_dwordx4 v124, s[4:5]
	s_add_i32 m0, s46, 0x2000
	s_nop 0
	global_load_lds_dwordx4 v125, s[4:5]
	s_mov_b32 m0, s64
	s_add_u32 s100, s22, s38
	s_addc_u32 s101, s23, s39
	v_mov_b32_e32 v0, v123
	global_load_lds_dwordx4 v122, s[100:101]
	s_mov_b32 m0, s65
	s_nop 0
	global_load_lds_dwordx4 v123, s[100:101]
	s_waitcnt vmcnt(8) lgkmcnt(0)
	s_setprio 1
	s_barrier
	v_mfma_f32_16x16x32_bf16 v[62:65], v[128:131], v[172:175], v[62:65]
	v_mfma_f32_16x16x32_bf16 v[58:61], v[146:149], v[172:175], v[58:61]
	v_mfma_f32_16x16x32_bf16 v[46:49], v[128:131], v[180:183], v[46:49]
	v_mfma_f32_16x16x32_bf16 v[42:45], v[146:149], v[180:183], v[42:45]
	v_mfma_f32_16x16x32_bf16 v[30:33], v[128:131], v[188:191], v[30:33]
	v_mfma_f32_16x16x32_bf16 v[26:29], v[146:149], v[188:191], v[26:29]
	v_mfma_f32_16x16x32_bf16 v[14:17], v[128:131], v[196:199], v[14:17]
	v_mfma_f32_16x16x32_bf16 v[10:13], v[146:149], v[196:199], v[10:13]
	v_mfma_f32_16x16x32_bf16 v[62:65], v[142:145], v[176:179], v[62:65]
	v_mfma_f32_16x16x32_bf16 v[58:61], v[150:153], v[176:179], v[58:61]
	v_mfma_f32_16x16x32_bf16 v[46:49], v[142:145], v[184:187], v[46:49]
	v_mfma_f32_16x16x32_bf16 v[42:45], v[150:153], v[184:187], v[42:45]
	v_mfma_f32_16x16x32_bf16 v[30:33], v[142:145], v[192:195], v[30:33]
	v_mfma_f32_16x16x32_bf16 v[26:29], v[150:153], v[192:195], v[26:29]
	v_mfma_f32_16x16x32_bf16 v[14:17], v[142:145], v[200:203], v[14:17]
	v_mfma_f32_16x16x32_bf16 v[10:13], v[150:153], v[200:203], v[10:13]
	s_setprio 0
	s_setprio 1
	v_mfma_f32_16x16x32_bf16 v[54:57], v[154:157], v[172:175], v[54:57]
	v_mfma_f32_16x16x32_bf16 v[50:53], v[164:167], v[172:175], v[50:53]
	v_mfma_f32_16x16x32_bf16 v[38:41], v[154:157], v[180:183], v[38:41]
	v_mfma_f32_16x16x32_bf16 v[34:37], v[164:167], v[180:183], v[34:37]
	v_mfma_f32_16x16x32_bf16 v[22:25], v[154:157], v[188:191], v[22:25]
	v_mfma_f32_16x16x32_bf16 v[18:21], v[164:167], v[188:191], v[18:21]
	v_mfma_f32_16x16x32_bf16 v[6:9], v[154:157], v[196:199], v[6:9]
	v_mfma_f32_16x16x32_bf16 v[2:5], v[164:167], v[196:199], v[2:5]
	v_mfma_f32_16x16x32_bf16 v[54:57], v[160:163], v[176:179], v[54:57]
	v_mfma_f32_16x16x32_bf16 v[50:53], v[168:171], v[176:179], v[50:53]
	v_mfma_f32_16x16x32_bf16 v[38:41], v[160:163], v[184:187], v[38:41]
	v_mfma_f32_16x16x32_bf16 v[34:37], v[168:171], v[184:187], v[34:37]
	v_mfma_f32_16x16x32_bf16 v[22:25], v[160:163], v[192:195], v[22:25]
	v_mfma_f32_16x16x32_bf16 v[18:21], v[168:171], v[192:195], v[18:21]
	v_mfma_f32_16x16x32_bf16 v[6:9], v[160:163], v[200:203], v[6:9]
	v_mfma_f32_16x16x32_bf16 v[2:5], v[168:171], v[200:203], v[2:5]
	s_setprio 0
	s_barrier
	s_add_i32 s68, s68, 2
	s_add_u32 s2, s2, 0x100
	s_addc_u32 s3, s3, 0
	s_cmp_gt_u32 s68, 41
	s_cbranch_scc0 .LBB0_869

.LBB0_953:
	s_add_u32 s58, s4, s2
	s_addc_u32 s59, s5, s3
	s_add_u32 s14, s58, 0x100
	s_addc_u32 s15, s59, 0
	s_add_u32 s16, s43, s2
	s_addc_u32 s17, s46, s3
	s_add_i32 s51, 0, 0x10000
	s_cmp_eq_u32 s50, 40
	s_cselect_b32 s15, s5, s15
	s_cselect_b32 s14, s4, s14
	v_add_u32_e32 v0, s51, v135
	s_cselect_b32 s17, s7, s17
	s_cselect_b32 s16, s6, s16
	s_add_i32 s60, 0, 0x14000
	ds_read_b128 v[138:141], v0
	ds_read_b128 v[142:145], v0 offset:1024
	ds_read_b128 v[146:149], v0 offset:2048
	ds_read_b128 v[150:153], v0 offset:3072
	ds_read_b128 v[154:157], v0 offset:16384
	ds_read_b128 v[158:161], v0 offset:17408
	ds_read_b128 v[162:165], v0 offset:18432
	ds_read_b128 v[166:169], v0 offset:19456
	ds_read_b128 v[170:173], v136
	ds_read_b128 v[174:177], v136 offset:1024
	ds_read_b128 v[178:181], v136 offset:2048
	ds_read_b128 v[182:185], v136 offset:3072
	ds_read_b128 v[186:189], v136 offset:4096
	ds_read_b128 v[190:193], v136 offset:5120
	ds_read_b128 v[194:197], v136 offset:6144
	ds_read_b128 v[198:201], v136 offset:7168
	s_add_i32 m0, s37, 0xc000
	s_add_u32 s100, s58, s62
	s_addc_u32 s101, s59, s63
	global_load_lds_dwordx4 v130, s[100:101]
	s_add_i32 m0, s37, 0xe000
	s_nop 0
	global_load_lds_dwordx4 v131, s[100:101]
	s_waitcnt vmcnt(8) lgkmcnt(0)
	s_setprio 1
	s_barrier
	v_mfma_f32_16x16x32_bf16 v[126:129], v[138:141], v[170:173], v[126:129]
	v_mfma_f32_16x16x32_bf16 v[122:125], v[146:149], v[170:173], v[122:125]
	v_mfma_f32_16x16x32_bf16 v[110:113], v[138:141], v[178:181], v[110:113]
	v_mfma_f32_16x16x32_bf16 v[106:109], v[146:149], v[178:181], v[106:109]
	v_mfma_f32_16x16x32_bf16 v[94:97], v[138:141], v[186:189], v[94:97]
	v_mfma_f32_16x16x32_bf16 v[90:93], v[146:149], v[186:189], v[90:93]
	v_mfma_f32_16x16x32_bf16 v[78:81], v[138:141], v[194:197], v[78:81]
	v_mfma_f32_16x16x32_bf16 v[74:77], v[146:149], v[194:197], v[74:77]
	v_mfma_f32_16x16x32_bf16 v[126:129], v[142:145], v[174:177], v[126:129]
	v_mfma_f32_16x16x32_bf16 v[122:125], v[150:153], v[174:177], v[122:125]
	v_mfma_f32_16x16x32_bf16 v[110:113], v[142:145], v[182:185], v[110:113]
	v_mfma_f32_16x16x32_bf16 v[106:109], v[150:153], v[182:185], v[106:109]
	v_mfma_f32_16x16x32_bf16 v[94:97], v[142:145], v[190:193], v[94:97]
	v_mfma_f32_16x16x32_bf16 v[90:93], v[150:153], v[190:193], v[90:93]
	v_mfma_f32_16x16x32_bf16 v[78:81], v[142:145], v[198:201], v[78:81]
	v_mfma_f32_16x16x32_bf16 v[74:77], v[150:153], v[198:201], v[74:77]
	s_setprio 0
	s_setprio 1
	v_mfma_f32_16x16x32_bf16 v[118:121], v[154:157], v[170:173], v[118:121]
	v_mfma_f32_16x16x32_bf16 v[114:117], v[162:165], v[170:173], v[114:117]
	v_mfma_f32_16x16x32_bf16 v[102:105], v[154:157], v[178:181], v[102:105]
	v_mfma_f32_16x16x32_bf16 v[98:101], v[162:165], v[178:181], v[98:101]
	v_mfma_f32_16x16x32_bf16 v[86:89], v[154:157], v[186:189], v[86:89]
	v_mfma_f32_16x16x32_bf16 v[82:85], v[162:165], v[186:189], v[82:85]
	v_mfma_f32_16x16x32_bf16 v[70:73], v[154:157], v[194:197], v[70:73]
	v_mfma_f32_16x16x32_bf16 v[66:69], v[162:165], v[194:197], v[66:69]
	v_mfma_f32_16x16x32_bf16 v[118:121], v[158:161], v[174:177], v[118:121]
	v_mfma_f32_16x16x32_bf16 v[114:117], v[166:169], v[174:177], v[114:117]
	v_mfma_f32_16x16x32_bf16 v[102:105], v[158:161], v[182:185], v[102:105]
	v_mfma_f32_16x16x32_bf16 v[98:101], v[166:169], v[182:185], v[98:101]
	v_mfma_f32_16x16x32_bf16 v[86:89], v[158:161], v[190:193], v[86:89]
	v_mfma_f32_16x16x32_bf16 v[82:85], v[166:169], v[190:193], v[82:85]
	v_mfma_f32_16x16x32_bf16 v[70:73], v[158:161], v[198:201], v[70:73]
	v_mfma_f32_16x16x32_bf16 v[66:69], v[166:169], v[198:201], v[66:69]
	s_setprio 0
	s_barrier
	s_add_i32 s51, s51, s26
	ds_read_b128 v[170:173], v136 offset:16384
	ds_read_b128 v[174:177], v136 offset:17408
	ds_read_b128 v[178:181], v136 offset:18432
	ds_read_b128 v[182:185], v136 offset:19456
	ds_read_b128 v[186:189], v136 offset:20480
	ds_read_b128 v[190:193], v136 offset:21504
	ds_read_b128 v[194:197], v136 offset:22528
	ds_read_b128 v[198:201], v136 offset:23552
	s_mov_b32 m0, s51
	s_nop 0
	global_load_lds_dwordx4 v133, s[16:17]
	s_add_i32 m0, s51, 0x2000
	s_add_u32 s58, s16, 0xb0000
	global_load_lds_dwordx4 v134, s[16:17]
	s_addc_u32 s59, s17, 0
	s_add_i32 s51, s60, s26
	s_mov_b32 m0, s51
	s_nop 0
	global_load_lds_dwordx4 v133, s[58:59]
	s_add_i32 m0, s51, 0x2000
	s_nop 0
	global_load_lds_dwordx4 v134, s[58:59]
	s_mov_b32 m0, s37
	s_nop 0
	global_load_lds_dwordx4 v130, s[14:15]
	s_mov_b32 m0, s40
	s_nop 0
	global_load_lds_dwordx4 v131, s[14:15]
	s_waitcnt vmcnt(8) lgkmcnt(0)
	s_setprio 1
	s_barrier
	v_mfma_f32_16x16x32_bf16 v[62:65], v[138:141], v[170:173], v[62:65]
	v_mfma_f32_16x16x32_bf16 v[58:61], v[146:149], v[170:173], v[58:61]
	v_mfma_f32_16x16x32_bf16 v[46:49], v[138:141], v[178:181], v[46:49]
	v_mfma_f32_16x16x32_bf16 v[42:45], v[146:149], v[178:181], v[42:45]
	v_mfma_f32_16x16x32_bf16 v[30:33], v[138:141], v[186:189], v[30:33]
	v_mfma_f32_16x16x32_bf16 v[26:29], v[146:149], v[186:189], v[26:29]
	v_mfma_f32_16x16x32_bf16 v[14:17], v[138:141], v[194:197], v[14:17]
	v_mfma_f32_16x16x32_bf16 v[10:13], v[146:149], v[194:197], v[10:13]
	v_mfma_f32_16x16x32_bf16 v[62:65], v[142:145], v[174:177], v[62:65]
	v_mfma_f32_16x16x32_bf16 v[58:61], v[150:153], v[174:177], v[58:61]
	v_mfma_f32_16x16x32_bf16 v[46:49], v[142:145], v[182:185], v[46:49]
	v_mfma_f32_16x16x32_bf16 v[42:45], v[150:153], v[182:185], v[42:45]
	v_mfma_f32_16x16x32_bf16 v[30:33], v[142:145], v[190:193], v[30:33]
	v_mfma_f32_16x16x32_bf16 v[26:29], v[150:153], v[190:193], v[26:29]
	v_mfma_f32_16x16x32_bf16 v[14:17], v[142:145], v[198:201], v[14:17]
	v_mfma_f32_16x16x32_bf16 v[10:13], v[150:153], v[198:201], v[10:13]
	s_setprio 0
	s_setprio 1
	v_mfma_f32_16x16x32_bf16 v[54:57], v[154:157], v[170:173], v[54:57]
	v_mfma_f32_16x16x32_bf16 v[50:53], v[162:165], v[170:173], v[50:53]
	v_mfma_f32_16x16x32_bf16 v[38:41], v[154:157], v[178:181], v[38:41]
	v_mfma_f32_16x16x32_bf16 v[34:37], v[162:165], v[178:181], v[34:37]
	v_mfma_f32_16x16x32_bf16 v[22:25], v[154:157], v[186:189], v[22:25]
	v_mfma_f32_16x16x32_bf16 v[18:21], v[162:165], v[186:189], v[18:21]
	v_mfma_f32_16x16x32_bf16 v[6:9], v[154:157], v[194:197], v[6:9]
	v_mfma_f32_16x16x32_bf16 v[2:5], v[162:165], v[194:197], v[2:5]
	v_mfma_f32_16x16x32_bf16 v[54:57], v[158:161], v[174:177], v[54:57]
	v_mfma_f32_16x16x32_bf16 v[50:53], v[166:169], v[174:177], v[50:53]
	v_mfma_f32_16x16x32_bf16 v[38:41], v[158:161], v[182:185], v[38:41]
	v_mfma_f32_16x16x32_bf16 v[34:37], v[166:169], v[182:185], v[34:37]
	v_mfma_f32_16x16x32_bf16 v[22:25], v[158:161], v[190:193], v[22:25]
	v_mfma_f32_16x16x32_bf16 v[18:21], v[166:169], v[190:193], v[18:21]
	v_mfma_f32_16x16x32_bf16 v[6:9], v[158:161], v[198:201], v[6:9]
	v_mfma_f32_16x16x32_bf16 v[2:5], v[166:169], v[198:201], v[2:5]
	s_setprio 0
	s_barrier
	s_add_i32 s51, 0, 0x18000
	s_add_i32 s60, 0, 0x1c000
	ds_read_b128 v[138:141], v0 offset:32768
	ds_read_b128 v[142:145], v0 offset:33792
	ds_read_b128 v[146:149], v0 offset:34816
	ds_read_b128 v[150:153], v0 offset:35840
	ds_read_b128 v[154:157], v0 offset:49152
	ds_read_b128 v[158:161], v0 offset:50176
	ds_read_b128 v[162:165], v0 offset:51200
	ds_read_b128 v[166:169], v0 offset:52224
	s_add_u32 s58, s14, 0xb0000
	s_mov_b32 m0, s41
	ds_read_b128 v[170:173], v136 offset:32768
	ds_read_b128 v[174:177], v136 offset:33792
	ds_read_b128 v[178:181], v136 offset:34816
	ds_read_b128 v[182:185], v136 offset:35840
	ds_read_b128 v[186:189], v136 offset:36864
	ds_read_b128 v[190:193], v136 offset:37888
	ds_read_b128 v[194:197], v136 offset:38912
	ds_read_b128 v[198:201], v136 offset:39936
	s_addc_u32 s59, s15, 0
	s_nop 0
	global_load_lds_dwordx4 v130, s[58:59]
	s_mov_b32 m0, s42
	s_nop 0
	global_load_lds_dwordx4 v131, s[58:59]
	s_waitcnt vmcnt(8) lgkmcnt(0)
	s_setprio 1
	s_barrier
	v_mfma_f32_16x16x32_bf16 v[126:129], v[138:141], v[170:173], v[126:129]
	v_mfma_f32_16x16x32_bf16 v[122:125], v[146:149], v[170:173], v[122:125]
	v_mfma_f32_16x16x32_bf16 v[110:113], v[138:141], v[178:181], v[110:113]
	v_mfma_f32_16x16x32_bf16 v[106:109], v[146:149], v[178:181], v[106:109]
	v_mfma_f32_16x16x32_bf16 v[94:97], v[138:141], v[186:189], v[94:97]
	v_mfma_f32_16x16x32_bf16 v[90:93], v[146:149], v[186:189], v[90:93]
	v_mfma_f32_16x16x32_bf16 v[78:81], v[138:141], v[194:197], v[78:81]
	v_mfma_f32_16x16x32_bf16 v[74:77], v[146:149], v[194:197], v[74:77]
	v_mfma_f32_16x16x32_bf16 v[126:129], v[142:145], v[174:177], v[126:129]
	v_mfma_f32_16x16x32_bf16 v[122:125], v[150:153], v[174:177], v[122:125]
	v_mfma_f32_16x16x32_bf16 v[110:113], v[142:145], v[182:185], v[110:113]
	v_mfma_f32_16x16x32_bf16 v[106:109], v[150:153], v[182:185], v[106:109]
	v_mfma_f32_16x16x32_bf16 v[94:97], v[142:145], v[190:193], v[94:97]
	v_mfma_f32_16x16x32_bf16 v[90:93], v[150:153], v[190:193], v[90:93]
	v_mfma_f32_16x16x32_bf16 v[78:81], v[142:145], v[198:201], v[78:81]
	v_mfma_f32_16x16x32_bf16 v[74:77], v[150:153], v[198:201], v[74:77]
	s_setprio 0
	s_setprio 1
	v_mfma_f32_16x16x32_bf16 v[118:121], v[154:157], v[170:173], v[118:121]
	v_mfma_f32_16x16x32_bf16 v[114:117], v[162:165], v[170:173], v[114:117]
	v_mfma_f32_16x16x32_bf16 v[102:105], v[154:157], v[178:181], v[102:105]
	v_mfma_f32_16x16x32_bf16 v[98:101], v[162:165], v[178:181], v[98:101]
	v_mfma_f32_16x16x32_bf16 v[86:89], v[154:157], v[186:189], v[86:89]
	v_mfma_f32_16x16x32_bf16 v[82:85], v[162:165], v[186:189], v[82:85]
	v_mfma_f32_16x16x32_bf16 v[70:73], v[154:157], v[194:197], v[70:73]
	v_mfma_f32_16x16x32_bf16 v[66:69], v[162:165], v[194:197], v[66:69]
	v_mfma_f32_16x16x32_bf16 v[118:121], v[158:161], v[174:177], v[118:121]
	v_mfma_f32_16x16x32_bf16 v[114:117], v[166:169], v[174:177], v[114:117]
	v_mfma_f32_16x16x32_bf16 v[102:105], v[158:161], v[182:185], v[102:105]
	v_mfma_f32_16x16x32_bf16 v[98:101], v[166:169], v[182:185], v[98:101]
	v_mfma_f32_16x16x32_bf16 v[86:89], v[158:161], v[190:193], v[86:89]
	v_mfma_f32_16x16x32_bf16 v[82:85], v[166:169], v[190:193], v[82:85]
	v_mfma_f32_16x16x32_bf16 v[70:73], v[158:161], v[198:201], v[70:73]
	v_mfma_f32_16x16x32_bf16 v[66:69], v[166:169], v[198:201], v[66:69]
	s_setprio 0
	s_barrier
	ds_read_b128 v[170:173], v136 offset:49152
	ds_read_b128 v[174:177], v136 offset:50176
	ds_read_b128 v[178:181], v136 offset:51200
	ds_read_b128 v[182:185], v136 offset:52224
	ds_read_b128 v[186:189], v136 offset:53248
	ds_read_b128 v[190:193], v136 offset:54272
	ds_read_b128 v[194:197], v136 offset:55296
	ds_read_b128 v[198:201], v136 offset:56320
	s_add_i32 s51, s51, s26
	s_add_u32 s100, s16, s38
	s_addc_u32 s101, s17, s39
	s_mov_b32 m0, s51
	s_nop 0
	global_load_lds_dwordx4 v133, s[100:101]
	s_add_i32 m0, s51, 0x2000
	s_nop 0
	s_add_u32 s16, s16, 0xb0080
	s_addc_u32 s17, s17, 0
	s_add_i32 s51, s60, s26
	global_load_lds_dwordx4 v134, s[100:101]
	s_mov_b32 m0, s51
	s_nop 0
	global_load_lds_dwordx4 v133, s[16:17]
	s_add_i32 m0, s51, 0x2000
	s_nop 0
	global_load_lds_dwordx4 v134, s[16:17]
	s_mov_b32 m0, s48
	s_add_u32 s100, s14, s38
	s_addc_u32 s101, s15, s39
	v_mov_b32_e32 v0, v131
	global_load_lds_dwordx4 v130, s[100:101]
	s_mov_b32 m0, s49
	s_nop 0
	global_load_lds_dwordx4 v131, s[100:101]
	s_waitcnt vmcnt(8) lgkmcnt(0)
	s_setprio 1
	s_barrier
	v_mfma_f32_16x16x32_bf16 v[62:65], v[138:141], v[170:173], v[62:65]
	v_mfma_f32_16x16x32_bf16 v[58:61], v[146:149], v[170:173], v[58:61]
	v_mfma_f32_16x16x32_bf16 v[46:49], v[138:141], v[178:181], v[46:49]
	v_mfma_f32_16x16x32_bf16 v[42:45], v[146:149], v[178:181], v[42:45]
	v_mfma_f32_16x16x32_bf16 v[30:33], v[138:141], v[186:189], v[30:33]
	v_mfma_f32_16x16x32_bf16 v[26:29], v[146:149], v[186:189], v[26:29]
	v_mfma_f32_16x16x32_bf16 v[14:17], v[138:141], v[194:197], v[14:17]
	v_mfma_f32_16x16x32_bf16 v[10:13], v[146:149], v[194:197], v[10:13]
	v_mfma_f32_16x16x32_bf16 v[62:65], v[142:145], v[174:177], v[62:65]
	v_mfma_f32_16x16x32_bf16 v[58:61], v[150:153], v[174:177], v[58:61]
	v_mfma_f32_16x16x32_bf16 v[46:49], v[142:145], v[182:185], v[46:49]
	v_mfma_f32_16x16x32_bf16 v[42:45], v[150:153], v[182:185], v[42:45]
	v_mfma_f32_16x16x32_bf16 v[30:33], v[142:145], v[190:193], v[30:33]
	v_mfma_f32_16x16x32_bf16 v[26:29], v[150:153], v[190:193], v[26:29]
	v_mfma_f32_16x16x32_bf16 v[14:17], v[142:145], v[198:201], v[14:17]
	v_mfma_f32_16x16x32_bf16 v[10:13], v[150:153], v[198:201], v[10:13]
	s_setprio 0
	s_setprio 1
	v_mfma_f32_16x16x32_bf16 v[54:57], v[154:157], v[170:173], v[54:57]
	v_mfma_f32_16x16x32_bf16 v[50:53], v[162:165], v[170:173], v[50:53]
	v_mfma_f32_16x16x32_bf16 v[38:41], v[154:157], v[178:181], v[38:41]
	v_mfma_f32_16x16x32_bf16 v[34:37], v[162:165], v[178:181], v[34:37]
	v_mfma_f32_16x16x32_bf16 v[22:25], v[154:157], v[186:189], v[22:25]
	v_mfma_f32_16x16x32_bf16 v[18:21], v[162:165], v[186:189], v[18:21]
	v_mfma_f32_16x16x32_bf16 v[6:9], v[154:157], v[194:197], v[6:9]
	v_mfma_f32_16x16x32_bf16 v[2:5], v[162:165], v[194:197], v[2:5]
	v_mfma_f32_16x16x32_bf16 v[54:57], v[158:161], v[174:177], v[54:57]
	v_mfma_f32_16x16x32_bf16 v[50:53], v[166:169], v[174:177], v[50:53]
	v_mfma_f32_16x16x32_bf16 v[38:41], v[158:161], v[182:185], v[38:41]
	v_mfma_f32_16x16x32_bf16 v[34:37], v[166:169], v[182:185], v[34:37]
	v_mfma_f32_16x16x32_bf16 v[22:25], v[158:161], v[190:193], v[22:25]
	v_mfma_f32_16x16x32_bf16 v[18:21], v[166:169], v[190:193], v[18:21]
	v_mfma_f32_16x16x32_bf16 v[6:9], v[158:161], v[198:201], v[6:9]
	v_mfma_f32_16x16x32_bf16 v[2:5], v[166:169], v[198:201], v[2:5]
	s_setprio 0
	s_barrier
	s_add_i32 s50, s50, 2
	s_add_u32 s2, s2, 0x100
	s_addc_u32 s3, s3, 0
	s_cmp_gt_u32 s50, 41
	s_cbranch_scc0 .LBB0_953

.LBB0_1087:
	s_add_u32 s2, s6, 0x40080
	s_addc_u32 s3, s7, 0
	s_add_u32 s8, s8, 0x100
	s_addc_u32 s9, s9, 0
	s_mov_b32 s22, -2
	s_add_u32 s4, s2, 0xfffc0080
	s_addc_u32 s5, s3, -1
	s_add_i32 s23, 0, 0x10000
	s_cmp_eq_u32 s22, 12
	s_cselect_b32 s5, s49, s5
	s_cselect_b32 s4, s48, s4
	s_waitcnt vmcnt(0)
	v_add_u32_e32 v0, s23, v145
	s_cselect_b32 s7, s97, s9
	s_cselect_b32 s6, s96, s8
	s_add_i32 s25, 0, 0x14000
	ds_read_b128 v[146:149], v0
	ds_read_b128 v[152:155], v0 offset:1024
	ds_read_b128 v[156:159], v0 offset:2048
	ds_read_b128 v[160:163], v0 offset:3072
	ds_read_b128 v[164:167], v0 offset:16384
	ds_read_b128 v[168:171], v0 offset:17408
	ds_read_b128 v[172:175], v0 offset:18432
	ds_read_b128 v[176:179], v0 offset:19456
	ds_read_b128 v[180:183], v150
	ds_read_b128 v[184:187], v150 offset:1024
	ds_read_b128 v[188:191], v150 offset:2048
	ds_read_b128 v[192:195], v150 offset:3072
	ds_read_b128 v[196:199], v150 offset:4096
	ds_read_b128 v[200:203], v150 offset:5120
	ds_read_b128 v[204:207], v150 offset:6144
	ds_read_b128 v[208:211], v150 offset:7168
	s_add_i32 m0, s60, 0xc000
	s_nop 0
	global_load_lds_dwordx4 v131, s[2:3]
	s_add_i32 m0, s60, 0xe000
	s_nop 0
	global_load_lds_dwordx4 v133, s[2:3]
	s_waitcnt vmcnt(8) lgkmcnt(0)
	s_setprio 1
	s_barrier
	v_mfma_f32_16x16x32_bf16 v[126:129], v[146:149], v[180:183], 0
	v_mfma_f32_16x16x32_bf16 v[122:125], v[156:159], v[180:183], 0
	v_mfma_f32_16x16x32_bf16 v[110:113], v[146:149], v[188:191], 0
	v_mfma_f32_16x16x32_bf16 v[106:109], v[156:159], v[188:191], 0
	v_mfma_f32_16x16x32_bf16 v[94:97], v[146:149], v[196:199], 0
	v_mfma_f32_16x16x32_bf16 v[90:93], v[156:159], v[196:199], 0
	v_mfma_f32_16x16x32_bf16 v[78:81], v[146:149], v[204:207], 0
	v_mfma_f32_16x16x32_bf16 v[74:77], v[156:159], v[204:207], 0
	v_mfma_f32_16x16x32_bf16 v[126:129], v[152:155], v[184:187], v[126:129]
	v_mfma_f32_16x16x32_bf16 v[122:125], v[160:163], v[184:187], v[122:125]
	v_mfma_f32_16x16x32_bf16 v[110:113], v[152:155], v[192:195], v[110:113]
	v_mfma_f32_16x16x32_bf16 v[106:109], v[160:163], v[192:195], v[106:109]
	v_mfma_f32_16x16x32_bf16 v[94:97], v[152:155], v[200:203], v[94:97]
	v_mfma_f32_16x16x32_bf16 v[90:93], v[160:163], v[200:203], v[90:93]
	v_mfma_f32_16x16x32_bf16 v[78:81], v[152:155], v[208:211], v[78:81]
	v_mfma_f32_16x16x32_bf16 v[74:77], v[160:163], v[208:211], v[74:77]
	s_setprio 0
	s_setprio 1
	v_mfma_f32_16x16x32_bf16 v[118:121], v[164:167], v[180:183], 0
	v_mfma_f32_16x16x32_bf16 v[114:117], v[172:175], v[180:183], 0
	v_mfma_f32_16x16x32_bf16 v[102:105], v[164:167], v[188:191], 0
	v_mfma_f32_16x16x32_bf16 v[98:101], v[172:175], v[188:191], 0
	v_mfma_f32_16x16x32_bf16 v[86:89], v[164:167], v[196:199], 0
	v_mfma_f32_16x16x32_bf16 v[82:85], v[172:175], v[196:199], 0
	v_mfma_f32_16x16x32_bf16 v[70:73], v[164:167], v[204:207], 0
	v_mfma_f32_16x16x32_bf16 v[66:69], v[172:175], v[204:207], 0
	v_mfma_f32_16x16x32_bf16 v[118:121], v[168:171], v[184:187], v[118:121]
	v_mfma_f32_16x16x32_bf16 v[114:117], v[176:179], v[184:187], v[114:117]
	v_mfma_f32_16x16x32_bf16 v[102:105], v[168:171], v[192:195], v[102:105]
	v_mfma_f32_16x16x32_bf16 v[98:101], v[176:179], v[192:195], v[98:101]
	v_mfma_f32_16x16x32_bf16 v[86:89], v[168:171], v[200:203], v[86:89]
	v_mfma_f32_16x16x32_bf16 v[82:85], v[176:179], v[200:203], v[82:85]
	v_mfma_f32_16x16x32_bf16 v[70:73], v[168:171], v[208:211], v[70:73]
	v_mfma_f32_16x16x32_bf16 v[66:69], v[176:179], v[208:211], v[66:69]
	s_setprio 0
	s_barrier
	s_add_i32 s23, s23, s42
	ds_read_b128 v[180:183], v150 offset:16384
	ds_read_b128 v[184:187], v150 offset:17408
	ds_read_b128 v[188:191], v150 offset:18432
	ds_read_b128 v[192:195], v150 offset:19456
	ds_read_b128 v[196:199], v150 offset:20480
	ds_read_b128 v[200:203], v150 offset:21504
	ds_read_b128 v[204:207], v150 offset:22528
	ds_read_b128 v[208:211], v150 offset:23552
	s_mov_b32 m0, s23
	s_nop 0
	global_load_lds_dwordx4 v137, s[6:7]
	s_add_i32 m0, s23, 0x2000
	s_add_u32 s46, s6, 0x40000
	global_load_lds_dwordx4 v139, s[6:7]
	s_addc_u32 s47, s7, 0
	s_add_i32 s23, s25, s42
	s_mov_b32 m0, s23
	s_nop 0
	global_load_lds_dwordx4 v137, s[46:47]
	s_add_i32 m0, s23, 0x2000
	s_nop 0
	global_load_lds_dwordx4 v139, s[46:47]
	s_mov_b32 m0, s60
	s_nop 0
	global_load_lds_dwordx4 v131, s[4:5]
	s_mov_b32 m0, s61
	s_nop 0
	global_load_lds_dwordx4 v133, s[4:5]
	s_waitcnt vmcnt(8) lgkmcnt(0)
	s_setprio 1
	s_barrier
	v_mfma_f32_16x16x32_bf16 v[62:65], v[146:149], v[180:183], 0
	v_mfma_f32_16x16x32_bf16 v[58:61], v[156:159], v[180:183], 0
	v_mfma_f32_16x16x32_bf16 v[46:49], v[146:149], v[188:191], 0
	v_mfma_f32_16x16x32_bf16 v[42:45], v[156:159], v[188:191], 0
	v_mfma_f32_16x16x32_bf16 v[30:33], v[146:149], v[196:199], 0
	v_mfma_f32_16x16x32_bf16 v[26:29], v[156:159], v[196:199], 0
	v_mfma_f32_16x16x32_bf16 v[14:17], v[146:149], v[204:207], 0
	v_mfma_f32_16x16x32_bf16 v[10:13], v[156:159], v[204:207], 0
	v_mfma_f32_16x16x32_bf16 v[62:65], v[152:155], v[184:187], v[62:65]
	v_mfma_f32_16x16x32_bf16 v[58:61], v[160:163], v[184:187], v[58:61]
	v_mfma_f32_16x16x32_bf16 v[46:49], v[152:155], v[192:195], v[46:49]
	v_mfma_f32_16x16x32_bf16 v[42:45], v[160:163], v[192:195], v[42:45]
	v_mfma_f32_16x16x32_bf16 v[30:33], v[152:155], v[200:203], v[30:33]
	v_mfma_f32_16x16x32_bf16 v[26:29], v[160:163], v[200:203], v[26:29]
	v_mfma_f32_16x16x32_bf16 v[14:17], v[152:155], v[208:211], v[14:17]
	v_mfma_f32_16x16x32_bf16 v[10:13], v[160:163], v[208:211], v[10:13]
	s_setprio 0
	s_setprio 1
	v_mfma_f32_16x16x32_bf16 v[54:57], v[164:167], v[180:183], 0
	v_mfma_f32_16x16x32_bf16 v[50:53], v[172:175], v[180:183], 0
	v_mfma_f32_16x16x32_bf16 v[38:41], v[164:167], v[188:191], 0
	v_mfma_f32_16x16x32_bf16 v[34:37], v[172:175], v[188:191], 0
	v_mfma_f32_16x16x32_bf16 v[22:25], v[164:167], v[196:199], 0
	v_mfma_f32_16x16x32_bf16 v[18:21], v[172:175], v[196:199], 0
	v_mfma_f32_16x16x32_bf16 v[6:9], v[164:167], v[204:207], 0
	v_mfma_f32_16x16x32_bf16 v[2:5], v[172:175], v[204:207], 0
	v_mfma_f32_16x16x32_bf16 v[54:57], v[168:171], v[184:187], v[54:57]
	v_mfma_f32_16x16x32_bf16 v[50:53], v[176:179], v[184:187], v[50:53]
	v_mfma_f32_16x16x32_bf16 v[38:41], v[168:171], v[192:195], v[38:41]
	v_mfma_f32_16x16x32_bf16 v[34:37], v[176:179], v[192:195], v[34:37]
	v_mfma_f32_16x16x32_bf16 v[22:25], v[168:171], v[200:203], v[22:25]
	v_mfma_f32_16x16x32_bf16 v[18:21], v[176:179], v[200:203], v[18:21]
	v_mfma_f32_16x16x32_bf16 v[6:9], v[168:171], v[208:211], v[6:9]
	v_mfma_f32_16x16x32_bf16 v[2:5], v[176:179], v[208:211], v[2:5]
	s_setprio 0
	s_barrier
	s_add_i32 s23, 0, 0x18000
	s_add_i32 s25, 0, 0x1c000
	ds_read_b128 v[146:149], v0 offset:32768
	ds_read_b128 v[152:155], v0 offset:33792
	ds_read_b128 v[156:159], v0 offset:34816
	ds_read_b128 v[160:163], v0 offset:35840
	ds_read_b128 v[164:167], v0 offset:49152
	ds_read_b128 v[168:171], v0 offset:50176
	ds_read_b128 v[172:175], v0 offset:51200
	ds_read_b128 v[176:179], v0 offset:52224
	s_add_u32 s46, s4, 0x40000
	s_mov_b32 m0, s66
	ds_read_b128 v[180:183], v150 offset:32768
	ds_read_b128 v[184:187], v150 offset:33792
	ds_read_b128 v[188:191], v150 offset:34816
	ds_read_b128 v[192:195], v150 offset:35840
	ds_read_b128 v[196:199], v150 offset:36864
	ds_read_b128 v[200:203], v150 offset:37888
	ds_read_b128 v[204:207], v150 offset:38912
	ds_read_b128 v[208:211], v150 offset:39936
	s_addc_u32 s47, s5, 0
	s_nop 0
	global_load_lds_dwordx4 v131, s[46:47]
	s_mov_b32 m0, s67
	s_nop 0
	global_load_lds_dwordx4 v133, s[46:47]
	s_waitcnt vmcnt(8) lgkmcnt(0)
	s_setprio 1
	s_barrier
	v_mfma_f32_16x16x32_bf16 v[126:129], v[146:149], v[180:183], v[126:129]
	v_mfma_f32_16x16x32_bf16 v[122:125], v[156:159], v[180:183], v[122:125]
	v_mfma_f32_16x16x32_bf16 v[110:113], v[146:149], v[188:191], v[110:113]
	v_mfma_f32_16x16x32_bf16 v[106:109], v[156:159], v[188:191], v[106:109]
	v_mfma_f32_16x16x32_bf16 v[94:97], v[146:149], v[196:199], v[94:97]
	v_mfma_f32_16x16x32_bf16 v[90:93], v[156:159], v[196:199], v[90:93]
	v_mfma_f32_16x16x32_bf16 v[78:81], v[146:149], v[204:207], v[78:81]
	v_mfma_f32_16x16x32_bf16 v[74:77], v[156:159], v[204:207], v[74:77]
	v_mfma_f32_16x16x32_bf16 v[126:129], v[152:155], v[184:187], v[126:129]
	v_mfma_f32_16x16x32_bf16 v[122:125], v[160:163], v[184:187], v[122:125]
	v_mfma_f32_16x16x32_bf16 v[110:113], v[152:155], v[192:195], v[110:113]
	v_mfma_f32_16x16x32_bf16 v[106:109], v[160:163], v[192:195], v[106:109]
	v_mfma_f32_16x16x32_bf16 v[94:97], v[152:155], v[200:203], v[94:97]
	v_mfma_f32_16x16x32_bf16 v[90:93], v[160:163], v[200:203], v[90:93]
	v_mfma_f32_16x16x32_bf16 v[78:81], v[152:155], v[208:211], v[78:81]
	v_mfma_f32_16x16x32_bf16 v[74:77], v[160:163], v[208:211], v[74:77]
	s_setprio 0
	s_setprio 1
	v_mfma_f32_16x16x32_bf16 v[118:121], v[164:167], v[180:183], v[118:121]
	v_mfma_f32_16x16x32_bf16 v[114:117], v[172:175], v[180:183], v[114:117]
	v_mfma_f32_16x16x32_bf16 v[102:105], v[164:167], v[188:191], v[102:105]
	v_mfma_f32_16x16x32_bf16 v[98:101], v[172:175], v[188:191], v[98:101]
	v_mfma_f32_16x16x32_bf16 v[86:89], v[164:167], v[196:199], v[86:89]
	v_mfma_f32_16x16x32_bf16 v[82:85], v[172:175], v[196:199], v[82:85]
	v_mfma_f32_16x16x32_bf16 v[70:73], v[164:167], v[204:207], v[70:73]
	v_mfma_f32_16x16x32_bf16 v[66:69], v[172:175], v[204:207], v[66:69]
	v_mfma_f32_16x16x32_bf16 v[118:121], v[168:171], v[184:187], v[118:121]
	v_mfma_f32_16x16x32_bf16 v[114:117], v[176:179], v[184:187], v[114:117]
	v_mfma_f32_16x16x32_bf16 v[102:105], v[168:171], v[192:195], v[102:105]
	v_mfma_f32_16x16x32_bf16 v[98:101], v[176:179], v[192:195], v[98:101]
	v_mfma_f32_16x16x32_bf16 v[86:89], v[168:171], v[200:203], v[86:89]
	v_mfma_f32_16x16x32_bf16 v[82:85], v[176:179], v[200:203], v[82:85]
	v_mfma_f32_16x16x32_bf16 v[70:73], v[168:171], v[208:211], v[70:73]
	v_mfma_f32_16x16x32_bf16 v[66:69], v[176:179], v[208:211], v[66:69]
	s_setprio 0
	s_barrier
	ds_read_b128 v[180:183], v150 offset:49152
	ds_read_b128 v[184:187], v150 offset:50176
	ds_read_b128 v[188:191], v150 offset:51200
	ds_read_b128 v[192:195], v150 offset:52224
	ds_read_b128 v[196:199], v150 offset:53248
	ds_read_b128 v[200:203], v150 offset:54272
	ds_read_b128 v[204:207], v150 offset:55296
	ds_read_b128 v[208:211], v150 offset:56320
	s_add_i32 s23, s23, s42
	s_add_u32 s100, s6, s38
	s_addc_u32 s101, s7, s39
	s_mov_b32 m0, s23
	s_nop 0
	global_load_lds_dwordx4 v137, s[100:101]
	s_add_i32 m0, s23, 0x2000
	s_nop 0
	s_add_u32 s6, s6, 0x40080
	s_addc_u32 s7, s7, 0
	s_add_i32 s23, s25, s42
	global_load_lds_dwordx4 v139, s[100:101]
	s_mov_b32 m0, s23
	s_nop 0
	global_load_lds_dwordx4 v137, s[6:7]
	s_add_i32 m0, s23, 0x2000
	s_nop 0
	global_load_lds_dwordx4 v139, s[6:7]
	s_mov_b32 m0, s70
	s_add_u32 s100, s4, s38
	s_addc_u32 s101, s5, s39
	v_mov_b32_e32 v0, v133
	global_load_lds_dwordx4 v131, s[100:101]
	s_mov_b32 m0, s71
	s_nop 0
	global_load_lds_dwordx4 v133, s[100:101]
	s_waitcnt vmcnt(8) lgkmcnt(0)
	s_setprio 1
	s_barrier
	v_mfma_f32_16x16x32_bf16 v[62:65], v[146:149], v[180:183], v[62:65]
	v_mfma_f32_16x16x32_bf16 v[58:61], v[156:159], v[180:183], v[58:61]
	v_mfma_f32_16x16x32_bf16 v[46:49], v[146:149], v[188:191], v[46:49]
	v_mfma_f32_16x16x32_bf16 v[42:45], v[156:159], v[188:191], v[42:45]
	v_mfma_f32_16x16x32_bf16 v[30:33], v[146:149], v[196:199], v[30:33]
	v_mfma_f32_16x16x32_bf16 v[26:29], v[156:159], v[196:199], v[26:29]
	v_mfma_f32_16x16x32_bf16 v[14:17], v[146:149], v[204:207], v[14:17]
	v_mfma_f32_16x16x32_bf16 v[10:13], v[156:159], v[204:207], v[10:13]
	v_mfma_f32_16x16x32_bf16 v[62:65], v[152:155], v[184:187], v[62:65]
	v_mfma_f32_16x16x32_bf16 v[58:61], v[160:163], v[184:187], v[58:61]
	v_mfma_f32_16x16x32_bf16 v[46:49], v[152:155], v[192:195], v[46:49]
	v_mfma_f32_16x16x32_bf16 v[42:45], v[160:163], v[192:195], v[42:45]
	v_mfma_f32_16x16x32_bf16 v[30:33], v[152:155], v[200:203], v[30:33]
	v_mfma_f32_16x16x32_bf16 v[26:29], v[160:163], v[200:203], v[26:29]
	v_mfma_f32_16x16x32_bf16 v[14:17], v[152:155], v[208:211], v[14:17]
	v_mfma_f32_16x16x32_bf16 v[10:13], v[160:163], v[208:211], v[10:13]
	s_setprio 0
	s_setprio 1
	v_mfma_f32_16x16x32_bf16 v[54:57], v[164:167], v[180:183], v[54:57]
	v_mfma_f32_16x16x32_bf16 v[50:53], v[172:175], v[180:183], v[50:53]
	v_mfma_f32_16x16x32_bf16 v[38:41], v[164:167], v[188:191], v[38:41]
	v_mfma_f32_16x16x32_bf16 v[34:37], v[172:175], v[188:191], v[34:37]
	v_mfma_f32_16x16x32_bf16 v[22:25], v[164:167], v[196:199], v[22:25]
	v_mfma_f32_16x16x32_bf16 v[18:21], v[172:175], v[196:199], v[18:21]
	v_mfma_f32_16x16x32_bf16 v[6:9], v[164:167], v[204:207], v[6:9]
	v_mfma_f32_16x16x32_bf16 v[2:5], v[172:175], v[204:207], v[2:5]
	v_mfma_f32_16x16x32_bf16 v[54:57], v[168:171], v[184:187], v[54:57]
	v_mfma_f32_16x16x32_bf16 v[50:53], v[176:179], v[184:187], v[50:53]
	v_mfma_f32_16x16x32_bf16 v[38:41], v[168:171], v[192:195], v[38:41]
	v_mfma_f32_16x16x32_bf16 v[34:37], v[176:179], v[192:195], v[34:37]
	v_mfma_f32_16x16x32_bf16 v[22:25], v[168:171], v[200:203], v[22:25]
	v_mfma_f32_16x16x32_bf16 v[18:21], v[176:179], v[200:203], v[18:21]
	v_mfma_f32_16x16x32_bf16 v[6:9], v[168:171], v[208:211], v[6:9]
	v_mfma_f32_16x16x32_bf16 v[2:5], v[176:179], v[208:211], v[2:5]
	s_setprio 0
	s_barrier
	s_add_i32 s22, s22, 2
	s_add_u32 s2, s2, 0x100
	s_addc_u32 s3, s3, 0
	s_add_u32 s8, s8, 0x100
	s_addc_u32 s9, s9, 0
	s_cmp_gt_u32 s22, 13
	s_cbranch_scc0 .LBB0_1088
	s_branch .Lpeel_exit_1088
	.p2align	6
.LBB0_1088:
	s_add_u32 s4, s2, 0xfffc0080
	s_addc_u32 s5, s3, -1
	s_add_i32 s23, 0, 0x10000
	s_cmp_eq_u32 s22, 12
	s_cselect_b32 s5, s49, s5
	s_cselect_b32 s4, s48, s4
	v_add_u32_e32 v0, s23, v145
	s_cselect_b32 s7, s97, s9
	s_cselect_b32 s6, s96, s8
	s_add_i32 s25, 0, 0x14000
	ds_read_b128 v[146:149], v0
	ds_read_b128 v[152:155], v0 offset:1024
	ds_read_b128 v[156:159], v0 offset:2048
	ds_read_b128 v[160:163], v0 offset:3072
	ds_read_b128 v[164:167], v0 offset:16384
	ds_read_b128 v[168:171], v0 offset:17408
	ds_read_b128 v[172:175], v0 offset:18432
	ds_read_b128 v[176:179], v0 offset:19456
	ds_read_b128 v[180:183], v150
	ds_read_b128 v[184:187], v150 offset:1024
	ds_read_b128 v[188:191], v150 offset:2048
	ds_read_b128 v[192:195], v150 offset:3072
	ds_read_b128 v[196:199], v150 offset:4096
	ds_read_b128 v[200:203], v150 offset:5120
	ds_read_b128 v[204:207], v150 offset:6144
	ds_read_b128 v[208:211], v150 offset:7168
	s_add_i32 m0, s60, 0xc000
	s_nop 0
	global_load_lds_dwordx4 v131, s[2:3]
	s_add_i32 m0, s60, 0xe000
	s_nop 0
	global_load_lds_dwordx4 v133, s[2:3]
	s_waitcnt vmcnt(8) lgkmcnt(0)
	s_setprio 1
	s_barrier
	v_mfma_f32_16x16x32_bf16 v[126:129], v[146:149], v[180:183], v[126:129]
	v_mfma_f32_16x16x32_bf16 v[122:125], v[156:159], v[180:183], v[122:125]
	v_mfma_f32_16x16x32_bf16 v[110:113], v[146:149], v[188:191], v[110:113]
	v_mfma_f32_16x16x32_bf16 v[106:109], v[156:159], v[188:191], v[106:109]
	v_mfma_f32_16x16x32_bf16 v[94:97], v[146:149], v[196:199], v[94:97]
	v_mfma_f32_16x16x32_bf16 v[90:93], v[156:159], v[196:199], v[90:93]
	v_mfma_f32_16x16x32_bf16 v[78:81], v[146:149], v[204:207], v[78:81]
	v_mfma_f32_16x16x32_bf16 v[74:77], v[156:159], v[204:207], v[74:77]
	v_mfma_f32_16x16x32_bf16 v[126:129], v[152:155], v[184:187], v[126:129]
	v_mfma_f32_16x16x32_bf16 v[122:125], v[160:163], v[184:187], v[122:125]
	v_mfma_f32_16x16x32_bf16 v[110:113], v[152:155], v[192:195], v[110:113]
	v_mfma_f32_16x16x32_bf16 v[106:109], v[160:163], v[192:195], v[106:109]
	v_mfma_f32_16x16x32_bf16 v[94:97], v[152:155], v[200:203], v[94:97]
	v_mfma_f32_16x16x32_bf16 v[90:93], v[160:163], v[200:203], v[90:93]
	v_mfma_f32_16x16x32_bf16 v[78:81], v[152:155], v[208:211], v[78:81]
	v_mfma_f32_16x16x32_bf16 v[74:77], v[160:163], v[208:211], v[74:77]
	s_setprio 0
	s_setprio 1
	v_mfma_f32_16x16x32_bf16 v[118:121], v[164:167], v[180:183], v[118:121]
	v_mfma_f32_16x16x32_bf16 v[114:117], v[172:175], v[180:183], v[114:117]
	v_mfma_f32_16x16x32_bf16 v[102:105], v[164:167], v[188:191], v[102:105]
	v_mfma_f32_16x16x32_bf16 v[98:101], v[172:175], v[188:191], v[98:101]
	v_mfma_f32_16x16x32_bf16 v[86:89], v[164:167], v[196:199], v[86:89]
	v_mfma_f32_16x16x32_bf16 v[82:85], v[172:175], v[196:199], v[82:85]
	v_mfma_f32_16x16x32_bf16 v[70:73], v[164:167], v[204:207], v[70:73]
	v_mfma_f32_16x16x32_bf16 v[66:69], v[172:175], v[204:207], v[66:69]
	v_mfma_f32_16x16x32_bf16 v[118:121], v[168:171], v[184:187], v[118:121]
	v_mfma_f32_16x16x32_bf16 v[114:117], v[176:179], v[184:187], v[114:117]
	v_mfma_f32_16x16x32_bf16 v[102:105], v[168:171], v[192:195], v[102:105]
	v_mfma_f32_16x16x32_bf16 v[98:101], v[176:179], v[192:195], v[98:101]
	v_mfma_f32_16x16x32_bf16 v[86:89], v[168:171], v[200:203], v[86:89]
	v_mfma_f32_16x16x32_bf16 v[82:85], v[176:179], v[200:203], v[82:85]
	v_mfma_f32_16x16x32_bf16 v[70:73], v[168:171], v[208:211], v[70:73]
	v_mfma_f32_16x16x32_bf16 v[66:69], v[176:179], v[208:211], v[66:69]
	s_setprio 0
	s_barrier
	s_add_i32 s23, s23, s42
	ds_read_b128 v[180:183], v150 offset:16384
	ds_read_b128 v[184:187], v150 offset:17408
	ds_read_b128 v[188:191], v150 offset:18432
	ds_read_b128 v[192:195], v150 offset:19456
	ds_read_b128 v[196:199], v150 offset:20480
	ds_read_b128 v[200:203], v150 offset:21504
	ds_read_b128 v[204:207], v150 offset:22528
	ds_read_b128 v[208:211], v150 offset:23552
	s_mov_b32 m0, s23
	s_nop 0
	global_load_lds_dwordx4 v137, s[6:7]
	s_add_i32 m0, s23, 0x2000
	s_add_u32 s46, s6, 0x40000
	global_load_lds_dwordx4 v139, s[6:7]
	s_addc_u32 s47, s7, 0
	s_add_i32 s23, s25, s42
	s_mov_b32 m0, s23
	s_nop 0
	global_load_lds_dwordx4 v137, s[46:47]
	s_add_i32 m0, s23, 0x2000
	s_nop 0
	global_load_lds_dwordx4 v139, s[46:47]
	s_mov_b32 m0, s60
	s_nop 0
	global_load_lds_dwordx4 v131, s[4:5]
	s_mov_b32 m0, s61
	s_nop 0
	global_load_lds_dwordx4 v133, s[4:5]
	s_waitcnt vmcnt(8) lgkmcnt(0)
	s_setprio 1
	s_barrier
	v_mfma_f32_16x16x32_bf16 v[62:65], v[146:149], v[180:183], v[62:65]
	v_mfma_f32_16x16x32_bf16 v[58:61], v[156:159], v[180:183], v[58:61]
	v_mfma_f32_16x16x32_bf16 v[46:49], v[146:149], v[188:191], v[46:49]
	v_mfma_f32_16x16x32_bf16 v[42:45], v[156:159], v[188:191], v[42:45]
	v_mfma_f32_16x16x32_bf16 v[30:33], v[146:149], v[196:199], v[30:33]
	v_mfma_f32_16x16x32_bf16 v[26:29], v[156:159], v[196:199], v[26:29]
	v_mfma_f32_16x16x32_bf16 v[14:17], v[146:149], v[204:207], v[14:17]
	v_mfma_f32_16x16x32_bf16 v[10:13], v[156:159], v[204:207], v[10:13]
	v_mfma_f32_16x16x32_bf16 v[62:65], v[152:155], v[184:187], v[62:65]
	v_mfma_f32_16x16x32_bf16 v[58:61], v[160:163], v[184:187], v[58:61]
	v_mfma_f32_16x16x32_bf16 v[46:49], v[152:155], v[192:195], v[46:49]
	v_mfma_f32_16x16x32_bf16 v[42:45], v[160:163], v[192:195], v[42:45]
	v_mfma_f32_16x16x32_bf16 v[30:33], v[152:155], v[200:203], v[30:33]
	v_mfma_f32_16x16x32_bf16 v[26:29], v[160:163], v[200:203], v[26:29]
	v_mfma_f32_16x16x32_bf16 v[14:17], v[152:155], v[208:211], v[14:17]
	v_mfma_f32_16x16x32_bf16 v[10:13], v[160:163], v[208:211], v[10:13]
	s_setprio 0
	s_setprio 1
	v_mfma_f32_16x16x32_bf16 v[54:57], v[164:167], v[180:183], v[54:57]
	v_mfma_f32_16x16x32_bf16 v[50:53], v[172:175], v[180:183], v[50:53]
	v_mfma_f32_16x16x32_bf16 v[38:41], v[164:167], v[188:191], v[38:41]
	v_mfma_f32_16x16x32_bf16 v[34:37], v[172:175], v[188:191], v[34:37]
	v_mfma_f32_16x16x32_bf16 v[22:25], v[164:167], v[196:199], v[22:25]
	v_mfma_f32_16x16x32_bf16 v[18:21], v[172:175], v[196:199], v[18:21]
	v_mfma_f32_16x16x32_bf16 v[6:9], v[164:167], v[204:207], v[6:9]
	v_mfma_f32_16x16x32_bf16 v[2:5], v[172:175], v[204:207], v[2:5]
	v_mfma_f32_16x16x32_bf16 v[54:57], v[168:171], v[184:187], v[54:57]
	v_mfma_f32_16x16x32_bf16 v[50:53], v[176:179], v[184:187], v[50:53]
	v_mfma_f32_16x16x32_bf16 v[38:41], v[168:171], v[192:195], v[38:41]
	v_mfma_f32_16x16x32_bf16 v[34:37], v[176:179], v[192:195], v[34:37]
	v_mfma_f32_16x16x32_bf16 v[22:25], v[168:171], v[200:203], v[22:25]
	v_mfma_f32_16x16x32_bf16 v[18:21], v[176:179], v[200:203], v[18:21]
	v_mfma_f32_16x16x32_bf16 v[6:9], v[168:171], v[208:211], v[6:9]
	v_mfma_f32_16x16x32_bf16 v[2:5], v[176:179], v[208:211], v[2:5]
	s_setprio 0
	s_barrier
	s_add_i32 s23, 0, 0x18000
	s_add_i32 s25, 0, 0x1c000
	ds_read_b128 v[146:149], v0 offset:32768
	ds_read_b128 v[152:155], v0 offset:33792
	ds_read_b128 v[156:159], v0 offset:34816
	ds_read_b128 v[160:163], v0 offset:35840
	ds_read_b128 v[164:167], v0 offset:49152
	ds_read_b128 v[168:171], v0 offset:50176
	ds_read_b128 v[172:175], v0 offset:51200
	ds_read_b128 v[176:179], v0 offset:52224
	s_add_u32 s46, s4, 0x40000
	s_mov_b32 m0, s66
	ds_read_b128 v[180:183], v150 offset:32768
	ds_read_b128 v[184:187], v150 offset:33792
	ds_read_b128 v[188:191], v150 offset:34816
	ds_read_b128 v[192:195], v150 offset:35840
	ds_read_b128 v[196:199], v150 offset:36864
	ds_read_b128 v[200:203], v150 offset:37888
	ds_read_b128 v[204:207], v150 offset:38912
	ds_read_b128 v[208:211], v150 offset:39936
	s_addc_u32 s47, s5, 0
	s_nop 0
	global_load_lds_dwordx4 v131, s[46:47]
	s_mov_b32 m0, s67
	s_nop 0
	global_load_lds_dwordx4 v133, s[46:47]
	s_waitcnt vmcnt(8) lgkmcnt(0)
	s_setprio 1
	s_barrier
	v_mfma_f32_16x16x32_bf16 v[126:129], v[146:149], v[180:183], v[126:129]
	v_mfma_f32_16x16x32_bf16 v[122:125], v[156:159], v[180:183], v[122:125]
	v_mfma_f32_16x16x32_bf16 v[110:113], v[146:149], v[188:191], v[110:113]
	v_mfma_f32_16x16x32_bf16 v[106:109], v[156:159], v[188:191], v[106:109]
	v_mfma_f32_16x16x32_bf16 v[94:97], v[146:149], v[196:199], v[94:97]
	v_mfma_f32_16x16x32_bf16 v[90:93], v[156:159], v[196:199], v[90:93]
	v_mfma_f32_16x16x32_bf16 v[78:81], v[146:149], v[204:207], v[78:81]
	v_mfma_f32_16x16x32_bf16 v[74:77], v[156:159], v[204:207], v[74:77]
	v_mfma_f32_16x16x32_bf16 v[126:129], v[152:155], v[184:187], v[126:129]
	v_mfma_f32_16x16x32_bf16 v[122:125], v[160:163], v[184:187], v[122:125]
	v_mfma_f32_16x16x32_bf16 v[110:113], v[152:155], v[192:195], v[110:113]
	v_mfma_f32_16x16x32_bf16 v[106:109], v[160:163], v[192:195], v[106:109]
	v_mfma_f32_16x16x32_bf16 v[94:97], v[152:155], v[200:203], v[94:97]
	v_mfma_f32_16x16x32_bf16 v[90:93], v[160:163], v[200:203], v[90:93]
	v_mfma_f32_16x16x32_bf16 v[78:81], v[152:155], v[208:211], v[78:81]
	v_mfma_f32_16x16x32_bf16 v[74:77], v[160:163], v[208:211], v[74:77]
	s_setprio 0
	s_setprio 1
	v_mfma_f32_16x16x32_bf16 v[118:121], v[164:167], v[180:183], v[118:121]
	v_mfma_f32_16x16x32_bf16 v[114:117], v[172:175], v[180:183], v[114:117]
	v_mfma_f32_16x16x32_bf16 v[102:105], v[164:167], v[188:191], v[102:105]
	v_mfma_f32_16x16x32_bf16 v[98:101], v[172:175], v[188:191], v[98:101]
	v_mfma_f32_16x16x32_bf16 v[86:89], v[164:167], v[196:199], v[86:89]
	v_mfma_f32_16x16x32_bf16 v[82:85], v[172:175], v[196:199], v[82:85]
	v_mfma_f32_16x16x32_bf16 v[70:73], v[164:167], v[204:207], v[70:73]
	v_mfma_f32_16x16x32_bf16 v[66:69], v[172:175], v[204:207], v[66:69]
	v_mfma_f32_16x16x32_bf16 v[118:121], v[168:171], v[184:187], v[118:121]
	v_mfma_f32_16x16x32_bf16 v[114:117], v[176:179], v[184:187], v[114:117]
	v_mfma_f32_16x16x32_bf16 v[102:105], v[168:171], v[192:195], v[102:105]
	v_mfma_f32_16x16x32_bf16 v[98:101], v[176:179], v[192:195], v[98:101]
	v_mfma_f32_16x16x32_bf16 v[86:89], v[168:171], v[200:203], v[86:89]
	v_mfma_f32_16x16x32_bf16 v[82:85], v[176:179], v[200:203], v[82:85]
	v_mfma_f32_16x16x32_bf16 v[70:73], v[168:171], v[208:211], v[70:73]
	v_mfma_f32_16x16x32_bf16 v[66:69], v[176:179], v[208:211], v[66:69]
	s_setprio 0
	s_barrier
	ds_read_b128 v[180:183], v150 offset:49152
	ds_read_b128 v[184:187], v150 offset:50176
	ds_read_b128 v[188:191], v150 offset:51200
	ds_read_b128 v[192:195], v150 offset:52224
	ds_read_b128 v[196:199], v150 offset:53248
	ds_read_b128 v[200:203], v150 offset:54272
	ds_read_b128 v[204:207], v150 offset:55296
	ds_read_b128 v[208:211], v150 offset:56320
	s_add_i32 s23, s23, s42
	s_add_u32 s100, s6, s38
	s_addc_u32 s101, s7, s39
	s_mov_b32 m0, s23
	s_nop 0
	global_load_lds_dwordx4 v137, s[100:101]
	s_add_i32 m0, s23, 0x2000
	s_nop 0
	s_add_u32 s6, s6, 0x40080
	s_addc_u32 s7, s7, 0
	s_add_i32 s23, s25, s42
	global_load_lds_dwordx4 v139, s[100:101]
	s_mov_b32 m0, s23
	s_nop 0
	global_load_lds_dwordx4 v137, s[6:7]
	s_add_i32 m0, s23, 0x2000
	s_nop 0
	global_load_lds_dwordx4 v139, s[6:7]
	s_mov_b32 m0, s70
	s_add_u32 s100, s4, s38
	s_addc_u32 s101, s5, s39
	v_mov_b32_e32 v0, v133
	global_load_lds_dwordx4 v131, s[100:101]
	s_mov_b32 m0, s71
	s_nop 0
	global_load_lds_dwordx4 v133, s[100:101]
	s_waitcnt vmcnt(8) lgkmcnt(0)
	s_setprio 1
	s_barrier
	v_mfma_f32_16x16x32_bf16 v[62:65], v[146:149], v[180:183], v[62:65]
	v_mfma_f32_16x16x32_bf16 v[58:61], v[156:159], v[180:183], v[58:61]
	v_mfma_f32_16x16x32_bf16 v[46:49], v[146:149], v[188:191], v[46:49]
	v_mfma_f32_16x16x32_bf16 v[42:45], v[156:159], v[188:191], v[42:45]
	v_mfma_f32_16x16x32_bf16 v[30:33], v[146:149], v[196:199], v[30:33]
	v_mfma_f32_16x16x32_bf16 v[26:29], v[156:159], v[196:199], v[26:29]
	v_mfma_f32_16x16x32_bf16 v[14:17], v[146:149], v[204:207], v[14:17]
	v_mfma_f32_16x16x32_bf16 v[10:13], v[156:159], v[204:207], v[10:13]
	v_mfma_f32_16x16x32_bf16 v[62:65], v[152:155], v[184:187], v[62:65]
	v_mfma_f32_16x16x32_bf16 v[58:61], v[160:163], v[184:187], v[58:61]
	v_mfma_f32_16x16x32_bf16 v[46:49], v[152:155], v[192:195], v[46:49]
	v_mfma_f32_16x16x32_bf16 v[42:45], v[160:163], v[192:195], v[42:45]
	v_mfma_f32_16x16x32_bf16 v[30:33], v[152:155], v[200:203], v[30:33]
	v_mfma_f32_16x16x32_bf16 v[26:29], v[160:163], v[200:203], v[26:29]
	v_mfma_f32_16x16x32_bf16 v[14:17], v[152:155], v[208:211], v[14:17]
	v_mfma_f32_16x16x32_bf16 v[10:13], v[160:163], v[208:211], v[10:13]
	s_setprio 0
	s_setprio 1
	v_mfma_f32_16x16x32_bf16 v[54:57], v[164:167], v[180:183], v[54:57]
	v_mfma_f32_16x16x32_bf16 v[50:53], v[172:175], v[180:183], v[50:53]
	v_mfma_f32_16x16x32_bf16 v[38:41], v[164:167], v[188:191], v[38:41]
	v_mfma_f32_16x16x32_bf16 v[34:37], v[172:175], v[188:191], v[34:37]
	v_mfma_f32_16x16x32_bf16 v[22:25], v[164:167], v[196:199], v[22:25]
	v_mfma_f32_16x16x32_bf16 v[18:21], v[172:175], v[196:199], v[18:21]
	v_mfma_f32_16x16x32_bf16 v[6:9], v[164:167], v[204:207], v[6:9]
	v_mfma_f32_16x16x32_bf16 v[2:5], v[172:175], v[204:207], v[2:5]
	v_mfma_f32_16x16x32_bf16 v[54:57], v[168:171], v[184:187], v[54:57]
	v_mfma_f32_16x16x32_bf16 v[50:53], v[176:179], v[184:187], v[50:53]
	v_mfma_f32_16x16x32_bf16 v[38:41], v[168:171], v[192:195], v[38:41]
	v_mfma_f32_16x16x32_bf16 v[34:37], v[176:179], v[192:195], v[34:37]
	v_mfma_f32_16x16x32_bf16 v[22:25], v[168:171], v[200:203], v[22:25]
	v_mfma_f32_16x16x32_bf16 v[18:21], v[176:179], v[200:203], v[18:21]
	v_mfma_f32_16x16x32_bf16 v[6:9], v[168:171], v[208:211], v[6:9]
	v_mfma_f32_16x16x32_bf16 v[2:5], v[176:179], v[208:211], v[2:5]
	s_setprio 0
	s_barrier
	s_add_i32 s22, s22, 2
	s_add_u32 s2, s2, 0x100
	s_addc_u32 s3, s3, 0
	s_add_u32 s8, s8, 0x100
	s_addc_u32 s9, s9, 0
	s_cmp_gt_u32 s22, 13
	s_cbranch_scc0 .LBB0_1088

.LBB0_1473:
	s_add_u32 s16, s4, s14
	s_addc_u32 s17, s5, s15
	s_add_u32 s22, s16, 0x100
	s_addc_u32 s23, s17, 0
	s_and_b64 s[10:11], s[12:13], exec
	s_cselect_b32 s11, s5, s23
	s_cselect_b32 s10, s4, s22
	s_add_u32 s14, s6, s14
	s_addc_u32 s15, s7, s15
	s_add_u32 s14, s14, 0x100
	s_addc_u32 s15, s15, 0
	s_add_i32 s69, 0, 0x10000
	s_and_b64 s[12:13], s[12:13], exec
	s_cselect_b32 s13, s7, s15
	s_cselect_b32 s12, s6, s14
	s_add_i32 s15, 0, 0x14000
	s_add_u32 s46, s16, 0x80080
	s_addc_u32 s47, s17, 0
	s_add_i32 s71, s69, s41
	s_add_i32 m0, s42, 0xc000
	s_add_i32 s74, s42, 0xe000
	s_add_i32 s67, s71, 0x2000
	v_add_u32_e32 v0, s69, v136
	s_add_u32 s22, s12, 0x40000
	ds_read_b128 v[138:141], v0
	ds_read_b128 v[142:145], v0 offset:1024
	ds_read_b128 v[146:149], v0 offset:2048
	ds_read_b128 v[150:153], v0 offset:3072
	s_addc_u32 s23, s13, 0
	s_add_i32 s68, s15, s41
	ds_read_b128 v[154:157], v0 offset:16384
	ds_read_b128 v[158:161], v0 offset:17408
	ds_read_b128 v[162:165], v0 offset:18432
	ds_read_b128 v[166:169], v0 offset:19456
	s_add_i32 s66, s68, 0x2000
	s_add_i32 s65, 0, 0x18000
	s_add_i32 s64, 0, 0x1c000
	s_add_u32 s16, s10, 0x80000
	s_addc_u32 s17, s11, 0
	s_add_i32 s61, s65, s41
	s_add_i32 s60, s61, 0x2000
	s_add_u32 s14, s12, 0x40080
	s_addc_u32 s15, s13, 0
	s_add_i32 s70, s64, s41
	s_add_i32 s69, s70, 0x2000
	ds_read_b128 v[170:173], v137
	ds_read_b128 v[174:177], v137 offset:1024
	ds_read_b128 v[178:181], v137 offset:2048
	ds_read_b128 v[182:185], v137 offset:3072
	ds_read_b128 v[186:189], v137 offset:4096
	ds_read_b128 v[190:193], v137 offset:5120
	ds_read_b128 v[194:197], v137 offset:6144
	ds_read_b128 v[198:201], v137 offset:7168
	s_nop 0
	global_load_lds_dwordx4 v130, s[46:47]
	s_mov_b32 m0, s74
	s_nop 0
	global_load_lds_dwordx4 v132, s[46:47]
	s_waitcnt vmcnt(8) lgkmcnt(0)
	s_setprio 1
	s_barrier
	v_mfma_f32_16x16x32_bf16 v[126:129], v[138:141], v[170:173], v[126:129]
	v_mfma_f32_16x16x32_bf16 v[122:125], v[146:149], v[170:173], v[122:125]
	v_mfma_f32_16x16x32_bf16 v[118:121], v[138:141], v[178:181], v[118:121]
	v_mfma_f32_16x16x32_bf16 v[110:113], v[146:149], v[178:181], v[110:113]
	v_mfma_f32_16x16x32_bf16 v[102:105], v[138:141], v[186:189], v[102:105]
	v_mfma_f32_16x16x32_bf16 v[94:97], v[146:149], v[186:189], v[94:97]
	v_mfma_f32_16x16x32_bf16 v[86:89], v[138:141], v[194:197], v[86:89]
	v_mfma_f32_16x16x32_bf16 v[78:81], v[146:149], v[194:197], v[78:81]
	v_mfma_f32_16x16x32_bf16 v[126:129], v[142:145], v[174:177], v[126:129]
	v_mfma_f32_16x16x32_bf16 v[122:125], v[150:153], v[174:177], v[122:125]
	v_mfma_f32_16x16x32_bf16 v[118:121], v[142:145], v[182:185], v[118:121]
	v_mfma_f32_16x16x32_bf16 v[110:113], v[150:153], v[182:185], v[110:113]
	v_mfma_f32_16x16x32_bf16 v[102:105], v[142:145], v[190:193], v[102:105]
	v_mfma_f32_16x16x32_bf16 v[94:97], v[150:153], v[190:193], v[94:97]
	v_mfma_f32_16x16x32_bf16 v[86:89], v[142:145], v[198:201], v[86:89]
	v_mfma_f32_16x16x32_bf16 v[78:81], v[150:153], v[198:201], v[78:81]
	s_setprio 0
	s_setprio 1
	v_mfma_f32_16x16x32_bf16 v[114:117], v[154:157], v[170:173], v[114:117]
	v_mfma_f32_16x16x32_bf16 v[106:109], v[162:165], v[170:173], v[106:109]
	v_mfma_f32_16x16x32_bf16 v[98:101], v[154:157], v[178:181], v[98:101]
	v_mfma_f32_16x16x32_bf16 v[90:93], v[162:165], v[178:181], v[90:93]
	v_mfma_f32_16x16x32_bf16 v[82:85], v[154:157], v[186:189], v[82:85]
	v_mfma_f32_16x16x32_bf16 v[74:77], v[162:165], v[186:189], v[74:77]
	v_mfma_f32_16x16x32_bf16 v[70:73], v[154:157], v[194:197], v[70:73]
	v_mfma_f32_16x16x32_bf16 v[62:65], v[162:165], v[194:197], v[62:65]
	v_mfma_f32_16x16x32_bf16 v[114:117], v[158:161], v[174:177], v[114:117]
	v_mfma_f32_16x16x32_bf16 v[106:109], v[166:169], v[174:177], v[106:109]
	v_mfma_f32_16x16x32_bf16 v[98:101], v[158:161], v[182:185], v[98:101]
	v_mfma_f32_16x16x32_bf16 v[90:93], v[166:169], v[182:185], v[90:93]
	v_mfma_f32_16x16x32_bf16 v[82:85], v[158:161], v[190:193], v[82:85]
	v_mfma_f32_16x16x32_bf16 v[74:77], v[166:169], v[190:193], v[74:77]
	v_mfma_f32_16x16x32_bf16 v[70:73], v[158:161], v[198:201], v[70:73]
	v_mfma_f32_16x16x32_bf16 v[62:65], v[166:169], v[198:201], v[62:65]
	s_setprio 0
	s_barrier
	s_mov_b32 m0, s71
	ds_read_b128 v[170:173], v137 offset:16384
	ds_read_b128 v[174:177], v137 offset:17408
	ds_read_b128 v[178:181], v137 offset:18432
	ds_read_b128 v[182:185], v137 offset:19456
	ds_read_b128 v[186:189], v137 offset:20480
	ds_read_b128 v[190:193], v137 offset:21504
	ds_read_b128 v[194:197], v137 offset:22528
	ds_read_b128 v[198:201], v137 offset:23552
	s_nop 0
	global_load_lds_dwordx4 v131, s[12:13]
	s_mov_b32 m0, s67
	s_nop 0
	global_load_lds_dwordx4 v133, s[12:13]
	s_mov_b32 m0, s68
	s_nop 0
	global_load_lds_dwordx4 v131, s[22:23]
	s_mov_b32 m0, s66
	s_nop 0
	global_load_lds_dwordx4 v133, s[22:23]
	s_mov_b32 m0, s42
	s_nop 0
	global_load_lds_dwordx4 v130, s[10:11]
	s_mov_b32 m0, s43
	s_nop 0
	global_load_lds_dwordx4 v132, s[10:11]
	s_waitcnt vmcnt(8) lgkmcnt(0)
	s_setprio 1
	s_barrier
	v_mfma_f32_16x16x32_bf16 v[66:69], v[138:141], v[170:173], v[66:69]
	v_mfma_f32_16x16x32_bf16 v[58:61], v[146:149], v[170:173], v[58:61]
	v_mfma_f32_16x16x32_bf16 v[54:57], v[138:141], v[178:181], v[54:57]
	v_mfma_f32_16x16x32_bf16 v[46:49], v[146:149], v[178:181], v[46:49]
	v_mfma_f32_16x16x32_bf16 v[38:41], v[138:141], v[186:189], v[38:41]
	v_mfma_f32_16x16x32_bf16 v[30:33], v[146:149], v[186:189], v[30:33]
	v_mfma_f32_16x16x32_bf16 v[22:25], v[138:141], v[194:197], v[22:25]
	v_mfma_f32_16x16x32_bf16 v[14:17], v[146:149], v[194:197], v[14:17]
	v_mfma_f32_16x16x32_bf16 v[66:69], v[142:145], v[174:177], v[66:69]
	v_mfma_f32_16x16x32_bf16 v[58:61], v[150:153], v[174:177], v[58:61]
	v_mfma_f32_16x16x32_bf16 v[54:57], v[142:145], v[182:185], v[54:57]
	v_mfma_f32_16x16x32_bf16 v[46:49], v[150:153], v[182:185], v[46:49]
	v_mfma_f32_16x16x32_bf16 v[38:41], v[142:145], v[190:193], v[38:41]
	v_mfma_f32_16x16x32_bf16 v[30:33], v[150:153], v[190:193], v[30:33]
	v_mfma_f32_16x16x32_bf16 v[22:25], v[142:145], v[198:201], v[22:25]
	v_mfma_f32_16x16x32_bf16 v[14:17], v[150:153], v[198:201], v[14:17]
	s_setprio 0
	s_setprio 1
	v_mfma_f32_16x16x32_bf16 v[50:53], v[154:157], v[170:173], v[50:53]
	v_mfma_f32_16x16x32_bf16 v[42:45], v[162:165], v[170:173], v[42:45]
	v_mfma_f32_16x16x32_bf16 v[34:37], v[154:157], v[178:181], v[34:37]
	v_mfma_f32_16x16x32_bf16 v[26:29], v[162:165], v[178:181], v[26:29]
	v_mfma_f32_16x16x32_bf16 v[18:21], v[154:157], v[186:189], v[18:21]
	v_mfma_f32_16x16x32_bf16 v[10:13], v[162:165], v[186:189], v[10:13]
	v_mfma_f32_16x16x32_bf16 v[6:9], v[154:157], v[194:197], v[6:9]
	v_mfma_f32_16x16x32_bf16 v[2:5], v[162:165], v[194:197], v[2:5]
	v_mfma_f32_16x16x32_bf16 v[50:53], v[158:161], v[174:177], v[50:53]
	v_mfma_f32_16x16x32_bf16 v[42:45], v[166:169], v[174:177], v[42:45]
	v_mfma_f32_16x16x32_bf16 v[34:37], v[158:161], v[182:185], v[34:37]
	v_mfma_f32_16x16x32_bf16 v[26:29], v[166:169], v[182:185], v[26:29]
	v_mfma_f32_16x16x32_bf16 v[18:21], v[158:161], v[190:193], v[18:21]
	v_mfma_f32_16x16x32_bf16 v[10:13], v[166:169], v[190:193], v[10:13]
	v_mfma_f32_16x16x32_bf16 v[6:9], v[158:161], v[198:201], v[6:9]
	v_mfma_f32_16x16x32_bf16 v[2:5], v[166:169], v[198:201], v[2:5]
	s_setprio 0
	s_barrier
	ds_read_b128 v[138:141], v0 offset:32768
	ds_read_b128 v[142:145], v0 offset:33792
	ds_read_b128 v[146:149], v0 offset:34816
	ds_read_b128 v[150:153], v0 offset:35840
	ds_read_b128 v[154:157], v0 offset:49152
	ds_read_b128 v[158:161], v0 offset:50176
	ds_read_b128 v[162:165], v0 offset:51200
	ds_read_b128 v[166:169], v0 offset:52224
	s_mov_b32 m0, s50
	ds_read_b128 v[170:173], v137 offset:32768
	ds_read_b128 v[174:177], v137 offset:33792
	ds_read_b128 v[178:181], v137 offset:34816
	ds_read_b128 v[182:185], v137 offset:35840
	ds_read_b128 v[186:189], v137 offset:36864
	ds_read_b128 v[190:193], v137 offset:37888
	ds_read_b128 v[194:197], v137 offset:38912
	ds_read_b128 v[198:201], v137 offset:39936
	s_nop 0
	global_load_lds_dwordx4 v130, s[16:17]
	s_mov_b32 m0, s51
	s_nop 0
	global_load_lds_dwordx4 v132, s[16:17]
	s_waitcnt vmcnt(8) lgkmcnt(0)
	s_setprio 1
	s_barrier
	v_mfma_f32_16x16x32_bf16 v[126:129], v[138:141], v[170:173], v[126:129]
	v_mfma_f32_16x16x32_bf16 v[122:125], v[146:149], v[170:173], v[122:125]
	v_mfma_f32_16x16x32_bf16 v[118:121], v[138:141], v[178:181], v[118:121]
	v_mfma_f32_16x16x32_bf16 v[110:113], v[146:149], v[178:181], v[110:113]
	v_mfma_f32_16x16x32_bf16 v[102:105], v[138:141], v[186:189], v[102:105]
	v_mfma_f32_16x16x32_bf16 v[94:97], v[146:149], v[186:189], v[94:97]
	v_mfma_f32_16x16x32_bf16 v[86:89], v[138:141], v[194:197], v[86:89]
	v_mfma_f32_16x16x32_bf16 v[78:81], v[146:149], v[194:197], v[78:81]
	v_mfma_f32_16x16x32_bf16 v[126:129], v[142:145], v[174:177], v[126:129]
	v_mfma_f32_16x16x32_bf16 v[122:125], v[150:153], v[174:177], v[122:125]
	v_mfma_f32_16x16x32_bf16 v[118:121], v[142:145], v[182:185], v[118:121]
	v_mfma_f32_16x16x32_bf16 v[110:113], v[150:153], v[182:185], v[110:113]
	v_mfma_f32_16x16x32_bf16 v[102:105], v[142:145], v[190:193], v[102:105]
	v_mfma_f32_16x16x32_bf16 v[94:97], v[150:153], v[190:193], v[94:97]
	v_mfma_f32_16x16x32_bf16 v[86:89], v[142:145], v[198:201], v[86:89]
	v_mfma_f32_16x16x32_bf16 v[78:81], v[150:153], v[198:201], v[78:81]
	s_setprio 0
	s_setprio 1
	v_mfma_f32_16x16x32_bf16 v[114:117], v[154:157], v[170:173], v[114:117]
	v_mfma_f32_16x16x32_bf16 v[106:109], v[162:165], v[170:173], v[106:109]
	v_mfma_f32_16x16x32_bf16 v[98:101], v[154:157], v[178:181], v[98:101]
	v_mfma_f32_16x16x32_bf16 v[90:93], v[162:165], v[178:181], v[90:93]
	v_mfma_f32_16x16x32_bf16 v[82:85], v[154:157], v[186:189], v[82:85]
	v_mfma_f32_16x16x32_bf16 v[74:77], v[162:165], v[186:189], v[74:77]
	v_mfma_f32_16x16x32_bf16 v[70:73], v[154:157], v[194:197], v[70:73]
	v_mfma_f32_16x16x32_bf16 v[62:65], v[162:165], v[194:197], v[62:65]
	v_mfma_f32_16x16x32_bf16 v[114:117], v[158:161], v[174:177], v[114:117]
	v_mfma_f32_16x16x32_bf16 v[106:109], v[166:169], v[174:177], v[106:109]
	v_mfma_f32_16x16x32_bf16 v[98:101], v[158:161], v[182:185], v[98:101]
	v_mfma_f32_16x16x32_bf16 v[90:93], v[166:169], v[182:185], v[90:93]
	v_mfma_f32_16x16x32_bf16 v[82:85], v[158:161], v[190:193], v[82:85]
	v_mfma_f32_16x16x32_bf16 v[74:77], v[166:169], v[190:193], v[74:77]
	v_mfma_f32_16x16x32_bf16 v[70:73], v[158:161], v[198:201], v[70:73]
	v_mfma_f32_16x16x32_bf16 v[62:65], v[166:169], v[198:201], v[62:65]
	s_setprio 0
	s_barrier
	ds_read_b128 v[170:173], v137 offset:49152
	ds_read_b128 v[174:177], v137 offset:50176
	ds_read_b128 v[178:181], v137 offset:51200
	ds_read_b128 v[182:185], v137 offset:52224
	ds_read_b128 v[186:189], v137 offset:53248
	ds_read_b128 v[190:193], v137 offset:54272
	ds_read_b128 v[194:197], v137 offset:55296
	ds_read_b128 v[198:201], v137 offset:56320
	s_mov_b32 m0, s61
	s_add_u32 s100, s12, s38
	s_addc_u32 s101, s13, s39
	global_load_lds_dwordx4 v131, s[100:101]
	s_mov_b32 m0, s60
	s_nop 0
	global_load_lds_dwordx4 v133, s[100:101]
	s_mov_b32 m0, s70
	s_nop 0
	global_load_lds_dwordx4 v131, s[14:15]
	s_mov_b32 m0, s69
	s_nop 0
	global_load_lds_dwordx4 v133, s[14:15]
	s_mov_b32 m0, s58
	s_add_u32 s100, s10, s38
	s_addc_u32 s101, s11, s39
	v_mov_b32_e32 v0, v132
	global_load_lds_dwordx4 v130, s[100:101]
	s_mov_b32 m0, s59
	s_nop 0
	global_load_lds_dwordx4 v132, s[100:101]
	s_waitcnt vmcnt(8) lgkmcnt(0)
	s_setprio 1
	s_barrier
	v_mfma_f32_16x16x32_bf16 v[66:69], v[138:141], v[170:173], v[66:69]
	v_mfma_f32_16x16x32_bf16 v[58:61], v[146:149], v[170:173], v[58:61]
	v_mfma_f32_16x16x32_bf16 v[54:57], v[138:141], v[178:181], v[54:57]
	v_mfma_f32_16x16x32_bf16 v[46:49], v[146:149], v[178:181], v[46:49]
	v_mfma_f32_16x16x32_bf16 v[38:41], v[138:141], v[186:189], v[38:41]
	v_mfma_f32_16x16x32_bf16 v[30:33], v[146:149], v[186:189], v[30:33]
	v_mfma_f32_16x16x32_bf16 v[22:25], v[138:141], v[194:197], v[22:25]
	v_mfma_f32_16x16x32_bf16 v[14:17], v[146:149], v[194:197], v[14:17]
	v_mfma_f32_16x16x32_bf16 v[66:69], v[142:145], v[174:177], v[66:69]
	v_mfma_f32_16x16x32_bf16 v[58:61], v[150:153], v[174:177], v[58:61]
	v_mfma_f32_16x16x32_bf16 v[54:57], v[142:145], v[182:185], v[54:57]
	v_mfma_f32_16x16x32_bf16 v[46:49], v[150:153], v[182:185], v[46:49]
	v_mfma_f32_16x16x32_bf16 v[38:41], v[142:145], v[190:193], v[38:41]
	v_mfma_f32_16x16x32_bf16 v[30:33], v[150:153], v[190:193], v[30:33]
	v_mfma_f32_16x16x32_bf16 v[22:25], v[142:145], v[198:201], v[22:25]
	v_mfma_f32_16x16x32_bf16 v[14:17], v[150:153], v[198:201], v[14:17]
	s_setprio 0
	s_setprio 1
	v_mfma_f32_16x16x32_bf16 v[50:53], v[154:157], v[170:173], v[50:53]
	v_mfma_f32_16x16x32_bf16 v[42:45], v[162:165], v[170:173], v[42:45]
	v_mfma_f32_16x16x32_bf16 v[34:37], v[154:157], v[178:181], v[34:37]
	v_mfma_f32_16x16x32_bf16 v[26:29], v[162:165], v[178:181], v[26:29]
	v_mfma_f32_16x16x32_bf16 v[18:21], v[154:157], v[186:189], v[18:21]
	v_mfma_f32_16x16x32_bf16 v[10:13], v[162:165], v[186:189], v[10:13]
	v_mfma_f32_16x16x32_bf16 v[6:9], v[154:157], v[194:197], v[6:9]
	v_mfma_f32_16x16x32_bf16 v[2:5], v[162:165], v[194:197], v[2:5]
	v_mfma_f32_16x16x32_bf16 v[50:53], v[158:161], v[174:177], v[50:53]
	v_mfma_f32_16x16x32_bf16 v[42:45], v[166:169], v[174:177], v[42:45]
	v_mfma_f32_16x16x32_bf16 v[34:37], v[158:161], v[182:185], v[34:37]
	v_mfma_f32_16x16x32_bf16 v[26:29], v[166:169], v[182:185], v[26:29]
	v_mfma_f32_16x16x32_bf16 v[18:21], v[158:161], v[190:193], v[18:21]
	v_mfma_f32_16x16x32_bf16 v[10:13], v[166:169], v[190:193], v[10:13]
	v_mfma_f32_16x16x32_bf16 v[6:9], v[158:161], v[198:201], v[6:9]
	v_mfma_f32_16x16x32_bf16 v[2:5], v[166:169], v[198:201], v[2:5]
	s_setprio 0
	s_barrier
	s_andn2_b64 vcc, exec, s[8:9]
	s_mov_b64 s[12:13], -1
	s_mov_b64 s[8:9], 0
	s_mov_b64 s[14:15], 0x100
	s_cbranch_vccz .LBB0_1473
	s_cmpk_lt_u32 s24, 0x100
	s_cbranch_scc0 .LBB0_1476
	s_barrier

.LBB0_1481:
	s_add_u32 s16, s4, s14
	s_addc_u32 s17, s5, s15
	s_add_u32 s22, s16, 0x100
	s_addc_u32 s23, s17, 0
	s_and_b64 s[10:11], s[12:13], exec
	s_cselect_b32 s11, s5, s23
	s_cselect_b32 s10, s4, s22
	s_add_u32 s14, s6, s14
	s_addc_u32 s15, s7, s15
	s_add_u32 s14, s14, 0x900
	s_addc_u32 s15, s15, 0
	s_add_i32 s70, 0, 0x10000
	s_and_b64 s[12:13], s[12:13], exec
	s_cselect_b32 s13, s58, s15
	s_cselect_b32 s12, s51, s14
	s_add_i32 s15, 0, 0x14000
	s_add_u32 s46, s16, 0x40080
	s_addc_u32 s47, s17, 0
	s_add_i32 s74, s70, s40
	s_add_i32 m0, s41, 0xc000
	s_add_i32 s75, s41, 0xe000
	s_add_i32 s68, s74, 0x2000
	v_add_u32_e32 v0, s70, v136
	s_add_u32 s22, s12, 0x80000
	ds_read_b128 v[138:141], v0
	ds_read_b128 v[142:145], v0 offset:1024
	ds_read_b128 v[146:149], v0 offset:2048
	ds_read_b128 v[150:153], v0 offset:3072
	s_addc_u32 s23, s13, 0
	s_add_i32 s69, s15, s40
	ds_read_b128 v[154:157], v0 offset:16384
	ds_read_b128 v[158:161], v0 offset:17408
	ds_read_b128 v[162:165], v0 offset:18432
	ds_read_b128 v[166:169], v0 offset:19456
	s_add_i32 s67, s69, 0x2000
	s_add_i32 s66, 0, 0x18000
	s_add_i32 s65, 0, 0x1c000
	s_add_u32 s16, s10, 0x40000
	s_addc_u32 s17, s11, 0
	s_add_i32 s64, s66, s40
	s_add_i32 s61, s64, 0x2000
	s_add_u32 s14, s12, 0x80080
	s_addc_u32 s15, s13, 0
	s_add_i32 s71, s65, s40
	s_add_i32 s70, s71, 0x2000
	ds_read_b128 v[170:173], v137
	ds_read_b128 v[174:177], v137 offset:1024
	ds_read_b128 v[178:181], v137 offset:2048
	ds_read_b128 v[182:185], v137 offset:3072
	ds_read_b128 v[186:189], v137 offset:4096
	ds_read_b128 v[190:193], v137 offset:5120
	ds_read_b128 v[194:197], v137 offset:6144
	ds_read_b128 v[198:201], v137 offset:7168
	s_nop 0
	global_load_lds_dwordx4 v130, s[46:47]
	s_mov_b32 m0, s75
	s_nop 0
	global_load_lds_dwordx4 v132, s[46:47]
	s_waitcnt vmcnt(8) lgkmcnt(0)
	s_setprio 1
	s_barrier
	v_mfma_f32_16x16x32_bf16 v[126:129], v[138:141], v[170:173], v[126:129]
	v_mfma_f32_16x16x32_bf16 v[122:125], v[146:149], v[170:173], v[122:125]
	v_mfma_f32_16x16x32_bf16 v[118:121], v[138:141], v[178:181], v[118:121]
	v_mfma_f32_16x16x32_bf16 v[110:113], v[146:149], v[178:181], v[110:113]
	v_mfma_f32_16x16x32_bf16 v[102:105], v[138:141], v[186:189], v[102:105]
	v_mfma_f32_16x16x32_bf16 v[94:97], v[146:149], v[186:189], v[94:97]
	v_mfma_f32_16x16x32_bf16 v[86:89], v[138:141], v[194:197], v[86:89]
	v_mfma_f32_16x16x32_bf16 v[78:81], v[146:149], v[194:197], v[78:81]
	v_mfma_f32_16x16x32_bf16 v[126:129], v[142:145], v[174:177], v[126:129]
	v_mfma_f32_16x16x32_bf16 v[122:125], v[150:153], v[174:177], v[122:125]
	v_mfma_f32_16x16x32_bf16 v[118:121], v[142:145], v[182:185], v[118:121]
	v_mfma_f32_16x16x32_bf16 v[110:113], v[150:153], v[182:185], v[110:113]
	v_mfma_f32_16x16x32_bf16 v[102:105], v[142:145], v[190:193], v[102:105]
	v_mfma_f32_16x16x32_bf16 v[94:97], v[150:153], v[190:193], v[94:97]
	v_mfma_f32_16x16x32_bf16 v[86:89], v[142:145], v[198:201], v[86:89]
	v_mfma_f32_16x16x32_bf16 v[78:81], v[150:153], v[198:201], v[78:81]
	s_setprio 0
	s_setprio 1
	v_mfma_f32_16x16x32_bf16 v[114:117], v[154:157], v[170:173], v[114:117]
	v_mfma_f32_16x16x32_bf16 v[106:109], v[162:165], v[170:173], v[106:109]
	v_mfma_f32_16x16x32_bf16 v[98:101], v[154:157], v[178:181], v[98:101]
	v_mfma_f32_16x16x32_bf16 v[90:93], v[162:165], v[178:181], v[90:93]
	v_mfma_f32_16x16x32_bf16 v[82:85], v[154:157], v[186:189], v[82:85]
	v_mfma_f32_16x16x32_bf16 v[74:77], v[162:165], v[186:189], v[74:77]
	v_mfma_f32_16x16x32_bf16 v[70:73], v[154:157], v[194:197], v[70:73]
	v_mfma_f32_16x16x32_bf16 v[62:65], v[162:165], v[194:197], v[62:65]
	v_mfma_f32_16x16x32_bf16 v[114:117], v[158:161], v[174:177], v[114:117]
	v_mfma_f32_16x16x32_bf16 v[106:109], v[166:169], v[174:177], v[106:109]
	v_mfma_f32_16x16x32_bf16 v[98:101], v[158:161], v[182:185], v[98:101]
	v_mfma_f32_16x16x32_bf16 v[90:93], v[166:169], v[182:185], v[90:93]
	v_mfma_f32_16x16x32_bf16 v[82:85], v[158:161], v[190:193], v[82:85]
	v_mfma_f32_16x16x32_bf16 v[74:77], v[166:169], v[190:193], v[74:77]
	v_mfma_f32_16x16x32_bf16 v[70:73], v[158:161], v[198:201], v[70:73]
	v_mfma_f32_16x16x32_bf16 v[62:65], v[166:169], v[198:201], v[62:65]
	s_setprio 0
	s_barrier
	s_mov_b32 m0, s74
	ds_read_b128 v[170:173], v137 offset:16384
	ds_read_b128 v[174:177], v137 offset:17408
	ds_read_b128 v[178:181], v137 offset:18432
	ds_read_b128 v[182:185], v137 offset:19456
	ds_read_b128 v[186:189], v137 offset:20480
	ds_read_b128 v[190:193], v137 offset:21504
	ds_read_b128 v[194:197], v137 offset:22528
	ds_read_b128 v[198:201], v137 offset:23552
	s_nop 0
	global_load_lds_dwordx4 v131, s[12:13]
	s_mov_b32 m0, s68
	s_nop 0
	global_load_lds_dwordx4 v133, s[12:13]
	s_mov_b32 m0, s69
	s_nop 0
	global_load_lds_dwordx4 v131, s[22:23]
	s_mov_b32 m0, s67
	s_nop 0
	global_load_lds_dwordx4 v133, s[22:23]
	s_mov_b32 m0, s41
	s_nop 0
	global_load_lds_dwordx4 v130, s[10:11]
	s_mov_b32 m0, s42
	s_nop 0
	global_load_lds_dwordx4 v132, s[10:11]
	s_waitcnt vmcnt(8) lgkmcnt(0)
	s_setprio 1
	s_barrier
	v_mfma_f32_16x16x32_bf16 v[66:69], v[138:141], v[170:173], v[66:69]
	v_mfma_f32_16x16x32_bf16 v[58:61], v[146:149], v[170:173], v[58:61]
	v_mfma_f32_16x16x32_bf16 v[54:57], v[138:141], v[178:181], v[54:57]
	v_mfma_f32_16x16x32_bf16 v[46:49], v[146:149], v[178:181], v[46:49]
	v_mfma_f32_16x16x32_bf16 v[38:41], v[138:141], v[186:189], v[38:41]
	v_mfma_f32_16x16x32_bf16 v[30:33], v[146:149], v[186:189], v[30:33]
	v_mfma_f32_16x16x32_bf16 v[22:25], v[138:141], v[194:197], v[22:25]
	v_mfma_f32_16x16x32_bf16 v[14:17], v[146:149], v[194:197], v[14:17]
	v_mfma_f32_16x16x32_bf16 v[66:69], v[142:145], v[174:177], v[66:69]
	v_mfma_f32_16x16x32_bf16 v[58:61], v[150:153], v[174:177], v[58:61]
	v_mfma_f32_16x16x32_bf16 v[54:57], v[142:145], v[182:185], v[54:57]
	v_mfma_f32_16x16x32_bf16 v[46:49], v[150:153], v[182:185], v[46:49]
	v_mfma_f32_16x16x32_bf16 v[38:41], v[142:145], v[190:193], v[38:41]
	v_mfma_f32_16x16x32_bf16 v[30:33], v[150:153], v[190:193], v[30:33]
	v_mfma_f32_16x16x32_bf16 v[22:25], v[142:145], v[198:201], v[22:25]
	v_mfma_f32_16x16x32_bf16 v[14:17], v[150:153], v[198:201], v[14:17]
	s_setprio 0
	s_setprio 1
	v_mfma_f32_16x16x32_bf16 v[50:53], v[154:157], v[170:173], v[50:53]
	v_mfma_f32_16x16x32_bf16 v[42:45], v[162:165], v[170:173], v[42:45]
	v_mfma_f32_16x16x32_bf16 v[34:37], v[154:157], v[178:181], v[34:37]
	v_mfma_f32_16x16x32_bf16 v[26:29], v[162:165], v[178:181], v[26:29]
	v_mfma_f32_16x16x32_bf16 v[18:21], v[154:157], v[186:189], v[18:21]
	v_mfma_f32_16x16x32_bf16 v[10:13], v[162:165], v[186:189], v[10:13]
	v_mfma_f32_16x16x32_bf16 v[6:9], v[154:157], v[194:197], v[6:9]
	v_mfma_f32_16x16x32_bf16 v[2:5], v[162:165], v[194:197], v[2:5]
	v_mfma_f32_16x16x32_bf16 v[50:53], v[158:161], v[174:177], v[50:53]
	v_mfma_f32_16x16x32_bf16 v[42:45], v[166:169], v[174:177], v[42:45]
	v_mfma_f32_16x16x32_bf16 v[34:37], v[158:161], v[182:185], v[34:37]
	v_mfma_f32_16x16x32_bf16 v[26:29], v[166:169], v[182:185], v[26:29]
	v_mfma_f32_16x16x32_bf16 v[18:21], v[158:161], v[190:193], v[18:21]
	v_mfma_f32_16x16x32_bf16 v[10:13], v[166:169], v[190:193], v[10:13]
	v_mfma_f32_16x16x32_bf16 v[6:9], v[158:161], v[198:201], v[6:9]
	v_mfma_f32_16x16x32_bf16 v[2:5], v[166:169], v[198:201], v[2:5]
	s_setprio 0
	s_barrier
	ds_read_b128 v[138:141], v0 offset:32768
	ds_read_b128 v[142:145], v0 offset:33792
	ds_read_b128 v[146:149], v0 offset:34816
	ds_read_b128 v[150:153], v0 offset:35840
	ds_read_b128 v[154:157], v0 offset:49152
	ds_read_b128 v[158:161], v0 offset:50176
	ds_read_b128 v[162:165], v0 offset:51200
	ds_read_b128 v[166:169], v0 offset:52224
	s_mov_b32 m0, s43
	ds_read_b128 v[170:173], v137 offset:32768
	ds_read_b128 v[174:177], v137 offset:33792
	ds_read_b128 v[178:181], v137 offset:34816
	ds_read_b128 v[182:185], v137 offset:35840
	ds_read_b128 v[186:189], v137 offset:36864
	ds_read_b128 v[190:193], v137 offset:37888
	ds_read_b128 v[194:197], v137 offset:38912
	ds_read_b128 v[198:201], v137 offset:39936
	s_nop 0
	global_load_lds_dwordx4 v130, s[16:17]
	s_mov_b32 m0, s50
	s_nop 0
	global_load_lds_dwordx4 v132, s[16:17]
	s_waitcnt vmcnt(8) lgkmcnt(0)
	s_setprio 1
	s_barrier
	v_mfma_f32_16x16x32_bf16 v[126:129], v[138:141], v[170:173], v[126:129]
	v_mfma_f32_16x16x32_bf16 v[122:125], v[146:149], v[170:173], v[122:125]
	v_mfma_f32_16x16x32_bf16 v[118:121], v[138:141], v[178:181], v[118:121]
	v_mfma_f32_16x16x32_bf16 v[110:113], v[146:149], v[178:181], v[110:113]
	v_mfma_f32_16x16x32_bf16 v[102:105], v[138:141], v[186:189], v[102:105]
	v_mfma_f32_16x16x32_bf16 v[94:97], v[146:149], v[186:189], v[94:97]
	v_mfma_f32_16x16x32_bf16 v[86:89], v[138:141], v[194:197], v[86:89]
	v_mfma_f32_16x16x32_bf16 v[78:81], v[146:149], v[194:197], v[78:81]
	v_mfma_f32_16x16x32_bf16 v[126:129], v[142:145], v[174:177], v[126:129]
	v_mfma_f32_16x16x32_bf16 v[122:125], v[150:153], v[174:177], v[122:125]
	v_mfma_f32_16x16x32_bf16 v[118:121], v[142:145], v[182:185], v[118:121]
	v_mfma_f32_16x16x32_bf16 v[110:113], v[150:153], v[182:185], v[110:113]
	v_mfma_f32_16x16x32_bf16 v[102:105], v[142:145], v[190:193], v[102:105]
	v_mfma_f32_16x16x32_bf16 v[94:97], v[150:153], v[190:193], v[94:97]
	v_mfma_f32_16x16x32_bf16 v[86:89], v[142:145], v[198:201], v[86:89]
	v_mfma_f32_16x16x32_bf16 v[78:81], v[150:153], v[198:201], v[78:81]
	s_setprio 0
	s_setprio 1
	v_mfma_f32_16x16x32_bf16 v[114:117], v[154:157], v[170:173], v[114:117]
	v_mfma_f32_16x16x32_bf16 v[106:109], v[162:165], v[170:173], v[106:109]
	v_mfma_f32_16x16x32_bf16 v[98:101], v[154:157], v[178:181], v[98:101]
	v_mfma_f32_16x16x32_bf16 v[90:93], v[162:165], v[178:181], v[90:93]
	v_mfma_f32_16x16x32_bf16 v[82:85], v[154:157], v[186:189], v[82:85]
	v_mfma_f32_16x16x32_bf16 v[74:77], v[162:165], v[186:189], v[74:77]
	v_mfma_f32_16x16x32_bf16 v[70:73], v[154:157], v[194:197], v[70:73]
	v_mfma_f32_16x16x32_bf16 v[62:65], v[162:165], v[194:197], v[62:65]
	v_mfma_f32_16x16x32_bf16 v[114:117], v[158:161], v[174:177], v[114:117]
	v_mfma_f32_16x16x32_bf16 v[106:109], v[166:169], v[174:177], v[106:109]
	v_mfma_f32_16x16x32_bf16 v[98:101], v[158:161], v[182:185], v[98:101]
	v_mfma_f32_16x16x32_bf16 v[90:93], v[166:169], v[182:185], v[90:93]
	v_mfma_f32_16x16x32_bf16 v[82:85], v[158:161], v[190:193], v[82:85]
	v_mfma_f32_16x16x32_bf16 v[74:77], v[166:169], v[190:193], v[74:77]
	v_mfma_f32_16x16x32_bf16 v[70:73], v[158:161], v[198:201], v[70:73]
	v_mfma_f32_16x16x32_bf16 v[62:65], v[166:169], v[198:201], v[62:65]
	s_setprio 0
	s_barrier
	ds_read_b128 v[170:173], v137 offset:49152
	ds_read_b128 v[174:177], v137 offset:50176
	ds_read_b128 v[178:181], v137 offset:51200
	ds_read_b128 v[182:185], v137 offset:52224
	ds_read_b128 v[186:189], v137 offset:53248
	ds_read_b128 v[190:193], v137 offset:54272
	ds_read_b128 v[194:197], v137 offset:55296
	ds_read_b128 v[198:201], v137 offset:56320
	s_mov_b32 m0, s64
	s_add_u32 s100, s12, s38
	s_addc_u32 s101, s13, s39
	global_load_lds_dwordx4 v131, s[100:101]
	s_mov_b32 m0, s61
	s_nop 0
	global_load_lds_dwordx4 v133, s[100:101]
	s_mov_b32 m0, s71
	s_nop 0
	global_load_lds_dwordx4 v131, s[14:15]
	s_mov_b32 m0, s70
	s_nop 0
	global_load_lds_dwordx4 v133, s[14:15]
	s_mov_b32 m0, s59
	s_add_u32 s100, s10, s38
	s_addc_u32 s101, s11, s39
	v_mov_b32_e32 v0, v132
	global_load_lds_dwordx4 v130, s[100:101]
	s_mov_b32 m0, s60
	s_nop 0
	global_load_lds_dwordx4 v132, s[100:101]
	s_waitcnt vmcnt(8) lgkmcnt(0)
	s_setprio 1
	s_barrier
	v_mfma_f32_16x16x32_bf16 v[66:69], v[138:141], v[170:173], v[66:69]
	v_mfma_f32_16x16x32_bf16 v[58:61], v[146:149], v[170:173], v[58:61]
	v_mfma_f32_16x16x32_bf16 v[54:57], v[138:141], v[178:181], v[54:57]
	v_mfma_f32_16x16x32_bf16 v[46:49], v[146:149], v[178:181], v[46:49]
	v_mfma_f32_16x16x32_bf16 v[38:41], v[138:141], v[186:189], v[38:41]
	v_mfma_f32_16x16x32_bf16 v[30:33], v[146:149], v[186:189], v[30:33]
	v_mfma_f32_16x16x32_bf16 v[22:25], v[138:141], v[194:197], v[22:25]
	v_mfma_f32_16x16x32_bf16 v[14:17], v[146:149], v[194:197], v[14:17]
	v_mfma_f32_16x16x32_bf16 v[66:69], v[142:145], v[174:177], v[66:69]
	v_mfma_f32_16x16x32_bf16 v[58:61], v[150:153], v[174:177], v[58:61]
	v_mfma_f32_16x16x32_bf16 v[54:57], v[142:145], v[182:185], v[54:57]
	v_mfma_f32_16x16x32_bf16 v[46:49], v[150:153], v[182:185], v[46:49]
	v_mfma_f32_16x16x32_bf16 v[38:41], v[142:145], v[190:193], v[38:41]
	v_mfma_f32_16x16x32_bf16 v[30:33], v[150:153], v[190:193], v[30:33]
	v_mfma_f32_16x16x32_bf16 v[22:25], v[142:145], v[198:201], v[22:25]
	v_mfma_f32_16x16x32_bf16 v[14:17], v[150:153], v[198:201], v[14:17]
	s_setprio 0
	s_setprio 1
	v_mfma_f32_16x16x32_bf16 v[50:53], v[154:157], v[170:173], v[50:53]
	v_mfma_f32_16x16x32_bf16 v[42:45], v[162:165], v[170:173], v[42:45]
	v_mfma_f32_16x16x32_bf16 v[34:37], v[154:157], v[178:181], v[34:37]
	v_mfma_f32_16x16x32_bf16 v[26:29], v[162:165], v[178:181], v[26:29]
	v_mfma_f32_16x16x32_bf16 v[18:21], v[154:157], v[186:189], v[18:21]
	v_mfma_f32_16x16x32_bf16 v[10:13], v[162:165], v[186:189], v[10:13]
	v_mfma_f32_16x16x32_bf16 v[6:9], v[154:157], v[194:197], v[6:9]
	v_mfma_f32_16x16x32_bf16 v[2:5], v[162:165], v[194:197], v[2:5]
	v_mfma_f32_16x16x32_bf16 v[50:53], v[158:161], v[174:177], v[50:53]
	v_mfma_f32_16x16x32_bf16 v[42:45], v[166:169], v[174:177], v[42:45]
	v_mfma_f32_16x16x32_bf16 v[34:37], v[158:161], v[182:185], v[34:37]
	v_mfma_f32_16x16x32_bf16 v[26:29], v[166:169], v[182:185], v[26:29]
	v_mfma_f32_16x16x32_bf16 v[18:21], v[158:161], v[190:193], v[18:21]
	v_mfma_f32_16x16x32_bf16 v[10:13], v[166:169], v[190:193], v[10:13]
	v_mfma_f32_16x16x32_bf16 v[6:9], v[158:161], v[198:201], v[6:9]
	v_mfma_f32_16x16x32_bf16 v[2:5], v[166:169], v[198:201], v[2:5]
	s_setprio 0
	s_barrier
	s_andn2_b64 vcc, exec, s[8:9]
	s_mov_b64 s[12:13], -1
	s_mov_b64 s[8:9], 0
	s_mov_b64 s[14:15], 0x100
	s_cbranch_vccz .LBB0_1481
	s_cmpk_lt_u32 s24, 0x100
	s_cbranch_scc0 .LBB0_1484
	s_barrier

.LBB0_1570:
	s_add_u32 s48, s41, s6
	s_addc_u32 s49, s42, s7
	s_add_u32 s8, s48, 0x9800100
	s_addc_u32 s9, s49, 0
	s_add_u32 s10, s43, s6
	s_addc_u32 s11, s46, s7
	s_cmpk_eq_i32 s6, 0x700
	s_cselect_b32 s9, s3, s9
	s_cselect_b32 s8, s2, s8
	s_cselect_b32 s11, s26, s11
	s_cselect_b32 s10, s25, s10
	s_add_i32 s50, 0, 0x10000
	v_add_u32_e32 v0, s50, v169
	s_add_i32 s51, 0, 0x14000
	ds_read_b128 v[172:175], v0
	ds_read_b128 v[176:179], v0 offset:1024
	ds_read_b128 v[180:183], v0 offset:2048
	ds_read_b128 v[184:187], v0 offset:3072
	ds_read_b128 v[188:191], v0 offset:16384
	ds_read_b128 v[192:195], v0 offset:17408
	ds_read_b128 v[196:199], v0 offset:18432
	ds_read_b128 v[200:203], v0 offset:19456
	ds_read_b128 v[204:207], v170
	ds_read_b128 v[208:211], v170 offset:1024
	ds_read_b128 v[212:215], v170 offset:2048
	ds_read_b128 v[216:219], v170 offset:3072
	ds_read_b128 v[220:223], v170 offset:4096
	ds_read_b128 v[224:227], v170 offset:5120
	ds_read_b128 v[232:235], v170 offset:6144
	ds_read_b128 v[242:245], v170 offset:7168
	s_mov_b64 s[58:59], 0x9840080
	s_add_u32 s100, s48, s58
	s_addc_u32 s101, s49, s59
	s_add_i32 m0, s17, 0xc000
	s_nop 0
	global_load_lds_dwordx4 v164, s[100:101]
	s_add_i32 m0, s17, 0xe000
	s_nop 0
	global_load_lds_dwordx4 v166, s[100:101]
	s_waitcnt vmcnt(8) lgkmcnt(0)
	s_setprio 1
	s_barrier
	v_mfma_f32_16x16x32_bf16 v[160:163], v[172:175], v[204:207], v[160:163]
	v_mfma_f32_16x16x32_bf16 v[156:159], v[180:183], v[204:207], v[156:159]
	v_mfma_f32_16x16x32_bf16 v[112:115], v[172:175], v[212:215], v[112:115]
	v_mfma_f32_16x16x32_bf16 v[108:111], v[180:183], v[212:215], v[108:111]
	v_mfma_f32_16x16x32_bf16 v[96:99], v[172:175], v[220:223], v[96:99]
	v_mfma_f32_16x16x32_bf16 v[92:95], v[180:183], v[220:223], v[92:95]
	v_mfma_f32_16x16x32_bf16 v[80:83], v[172:175], v[232:235], v[80:83]
	v_mfma_f32_16x16x32_bf16 v[76:79], v[180:183], v[232:235], v[76:79]
	v_mfma_f32_16x16x32_bf16 v[160:163], v[176:179], v[208:211], v[160:163]
	v_mfma_f32_16x16x32_bf16 v[156:159], v[184:187], v[208:211], v[156:159]
	v_mfma_f32_16x16x32_bf16 v[112:115], v[176:179], v[216:219], v[112:115]
	v_mfma_f32_16x16x32_bf16 v[108:111], v[184:187], v[216:219], v[108:111]
	v_mfma_f32_16x16x32_bf16 v[96:99], v[176:179], v[224:227], v[96:99]
	v_mfma_f32_16x16x32_bf16 v[92:95], v[184:187], v[224:227], v[92:95]
	v_mfma_f32_16x16x32_bf16 v[80:83], v[176:179], v[242:245], v[80:83]
	v_mfma_f32_16x16x32_bf16 v[76:79], v[184:187], v[242:245], v[76:79]
	s_setprio 0
	s_setprio 1
	v_mfma_f32_16x16x32_bf16 v[128:131], v[188:191], v[204:207], v[128:131]
	v_mfma_f32_16x16x32_bf16 v[120:123], v[196:199], v[204:207], v[120:123]
	v_mfma_f32_16x16x32_bf16 v[104:107], v[188:191], v[212:215], v[104:107]
	v_mfma_f32_16x16x32_bf16 v[100:103], v[196:199], v[212:215], v[100:103]
	v_mfma_f32_16x16x32_bf16 v[88:91], v[188:191], v[220:223], v[88:91]
	v_mfma_f32_16x16x32_bf16 v[84:87], v[196:199], v[220:223], v[84:87]
	v_mfma_f32_16x16x32_bf16 v[72:75], v[188:191], v[232:235], v[72:75]
	v_mfma_f32_16x16x32_bf16 v[68:71], v[196:199], v[232:235], v[68:71]
	v_mfma_f32_16x16x32_bf16 v[128:131], v[192:195], v[208:211], v[128:131]
	v_mfma_f32_16x16x32_bf16 v[120:123], v[200:203], v[208:211], v[120:123]
	v_mfma_f32_16x16x32_bf16 v[104:107], v[192:195], v[216:219], v[104:107]
	v_mfma_f32_16x16x32_bf16 v[100:103], v[200:203], v[216:219], v[100:103]
	v_mfma_f32_16x16x32_bf16 v[88:91], v[192:195], v[224:227], v[88:91]
	v_mfma_f32_16x16x32_bf16 v[84:87], v[200:203], v[224:227], v[84:87]
	v_mfma_f32_16x16x32_bf16 v[72:75], v[192:195], v[242:245], v[72:75]
	v_mfma_f32_16x16x32_bf16 v[68:71], v[200:203], v[242:245], v[68:71]
	s_setprio 0
	s_barrier
	s_add_i32 s48, s50, s16
	ds_read_b128 v[204:207], v170 offset:16384
	ds_read_b128 v[208:211], v170 offset:17408
	ds_read_b128 v[212:215], v170 offset:18432
	ds_read_b128 v[216:219], v170 offset:19456
	ds_read_b128 v[220:223], v170 offset:20480
	ds_read_b128 v[224:227], v170 offset:21504
	ds_read_b128 v[232:235], v170 offset:22528
	ds_read_b128 v[242:245], v170 offset:23552
	s_mov_b32 m0, s48
	s_nop 0
	global_load_lds_dwordx4 v167, s[10:11]
	s_add_i32 m0, s48, 0x2000
	s_add_u32 s48, s10, 0x40000
	global_load_lds_dwordx4 v168, s[10:11]
	s_addc_u32 s49, s11, 0
	s_add_i32 s50, s51, s16
	s_mov_b32 m0, s50
	s_nop 0
	global_load_lds_dwordx4 v167, s[48:49]
	s_add_i32 m0, s50, 0x2000
	s_nop 0
	global_load_lds_dwordx4 v168, s[48:49]
	s_mov_b32 m0, s17
	s_nop 0
	global_load_lds_dwordx4 v164, s[8:9]
	s_mov_b32 m0, s22
	s_nop 0
	global_load_lds_dwordx4 v166, s[8:9]
	s_waitcnt vmcnt(8) lgkmcnt(0)
	s_setprio 1
	s_barrier
	v_mfma_f32_16x16x32_bf16 v[64:67], v[172:175], v[204:207], v[64:67]
	v_mfma_f32_16x16x32_bf16 v[60:63], v[180:183], v[204:207], v[60:63]
	v_mfma_f32_16x16x32_bf16 v[48:51], v[172:175], v[212:215], v[48:51]
	v_mfma_f32_16x16x32_bf16 v[44:47], v[180:183], v[212:215], v[44:47]
	v_mfma_f32_16x16x32_bf16 v[32:35], v[172:175], v[220:223], v[32:35]
	v_mfma_f32_16x16x32_bf16 v[28:31], v[180:183], v[220:223], v[28:31]
	v_mfma_f32_16x16x32_bf16 v[16:19], v[172:175], v[232:235], v[16:19]
	v_mfma_f32_16x16x32_bf16 v[12:15], v[180:183], v[232:235], v[12:15]
	v_mfma_f32_16x16x32_bf16 v[64:67], v[176:179], v[208:211], v[64:67]
	v_mfma_f32_16x16x32_bf16 v[60:63], v[184:187], v[208:211], v[60:63]
	v_mfma_f32_16x16x32_bf16 v[48:51], v[176:179], v[216:219], v[48:51]
	v_mfma_f32_16x16x32_bf16 v[44:47], v[184:187], v[216:219], v[44:47]
	v_mfma_f32_16x16x32_bf16 v[32:35], v[176:179], v[224:227], v[32:35]
	v_mfma_f32_16x16x32_bf16 v[28:31], v[184:187], v[224:227], v[28:31]
	v_mfma_f32_16x16x32_bf16 v[16:19], v[176:179], v[242:245], v[16:19]
	v_mfma_f32_16x16x32_bf16 v[12:15], v[184:187], v[242:245], v[12:15]
	s_setprio 0
	s_setprio 1
	v_mfma_f32_16x16x32_bf16 v[56:59], v[188:191], v[204:207], v[56:59]
	v_mfma_f32_16x16x32_bf16 v[52:55], v[196:199], v[204:207], v[52:55]
	v_mfma_f32_16x16x32_bf16 v[40:43], v[188:191], v[212:215], v[40:43]
	v_mfma_f32_16x16x32_bf16 v[36:39], v[196:199], v[212:215], v[36:39]
	v_mfma_f32_16x16x32_bf16 v[24:27], v[188:191], v[220:223], v[24:27]
	v_mfma_f32_16x16x32_bf16 v[20:23], v[196:199], v[220:223], v[20:23]
	v_mfma_f32_16x16x32_bf16 v[8:11], v[188:191], v[232:235], v[8:11]
	v_mfma_f32_16x16x32_bf16 v[2:5], v[196:199], v[232:235], v[4:7]
	v_mfma_f32_16x16x32_bf16 v[56:59], v[192:195], v[208:211], v[56:59]
	v_mfma_f32_16x16x32_bf16 v[52:55], v[200:203], v[208:211], v[52:55]
	v_mfma_f32_16x16x32_bf16 v[40:43], v[192:195], v[216:219], v[40:43]
	v_mfma_f32_16x16x32_bf16 v[36:39], v[200:203], v[216:219], v[36:39]
	v_mfma_f32_16x16x32_bf16 v[24:27], v[192:195], v[224:227], v[24:27]
	v_mfma_f32_16x16x32_bf16 v[20:23], v[200:203], v[224:227], v[20:23]
	v_mfma_f32_16x16x32_bf16 v[8:11], v[192:195], v[242:245], v[8:11]
	v_mfma_f32_16x16x32_bf16 v[2:5], v[200:203], v[242:245], v[2:5]
	s_setprio 0
	s_barrier
	s_add_i32 s50, 0, 0x18000
	s_add_i32 s51, 0, 0x1c000
	ds_read_b128 v[172:175], v0 offset:32768
	ds_read_b128 v[176:179], v0 offset:33792
	ds_read_b128 v[180:183], v0 offset:34816
	ds_read_b128 v[184:187], v0 offset:35840
	ds_read_b128 v[188:191], v0 offset:49152
	ds_read_b128 v[192:195], v0 offset:50176
	ds_read_b128 v[196:199], v0 offset:51200
	ds_read_b128 v[200:203], v0 offset:52224
	s_add_u32 s48, s8, 0x40000
	s_mov_b32 m0, s23
	ds_read_b128 v[204:207], v170 offset:32768
	ds_read_b128 v[208:211], v170 offset:33792
	ds_read_b128 v[212:215], v170 offset:34816
	ds_read_b128 v[216:219], v170 offset:35840
	ds_read_b128 v[220:223], v170 offset:36864
	ds_read_b128 v[224:227], v170 offset:37888
	ds_read_b128 v[232:235], v170 offset:38912
	ds_read_b128 v[242:245], v170 offset:39936
	s_addc_u32 s49, s9, 0
	s_nop 0
	global_load_lds_dwordx4 v164, s[48:49]
	s_mov_b32 m0, s24
	s_nop 0
	global_load_lds_dwordx4 v166, s[48:49]
	s_waitcnt vmcnt(8) lgkmcnt(0)
	s_setprio 1
	s_barrier
	v_mfma_f32_16x16x32_bf16 v[160:163], v[172:175], v[204:207], v[160:163]
	v_mfma_f32_16x16x32_bf16 v[156:159], v[180:183], v[204:207], v[156:159]
	v_mfma_f32_16x16x32_bf16 v[112:115], v[172:175], v[212:215], v[112:115]
	v_mfma_f32_16x16x32_bf16 v[108:111], v[180:183], v[212:215], v[108:111]
	v_mfma_f32_16x16x32_bf16 v[96:99], v[172:175], v[220:223], v[96:99]
	v_mfma_f32_16x16x32_bf16 v[92:95], v[180:183], v[220:223], v[92:95]
	v_mfma_f32_16x16x32_bf16 v[80:83], v[172:175], v[232:235], v[80:83]
	v_mfma_f32_16x16x32_bf16 v[76:79], v[180:183], v[232:235], v[76:79]
	v_mfma_f32_16x16x32_bf16 v[160:163], v[176:179], v[208:211], v[160:163]
	v_mfma_f32_16x16x32_bf16 v[156:159], v[184:187], v[208:211], v[156:159]
	v_mfma_f32_16x16x32_bf16 v[112:115], v[176:179], v[216:219], v[112:115]
	v_mfma_f32_16x16x32_bf16 v[108:111], v[184:187], v[216:219], v[108:111]
	v_mfma_f32_16x16x32_bf16 v[96:99], v[176:179], v[224:227], v[96:99]
	v_mfma_f32_16x16x32_bf16 v[92:95], v[184:187], v[224:227], v[92:95]
	v_mfma_f32_16x16x32_bf16 v[80:83], v[176:179], v[242:245], v[80:83]
	v_mfma_f32_16x16x32_bf16 v[76:79], v[184:187], v[242:245], v[76:79]
	s_setprio 0
	s_setprio 1
	v_mfma_f32_16x16x32_bf16 v[128:131], v[188:191], v[204:207], v[128:131]
	v_mfma_f32_16x16x32_bf16 v[120:123], v[196:199], v[204:207], v[120:123]
	v_mfma_f32_16x16x32_bf16 v[104:107], v[188:191], v[212:215], v[104:107]
	v_mfma_f32_16x16x32_bf16 v[100:103], v[196:199], v[212:215], v[100:103]
	v_mfma_f32_16x16x32_bf16 v[88:91], v[188:191], v[220:223], v[88:91]
	v_mfma_f32_16x16x32_bf16 v[84:87], v[196:199], v[220:223], v[84:87]
	v_mfma_f32_16x16x32_bf16 v[72:75], v[188:191], v[232:235], v[72:75]
	v_mfma_f32_16x16x32_bf16 v[68:71], v[196:199], v[232:235], v[68:71]
	v_mfma_f32_16x16x32_bf16 v[128:131], v[192:195], v[208:211], v[128:131]
	v_mfma_f32_16x16x32_bf16 v[120:123], v[200:203], v[208:211], v[120:123]
	v_mfma_f32_16x16x32_bf16 v[104:107], v[192:195], v[216:219], v[104:107]
	v_mfma_f32_16x16x32_bf16 v[100:103], v[200:203], v[216:219], v[100:103]
	v_mfma_f32_16x16x32_bf16 v[88:91], v[192:195], v[224:227], v[88:91]
	v_mfma_f32_16x16x32_bf16 v[84:87], v[200:203], v[224:227], v[84:87]
	v_mfma_f32_16x16x32_bf16 v[72:75], v[192:195], v[242:245], v[72:75]
	v_mfma_f32_16x16x32_bf16 v[68:71], v[200:203], v[242:245], v[68:71]
	s_setprio 0
	s_barrier
	ds_read_b128 v[204:207], v170 offset:49152
	ds_read_b128 v[208:211], v170 offset:50176
	ds_read_b128 v[212:215], v170 offset:51200
	ds_read_b128 v[216:219], v170 offset:52224
	ds_read_b128 v[220:223], v170 offset:53248
	ds_read_b128 v[224:227], v170 offset:54272
	ds_read_b128 v[232:235], v170 offset:55296
	ds_read_b128 v[242:245], v170 offset:56320
	s_add_i32 s48, s50, s16
	s_add_u32 s100, s10, s38
	s_addc_u32 s101, s11, s39
	s_mov_b32 m0, s48
	s_nop 0
	global_load_lds_dwordx4 v167, s[100:101]
	s_add_i32 m0, s48, 0x2000
	s_nop 0
	s_add_u32 s10, s10, 0x40080
	s_addc_u32 s11, s11, 0
	s_add_i32 s48, s51, s16
	global_load_lds_dwordx4 v168, s[100:101]
	s_mov_b32 m0, s48
	s_nop 0
	global_load_lds_dwordx4 v167, s[10:11]
	s_add_i32 m0, s48, 0x2000
	s_nop 0
	global_load_lds_dwordx4 v168, s[10:11]
	s_mov_b32 m0, s37
	s_add_u32 s100, s8, s38
	s_addc_u32 s101, s9, s39
	v_mov_b32_e32 v0, v166
	global_load_lds_dwordx4 v164, s[100:101]
	s_mov_b32 m0, s40
	s_nop 0
	global_load_lds_dwordx4 v166, s[100:101]
	s_waitcnt vmcnt(8) lgkmcnt(0)
	s_setprio 1
	s_barrier
	v_mfma_f32_16x16x32_bf16 v[64:67], v[172:175], v[204:207], v[64:67]
	v_mfma_f32_16x16x32_bf16 v[60:63], v[180:183], v[204:207], v[60:63]
	v_mfma_f32_16x16x32_bf16 v[48:51], v[172:175], v[212:215], v[48:51]
	v_mfma_f32_16x16x32_bf16 v[44:47], v[180:183], v[212:215], v[44:47]
	v_mfma_f32_16x16x32_bf16 v[32:35], v[172:175], v[220:223], v[32:35]
	v_mfma_f32_16x16x32_bf16 v[28:31], v[180:183], v[220:223], v[28:31]
	v_mfma_f32_16x16x32_bf16 v[16:19], v[172:175], v[232:235], v[16:19]
	v_mfma_f32_16x16x32_bf16 v[12:15], v[180:183], v[232:235], v[12:15]
	v_mfma_f32_16x16x32_bf16 v[64:67], v[176:179], v[208:211], v[64:67]
	v_mfma_f32_16x16x32_bf16 v[60:63], v[184:187], v[208:211], v[60:63]
	v_mfma_f32_16x16x32_bf16 v[48:51], v[176:179], v[216:219], v[48:51]
	v_mfma_f32_16x16x32_bf16 v[44:47], v[184:187], v[216:219], v[44:47]
	v_mfma_f32_16x16x32_bf16 v[32:35], v[176:179], v[224:227], v[32:35]
	v_mfma_f32_16x16x32_bf16 v[28:31], v[184:187], v[224:227], v[28:31]
	v_mfma_f32_16x16x32_bf16 v[16:19], v[176:179], v[242:245], v[16:19]
	v_mfma_f32_16x16x32_bf16 v[12:15], v[184:187], v[242:245], v[12:15]
	s_setprio 0
	s_setprio 1
	v_mfma_f32_16x16x32_bf16 v[56:59], v[188:191], v[204:207], v[56:59]
	v_mfma_f32_16x16x32_bf16 v[52:55], v[196:199], v[204:207], v[52:55]
	v_mfma_f32_16x16x32_bf16 v[40:43], v[188:191], v[212:215], v[40:43]
	v_mfma_f32_16x16x32_bf16 v[36:39], v[196:199], v[212:215], v[36:39]
	v_mfma_f32_16x16x32_bf16 v[24:27], v[188:191], v[220:223], v[24:27]
	v_mfma_f32_16x16x32_bf16 v[20:23], v[196:199], v[220:223], v[20:23]
	v_mfma_f32_16x16x32_bf16 v[6:9], v[188:191], v[232:235], v[8:11]
	v_mfma_f32_16x16x32_bf16 v[2:5], v[196:199], v[232:235], v[2:5]
	v_mfma_f32_16x16x32_bf16 v[56:59], v[192:195], v[208:211], v[56:59]
	v_mfma_f32_16x16x32_bf16 v[52:55], v[200:203], v[208:211], v[52:55]
	v_mfma_f32_16x16x32_bf16 v[40:43], v[192:195], v[216:219], v[40:43]
	v_mfma_f32_16x16x32_bf16 v[36:39], v[200:203], v[216:219], v[36:39]
	v_mfma_f32_16x16x32_bf16 v[24:27], v[192:195], v[224:227], v[24:27]
	v_mfma_f32_16x16x32_bf16 v[20:23], v[200:203], v[224:227], v[20:23]
	v_mfma_f32_16x16x32_bf16 v[8:11], v[192:195], v[242:245], v[6:9]
	v_mfma_f32_16x16x32_bf16 v[4:7], v[200:203], v[242:245], v[2:5]
	s_setprio 0
	s_barrier
	s_add_i32 s47, s47, 2
	s_add_u32 s6, s6, 0x100
	s_addc_u32 s7, s7, 0
	s_cmp_gt_u32 s47, 13
	s_cbranch_scc1 .LBB0_1573

.LBB0_1681:
	s_add_u32 s48, s6, s2
	s_addc_u32 s49, s7, s3
	s_add_u32 s10, s48, 0x100
	s_addc_u32 s11, s49, 0
	s_add_u32 s12, s37, s2
	s_addc_u32 s13, s40, s3
	s_add_i32 s47, 0, 0x10000
	s_cmp_eq_u32 s46, 12
	s_cselect_b32 s11, s7, s11
	s_cselect_b32 s10, s6, s10
	v_add_u32_e32 v0, s47, v136
	s_cselect_b32 s13, s9, s13
	s_cselect_b32 s12, s8, s12
	s_add_i32 s50, 0, 0x14000
	ds_read_b128 v[138:141], v0
	ds_read_b128 v[142:145], v0 offset:1024
	ds_read_b128 v[146:149], v0 offset:2048
	ds_read_b128 v[150:153], v0 offset:3072
	ds_read_b128 v[154:157], v0 offset:16384
	ds_read_b128 v[158:161], v0 offset:17408
	ds_read_b128 v[162:165], v0 offset:18432
	ds_read_b128 v[166:169], v0 offset:19456
	ds_read_b128 v[170:173], v137
	ds_read_b128 v[174:177], v137 offset:1024
	ds_read_b128 v[178:181], v137 offset:2048
	ds_read_b128 v[182:185], v137 offset:3072
	ds_read_b128 v[186:189], v137 offset:4096
	ds_read_b128 v[190:193], v137 offset:5120
	ds_read_b128 v[194:197], v137 offset:6144
	ds_read_b128 v[198:201], v137 offset:7168
	s_add_i32 m0, s23, 0xc000
	s_add_u32 s100, s48, s56
	s_addc_u32 s101, s49, s57
	global_load_lds_dwordx4 v130, s[100:101]
	s_add_i32 m0, s23, 0xe000
	s_nop 0
	global_load_lds_dwordx4 v132, s[100:101]
	s_waitcnt vmcnt(8) lgkmcnt(0)
	s_setprio 1
	s_barrier
	v_mfma_f32_16x16x32_bf16 v[126:129], v[138:141], v[170:173], v[126:129]
	v_mfma_f32_16x16x32_bf16 v[122:125], v[146:149], v[170:173], v[122:125]
	v_mfma_f32_16x16x32_bf16 v[110:113], v[138:141], v[178:181], v[110:113]
	v_mfma_f32_16x16x32_bf16 v[106:109], v[146:149], v[178:181], v[106:109]
	v_mfma_f32_16x16x32_bf16 v[94:97], v[138:141], v[186:189], v[94:97]
	v_mfma_f32_16x16x32_bf16 v[90:93], v[146:149], v[186:189], v[90:93]
	v_mfma_f32_16x16x32_bf16 v[78:81], v[138:141], v[194:197], v[78:81]
	v_mfma_f32_16x16x32_bf16 v[74:77], v[146:149], v[194:197], v[74:77]
	v_mfma_f32_16x16x32_bf16 v[126:129], v[142:145], v[174:177], v[126:129]
	v_mfma_f32_16x16x32_bf16 v[122:125], v[150:153], v[174:177], v[122:125]
	v_mfma_f32_16x16x32_bf16 v[110:113], v[142:145], v[182:185], v[110:113]
	v_mfma_f32_16x16x32_bf16 v[106:109], v[150:153], v[182:185], v[106:109]
	v_mfma_f32_16x16x32_bf16 v[94:97], v[142:145], v[190:193], v[94:97]
	v_mfma_f32_16x16x32_bf16 v[90:93], v[150:153], v[190:193], v[90:93]
	v_mfma_f32_16x16x32_bf16 v[78:81], v[142:145], v[198:201], v[78:81]
	v_mfma_f32_16x16x32_bf16 v[74:77], v[150:153], v[198:201], v[74:77]
	s_setprio 0
	s_setprio 1
	v_mfma_f32_16x16x32_bf16 v[118:121], v[154:157], v[170:173], v[118:121]
	v_mfma_f32_16x16x32_bf16 v[114:117], v[162:165], v[170:173], v[114:117]
	v_mfma_f32_16x16x32_bf16 v[102:105], v[154:157], v[178:181], v[102:105]
	v_mfma_f32_16x16x32_bf16 v[98:101], v[162:165], v[178:181], v[98:101]
	v_mfma_f32_16x16x32_bf16 v[86:89], v[154:157], v[186:189], v[86:89]
	v_mfma_f32_16x16x32_bf16 v[82:85], v[162:165], v[186:189], v[82:85]
	v_mfma_f32_16x16x32_bf16 v[70:73], v[154:157], v[194:197], v[70:73]
	v_mfma_f32_16x16x32_bf16 v[66:69], v[162:165], v[194:197], v[66:69]
	v_mfma_f32_16x16x32_bf16 v[118:121], v[158:161], v[174:177], v[118:121]
	v_mfma_f32_16x16x32_bf16 v[114:117], v[166:169], v[174:177], v[114:117]
	v_mfma_f32_16x16x32_bf16 v[102:105], v[158:161], v[182:185], v[102:105]
	v_mfma_f32_16x16x32_bf16 v[98:101], v[166:169], v[182:185], v[98:101]
	v_mfma_f32_16x16x32_bf16 v[86:89], v[158:161], v[190:193], v[86:89]
	v_mfma_f32_16x16x32_bf16 v[82:85], v[166:169], v[190:193], v[82:85]
	v_mfma_f32_16x16x32_bf16 v[70:73], v[158:161], v[198:201], v[70:73]
	v_mfma_f32_16x16x32_bf16 v[66:69], v[166:169], v[198:201], v[66:69]
	s_setprio 0
	s_barrier
	s_add_i32 s47, s47, s22
	ds_read_b128 v[170:173], v137 offset:16384
	ds_read_b128 v[174:177], v137 offset:17408
	ds_read_b128 v[178:181], v137 offset:18432
	ds_read_b128 v[182:185], v137 offset:19456
	ds_read_b128 v[186:189], v137 offset:20480
	ds_read_b128 v[190:193], v137 offset:21504
	ds_read_b128 v[194:197], v137 offset:22528
	ds_read_b128 v[198:201], v137 offset:23552
	s_mov_b32 m0, s47
	s_nop 0
	global_load_lds_dwordx4 v134, s[12:13]
	s_add_i32 m0, s47, 0x2000
	s_add_u32 s48, s12, 0x40000
	global_load_lds_dwordx4 v135, s[12:13]
	s_addc_u32 s49, s13, 0
	s_add_i32 s47, s50, s22
	s_mov_b32 m0, s47
	s_nop 0
	global_load_lds_dwordx4 v134, s[48:49]
	s_add_i32 m0, s47, 0x2000
	s_nop 0
	global_load_lds_dwordx4 v135, s[48:49]
	s_mov_b32 m0, s23
	s_nop 0
	global_load_lds_dwordx4 v130, s[10:11]
	s_mov_b32 m0, s24
	s_nop 0
	global_load_lds_dwordx4 v132, s[10:11]
	s_waitcnt vmcnt(8) lgkmcnt(0)
	s_setprio 1
	s_barrier
	v_mfma_f32_16x16x32_bf16 v[62:65], v[138:141], v[170:173], v[62:65]
	v_mfma_f32_16x16x32_bf16 v[58:61], v[146:149], v[170:173], v[58:61]
	v_mfma_f32_16x16x32_bf16 v[46:49], v[138:141], v[178:181], v[46:49]
	v_mfma_f32_16x16x32_bf16 v[42:45], v[146:149], v[178:181], v[42:45]
	v_mfma_f32_16x16x32_bf16 v[30:33], v[138:141], v[186:189], v[30:33]
	v_mfma_f32_16x16x32_bf16 v[26:29], v[146:149], v[186:189], v[26:29]
	v_mfma_f32_16x16x32_bf16 v[14:17], v[138:141], v[194:197], v[14:17]
	v_mfma_f32_16x16x32_bf16 v[10:13], v[146:149], v[194:197], v[10:13]
	v_mfma_f32_16x16x32_bf16 v[62:65], v[142:145], v[174:177], v[62:65]
	v_mfma_f32_16x16x32_bf16 v[58:61], v[150:153], v[174:177], v[58:61]
	v_mfma_f32_16x16x32_bf16 v[46:49], v[142:145], v[182:185], v[46:49]
	v_mfma_f32_16x16x32_bf16 v[42:45], v[150:153], v[182:185], v[42:45]
	v_mfma_f32_16x16x32_bf16 v[30:33], v[142:145], v[190:193], v[30:33]
	v_mfma_f32_16x16x32_bf16 v[26:29], v[150:153], v[190:193], v[26:29]
	v_mfma_f32_16x16x32_bf16 v[14:17], v[142:145], v[198:201], v[14:17]
	v_mfma_f32_16x16x32_bf16 v[10:13], v[150:153], v[198:201], v[10:13]
	s_setprio 0
	s_setprio 1
	v_mfma_f32_16x16x32_bf16 v[54:57], v[154:157], v[170:173], v[54:57]
	v_mfma_f32_16x16x32_bf16 v[50:53], v[162:165], v[170:173], v[50:53]
	v_mfma_f32_16x16x32_bf16 v[38:41], v[154:157], v[178:181], v[38:41]
	v_mfma_f32_16x16x32_bf16 v[34:37], v[162:165], v[178:181], v[34:37]
	v_mfma_f32_16x16x32_bf16 v[22:25], v[154:157], v[186:189], v[22:25]
	v_mfma_f32_16x16x32_bf16 v[18:21], v[162:165], v[186:189], v[18:21]
	v_mfma_f32_16x16x32_bf16 v[6:9], v[154:157], v[194:197], v[6:9]
	v_mfma_f32_16x16x32_bf16 v[2:5], v[162:165], v[194:197], v[2:5]
	v_mfma_f32_16x16x32_bf16 v[54:57], v[158:161], v[174:177], v[54:57]
	v_mfma_f32_16x16x32_bf16 v[50:53], v[166:169], v[174:177], v[50:53]
	v_mfma_f32_16x16x32_bf16 v[38:41], v[158:161], v[182:185], v[38:41]
	v_mfma_f32_16x16x32_bf16 v[34:37], v[166:169], v[182:185], v[34:37]
	v_mfma_f32_16x16x32_bf16 v[22:25], v[158:161], v[190:193], v[22:25]
	v_mfma_f32_16x16x32_bf16 v[18:21], v[166:169], v[190:193], v[18:21]
	v_mfma_f32_16x16x32_bf16 v[6:9], v[158:161], v[198:201], v[6:9]
	v_mfma_f32_16x16x32_bf16 v[2:5], v[166:169], v[198:201], v[2:5]
	s_setprio 0
	s_barrier
	s_add_i32 s47, 0, 0x18000
	s_add_i32 s50, 0, 0x1c000
	ds_read_b128 v[138:141], v0 offset:32768
	ds_read_b128 v[142:145], v0 offset:33792
	ds_read_b128 v[146:149], v0 offset:34816
	ds_read_b128 v[150:153], v0 offset:35840
	ds_read_b128 v[154:157], v0 offset:49152
	ds_read_b128 v[158:161], v0 offset:50176
	ds_read_b128 v[162:165], v0 offset:51200
	ds_read_b128 v[166:169], v0 offset:52224
	s_add_u32 s48, s10, 0x40000
	s_mov_b32 m0, s25
	ds_read_b128 v[170:173], v137 offset:32768
	ds_read_b128 v[174:177], v137 offset:33792
	ds_read_b128 v[178:181], v137 offset:34816
	ds_read_b128 v[182:185], v137 offset:35840
	ds_read_b128 v[186:189], v137 offset:36864
	ds_read_b128 v[190:193], v137 offset:37888
	ds_read_b128 v[194:197], v137 offset:38912
	ds_read_b128 v[198:201], v137 offset:39936
	s_addc_u32 s49, s11, 0
	s_nop 0
	global_load_lds_dwordx4 v130, s[48:49]
	s_mov_b32 m0, s26
	s_nop 0
	global_load_lds_dwordx4 v132, s[48:49]
	s_waitcnt vmcnt(8) lgkmcnt(0)
	s_setprio 1
	s_barrier
	v_mfma_f32_16x16x32_bf16 v[126:129], v[138:141], v[170:173], v[126:129]
	v_mfma_f32_16x16x32_bf16 v[122:125], v[146:149], v[170:173], v[122:125]
	v_mfma_f32_16x16x32_bf16 v[110:113], v[138:141], v[178:181], v[110:113]
	v_mfma_f32_16x16x32_bf16 v[106:109], v[146:149], v[178:181], v[106:109]
	v_mfma_f32_16x16x32_bf16 v[94:97], v[138:141], v[186:189], v[94:97]
	v_mfma_f32_16x16x32_bf16 v[90:93], v[146:149], v[186:189], v[90:93]
	v_mfma_f32_16x16x32_bf16 v[78:81], v[138:141], v[194:197], v[78:81]
	v_mfma_f32_16x16x32_bf16 v[74:77], v[146:149], v[194:197], v[74:77]
	v_mfma_f32_16x16x32_bf16 v[126:129], v[142:145], v[174:177], v[126:129]
	v_mfma_f32_16x16x32_bf16 v[122:125], v[150:153], v[174:177], v[122:125]
	v_mfma_f32_16x16x32_bf16 v[110:113], v[142:145], v[182:185], v[110:113]
	v_mfma_f32_16x16x32_bf16 v[106:109], v[150:153], v[182:185], v[106:109]
	v_mfma_f32_16x16x32_bf16 v[94:97], v[142:145], v[190:193], v[94:97]
	v_mfma_f32_16x16x32_bf16 v[90:93], v[150:153], v[190:193], v[90:93]
	v_mfma_f32_16x16x32_bf16 v[78:81], v[142:145], v[198:201], v[78:81]
	v_mfma_f32_16x16x32_bf16 v[74:77], v[150:153], v[198:201], v[74:77]
	s_setprio 0
	s_setprio 1
	v_mfma_f32_16x16x32_bf16 v[118:121], v[154:157], v[170:173], v[118:121]
	v_mfma_f32_16x16x32_bf16 v[114:117], v[162:165], v[170:173], v[114:117]
	v_mfma_f32_16x16x32_bf16 v[102:105], v[154:157], v[178:181], v[102:105]
	v_mfma_f32_16x16x32_bf16 v[98:101], v[162:165], v[178:181], v[98:101]
	v_mfma_f32_16x16x32_bf16 v[86:89], v[154:157], v[186:189], v[86:89]
	v_mfma_f32_16x16x32_bf16 v[82:85], v[162:165], v[186:189], v[82:85]
	v_mfma_f32_16x16x32_bf16 v[70:73], v[154:157], v[194:197], v[70:73]
	v_mfma_f32_16x16x32_bf16 v[66:69], v[162:165], v[194:197], v[66:69]
	v_mfma_f32_16x16x32_bf16 v[118:121], v[158:161], v[174:177], v[118:121]
	v_mfma_f32_16x16x32_bf16 v[114:117], v[166:169], v[174:177], v[114:117]
	v_mfma_f32_16x16x32_bf16 v[102:105], v[158:161], v[182:185], v[102:105]
	v_mfma_f32_16x16x32_bf16 v[98:101], v[166:169], v[182:185], v[98:101]
	v_mfma_f32_16x16x32_bf16 v[86:89], v[158:161], v[190:193], v[86:89]
	v_mfma_f32_16x16x32_bf16 v[82:85], v[166:169], v[190:193], v[82:85]
	v_mfma_f32_16x16x32_bf16 v[70:73], v[158:161], v[198:201], v[70:73]
	v_mfma_f32_16x16x32_bf16 v[66:69], v[166:169], v[198:201], v[66:69]
	s_setprio 0
	s_barrier
	ds_read_b128 v[170:173], v137 offset:49152
	ds_read_b128 v[174:177], v137 offset:50176
	ds_read_b128 v[178:181], v137 offset:51200
	ds_read_b128 v[182:185], v137 offset:52224
	ds_read_b128 v[186:189], v137 offset:53248
	ds_read_b128 v[190:193], v137 offset:54272
	ds_read_b128 v[194:197], v137 offset:55296
	ds_read_b128 v[198:201], v137 offset:56320
	s_add_i32 s47, s47, s22
	s_add_u32 s100, s12, s38
	s_addc_u32 s101, s13, s39
	s_mov_b32 m0, s47
	s_nop 0
	global_load_lds_dwordx4 v134, s[100:101]
	s_add_i32 m0, s47, 0x2000
	s_nop 0
	s_add_u32 s12, s12, 0x40080
	s_addc_u32 s13, s13, 0
	s_add_i32 s47, s50, s22
	global_load_lds_dwordx4 v135, s[100:101]
	s_mov_b32 m0, s47
	s_nop 0
	global_load_lds_dwordx4 v134, s[12:13]
	s_add_i32 m0, s47, 0x2000
	s_nop 0
	global_load_lds_dwordx4 v135, s[12:13]
	s_mov_b32 m0, s42
	s_add_u32 s100, s10, s38
	s_addc_u32 s101, s11, s39
	v_mov_b32_e32 v0, v132
	global_load_lds_dwordx4 v130, s[100:101]
	s_mov_b32 m0, s43
	s_nop 0
	global_load_lds_dwordx4 v132, s[100:101]
	s_waitcnt vmcnt(8) lgkmcnt(0)
	s_setprio 1
	s_barrier
	v_mfma_f32_16x16x32_bf16 v[62:65], v[138:141], v[170:173], v[62:65]
	v_mfma_f32_16x16x32_bf16 v[58:61], v[146:149], v[170:173], v[58:61]
	v_mfma_f32_16x16x32_bf16 v[46:49], v[138:141], v[178:181], v[46:49]
	v_mfma_f32_16x16x32_bf16 v[42:45], v[146:149], v[178:181], v[42:45]
	v_mfma_f32_16x16x32_bf16 v[30:33], v[138:141], v[186:189], v[30:33]
	v_mfma_f32_16x16x32_bf16 v[26:29], v[146:149], v[186:189], v[26:29]
	v_mfma_f32_16x16x32_bf16 v[14:17], v[138:141], v[194:197], v[14:17]
	v_mfma_f32_16x16x32_bf16 v[10:13], v[146:149], v[194:197], v[10:13]
	v_mfma_f32_16x16x32_bf16 v[62:65], v[142:145], v[174:177], v[62:65]
	v_mfma_f32_16x16x32_bf16 v[58:61], v[150:153], v[174:177], v[58:61]
	v_mfma_f32_16x16x32_bf16 v[46:49], v[142:145], v[182:185], v[46:49]
	v_mfma_f32_16x16x32_bf16 v[42:45], v[150:153], v[182:185], v[42:45]
	v_mfma_f32_16x16x32_bf16 v[30:33], v[142:145], v[190:193], v[30:33]
	v_mfma_f32_16x16x32_bf16 v[26:29], v[150:153], v[190:193], v[26:29]
	v_mfma_f32_16x16x32_bf16 v[14:17], v[142:145], v[198:201], v[14:17]
	v_mfma_f32_16x16x32_bf16 v[10:13], v[150:153], v[198:201], v[10:13]
	s_setprio 0
	s_setprio 1
	v_mfma_f32_16x16x32_bf16 v[54:57], v[154:157], v[170:173], v[54:57]
	v_mfma_f32_16x16x32_bf16 v[50:53], v[162:165], v[170:173], v[50:53]
	v_mfma_f32_16x16x32_bf16 v[38:41], v[154:157], v[178:181], v[38:41]
	v_mfma_f32_16x16x32_bf16 v[34:37], v[162:165], v[178:181], v[34:37]
	v_mfma_f32_16x16x32_bf16 v[22:25], v[154:157], v[186:189], v[22:25]
	v_mfma_f32_16x16x32_bf16 v[18:21], v[162:165], v[186:189], v[18:21]
	v_mfma_f32_16x16x32_bf16 v[6:9], v[154:157], v[194:197], v[6:9]
	v_mfma_f32_16x16x32_bf16 v[2:5], v[162:165], v[194:197], v[2:5]
	v_mfma_f32_16x16x32_bf16 v[54:57], v[158:161], v[174:177], v[54:57]
	v_mfma_f32_16x16x32_bf16 v[50:53], v[166:169], v[174:177], v[50:53]
	v_mfma_f32_16x16x32_bf16 v[38:41], v[158:161], v[182:185], v[38:41]
	v_mfma_f32_16x16x32_bf16 v[34:37], v[166:169], v[182:185], v[34:37]
	v_mfma_f32_16x16x32_bf16 v[22:25], v[158:161], v[190:193], v[22:25]
	v_mfma_f32_16x16x32_bf16 v[18:21], v[166:169], v[190:193], v[18:21]
	v_mfma_f32_16x16x32_bf16 v[6:9], v[158:161], v[198:201], v[6:9]
	v_mfma_f32_16x16x32_bf16 v[2:5], v[166:169], v[198:201], v[2:5]
	s_setprio 0
	s_barrier
	s_add_i32 s46, s46, 2
	s_add_u32 s2, s2, 0x100
	s_addc_u32 s3, s3, 0
	s_cmp_gt_u32 s46, 13
	s_cbranch_scc0 .LBB0_1681

.LBB0_1807:
	s_add_u32 s68, s4, s14
	s_addc_u32 s69, s5, s15
	s_add_u32 s16, s68, 0x100
	s_addc_u32 s17, s69, 0
	s_add_u32 s22, s50, s14
	s_addc_u32 s23, s51, s15
	s_add_i32 s67, 0, 0x10000
	s_cmp_eq_u32 s66, 12
	s_cselect_b32 s17, s5, s17
	s_cselect_b32 s16, s4, s16
	v_add_u32_e32 v0, s67, v126
	s_cselect_b32 s23, s13, s23
	s_cselect_b32 s22, s12, s22
	s_add_i32 s70, 0, 0x14000
	ds_read_b128 v[128:131], v0
	ds_read_b128 v[142:145], v0 offset:1024
	ds_read_b128 v[146:149], v0 offset:2048
	ds_read_b128 v[150:153], v0 offset:3072
	ds_read_b128 v[154:157], v0 offset:16384
	ds_read_b128 v[160:163], v0 offset:17408
	ds_read_b128 v[164:167], v0 offset:18432
	ds_read_b128 v[168:171], v0 offset:19456
	ds_read_b128 v[172:175], v127
	ds_read_b128 v[176:179], v127 offset:1024
	ds_read_b128 v[180:183], v127 offset:2048
	ds_read_b128 v[184:187], v127 offset:3072
	ds_read_b128 v[188:191], v127 offset:4096
	ds_read_b128 v[192:195], v127 offset:5120
	ds_read_b128 v[196:199], v127 offset:6144
	ds_read_b128 v[200:203], v127 offset:7168
	s_add_i32 m0, s43, 0xc000
	s_add_u32 s100, s68, s56
	s_addc_u32 s101, s69, s57
	global_load_lds_dwordx4 v122, s[100:101]
	s_add_i32 m0, s43, 0xe000
	s_nop 0
	global_load_lds_dwordx4 v123, s[100:101]
	s_waitcnt vmcnt(8) lgkmcnt(0)
	s_setprio 1
	s_barrier
	v_mfma_f32_16x16x32_bf16 v[138:141], v[128:131], v[172:175], v[138:141]
	v_mfma_f32_16x16x32_bf16 v[132:135], v[146:149], v[172:175], v[134:137]
	v_mfma_f32_16x16x32_bf16 v[110:113], v[128:131], v[180:183], v[110:113]
	v_mfma_f32_16x16x32_bf16 v[106:109], v[146:149], v[180:183], v[106:109]
	v_mfma_f32_16x16x32_bf16 v[94:97], v[128:131], v[188:191], v[94:97]
	v_mfma_f32_16x16x32_bf16 v[90:93], v[146:149], v[188:191], v[90:93]
	v_mfma_f32_16x16x32_bf16 v[78:81], v[128:131], v[196:199], v[78:81]
	v_mfma_f32_16x16x32_bf16 v[74:77], v[146:149], v[196:199], v[74:77]
	v_mfma_f32_16x16x32_bf16 v[138:141], v[142:145], v[176:179], v[138:141]
	v_mfma_f32_16x16x32_bf16 v[132:135], v[150:153], v[176:179], v[132:135]
	v_mfma_f32_16x16x32_bf16 v[110:113], v[142:145], v[184:187], v[110:113]
	v_mfma_f32_16x16x32_bf16 v[106:109], v[150:153], v[184:187], v[106:109]
	v_mfma_f32_16x16x32_bf16 v[94:97], v[142:145], v[192:195], v[94:97]
	v_mfma_f32_16x16x32_bf16 v[90:93], v[150:153], v[192:195], v[90:93]
	v_mfma_f32_16x16x32_bf16 v[78:81], v[142:145], v[200:203], v[78:81]
	v_mfma_f32_16x16x32_bf16 v[74:77], v[150:153], v[200:203], v[74:77]
	s_setprio 0
	s_setprio 1
	v_mfma_f32_16x16x32_bf16 v[118:121], v[154:157], v[172:175], v[118:121]
	v_mfma_f32_16x16x32_bf16 v[114:117], v[164:167], v[172:175], v[114:117]
	v_mfma_f32_16x16x32_bf16 v[102:105], v[154:157], v[180:183], v[102:105]
	v_mfma_f32_16x16x32_bf16 v[98:101], v[164:167], v[180:183], v[98:101]
	v_mfma_f32_16x16x32_bf16 v[86:89], v[154:157], v[188:191], v[86:89]
	v_mfma_f32_16x16x32_bf16 v[82:85], v[164:167], v[188:191], v[82:85]
	v_mfma_f32_16x16x32_bf16 v[70:73], v[154:157], v[196:199], v[70:73]
	v_mfma_f32_16x16x32_bf16 v[66:69], v[164:167], v[196:199], v[66:69]
	v_mfma_f32_16x16x32_bf16 v[118:121], v[160:163], v[176:179], v[118:121]
	v_mfma_f32_16x16x32_bf16 v[114:117], v[168:171], v[176:179], v[114:117]
	v_mfma_f32_16x16x32_bf16 v[102:105], v[160:163], v[184:187], v[102:105]
	v_mfma_f32_16x16x32_bf16 v[98:101], v[168:171], v[184:187], v[98:101]
	v_mfma_f32_16x16x32_bf16 v[86:89], v[160:163], v[192:195], v[86:89]
	v_mfma_f32_16x16x32_bf16 v[82:85], v[168:171], v[192:195], v[82:85]
	v_mfma_f32_16x16x32_bf16 v[70:73], v[160:163], v[200:203], v[70:73]
	v_mfma_f32_16x16x32_bf16 v[66:69], v[168:171], v[200:203], v[66:69]
	s_setprio 0
	s_barrier
	s_add_i32 s67, s67, s42
	ds_read_b128 v[172:175], v127 offset:16384
	ds_read_b128 v[176:179], v127 offset:17408
	ds_read_b128 v[180:183], v127 offset:18432
	ds_read_b128 v[184:187], v127 offset:19456
	ds_read_b128 v[188:191], v127 offset:20480
	ds_read_b128 v[192:195], v127 offset:21504
	ds_read_b128 v[196:199], v127 offset:22528
	ds_read_b128 v[200:203], v127 offset:23552
	s_mov_b32 m0, s67
	s_nop 0
	global_load_lds_dwordx4 v124, s[22:23]
	s_add_i32 m0, s67, 0x2000
	s_add_u32 s68, s22, 0x40000
	global_load_lds_dwordx4 v125, s[22:23]
	s_addc_u32 s69, s23, 0
	s_add_i32 s67, s70, s42
	s_mov_b32 m0, s67
	s_nop 0
	global_load_lds_dwordx4 v124, s[68:69]
	s_add_i32 m0, s67, 0x2000
	s_nop 0
	global_load_lds_dwordx4 v125, s[68:69]
	s_mov_b32 m0, s43
	s_nop 0
	global_load_lds_dwordx4 v122, s[16:17]
	s_mov_b32 m0, s46
	s_nop 0
	global_load_lds_dwordx4 v123, s[16:17]
	s_waitcnt vmcnt(8) lgkmcnt(0)
	s_setprio 1
	s_barrier
	v_mfma_f32_16x16x32_bf16 v[62:65], v[128:131], v[172:175], v[62:65]
	v_mfma_f32_16x16x32_bf16 v[58:61], v[146:149], v[172:175], v[58:61]
	v_mfma_f32_16x16x32_bf16 v[46:49], v[128:131], v[180:183], v[46:49]
	v_mfma_f32_16x16x32_bf16 v[42:45], v[146:149], v[180:183], v[42:45]
	v_mfma_f32_16x16x32_bf16 v[30:33], v[128:131], v[188:191], v[30:33]
	v_mfma_f32_16x16x32_bf16 v[26:29], v[146:149], v[188:191], v[26:29]
	v_mfma_f32_16x16x32_bf16 v[14:17], v[128:131], v[196:199], v[14:17]
	v_mfma_f32_16x16x32_bf16 v[10:13], v[146:149], v[196:199], v[10:13]
	v_mfma_f32_16x16x32_bf16 v[62:65], v[142:145], v[176:179], v[62:65]
	v_mfma_f32_16x16x32_bf16 v[58:61], v[150:153], v[176:179], v[58:61]
	v_mfma_f32_16x16x32_bf16 v[46:49], v[142:145], v[184:187], v[46:49]
	v_mfma_f32_16x16x32_bf16 v[42:45], v[150:153], v[184:187], v[42:45]
	v_mfma_f32_16x16x32_bf16 v[30:33], v[142:145], v[192:195], v[30:33]
	v_mfma_f32_16x16x32_bf16 v[26:29], v[150:153], v[192:195], v[26:29]
	v_mfma_f32_16x16x32_bf16 v[14:17], v[142:145], v[200:203], v[14:17]
	v_mfma_f32_16x16x32_bf16 v[10:13], v[150:153], v[200:203], v[10:13]
	s_setprio 0
	s_setprio 1
	v_mfma_f32_16x16x32_bf16 v[54:57], v[154:157], v[172:175], v[54:57]
	v_mfma_f32_16x16x32_bf16 v[50:53], v[164:167], v[172:175], v[50:53]
	v_mfma_f32_16x16x32_bf16 v[38:41], v[154:157], v[180:183], v[38:41]
	v_mfma_f32_16x16x32_bf16 v[34:37], v[164:167], v[180:183], v[34:37]
	v_mfma_f32_16x16x32_bf16 v[22:25], v[154:157], v[188:191], v[22:25]
	v_mfma_f32_16x16x32_bf16 v[18:21], v[164:167], v[188:191], v[18:21]
	v_mfma_f32_16x16x32_bf16 v[6:9], v[154:157], v[196:199], v[6:9]
	v_mfma_f32_16x16x32_bf16 v[2:5], v[164:167], v[196:199], v[2:5]
	v_mfma_f32_16x16x32_bf16 v[54:57], v[160:163], v[176:179], v[54:57]
	v_mfma_f32_16x16x32_bf16 v[50:53], v[168:171], v[176:179], v[50:53]
	v_mfma_f32_16x16x32_bf16 v[38:41], v[160:163], v[184:187], v[38:41]
	v_mfma_f32_16x16x32_bf16 v[34:37], v[168:171], v[184:187], v[34:37]
	v_mfma_f32_16x16x32_bf16 v[22:25], v[160:163], v[192:195], v[22:25]
	v_mfma_f32_16x16x32_bf16 v[18:21], v[168:171], v[192:195], v[18:21]
	v_mfma_f32_16x16x32_bf16 v[6:9], v[160:163], v[200:203], v[6:9]
	v_mfma_f32_16x16x32_bf16 v[2:5], v[168:171], v[200:203], v[2:5]
	s_setprio 0
	s_barrier
	s_add_i32 s67, 0, 0x18000
	s_add_i32 s70, 0, 0x1c000
	ds_read_b128 v[128:131], v0 offset:32768
	ds_read_b128 v[142:145], v0 offset:33792
	ds_read_b128 v[146:149], v0 offset:34816
	ds_read_b128 v[150:153], v0 offset:35840
	ds_read_b128 v[154:157], v0 offset:49152
	ds_read_b128 v[160:163], v0 offset:50176
	ds_read_b128 v[164:167], v0 offset:51200
	ds_read_b128 v[168:171], v0 offset:52224
	s_add_u32 s68, s16, 0x40000
	s_mov_b32 m0, s47
	ds_read_b128 v[172:175], v127 offset:32768
	ds_read_b128 v[176:179], v127 offset:33792
	ds_read_b128 v[180:183], v127 offset:34816
	ds_read_b128 v[184:187], v127 offset:35840
	ds_read_b128 v[188:191], v127 offset:36864
	ds_read_b128 v[192:195], v127 offset:37888
	ds_read_b128 v[196:199], v127 offset:38912
	ds_read_b128 v[200:203], v127 offset:39936
	s_addc_u32 s69, s17, 0
	s_nop 0
	global_load_lds_dwordx4 v122, s[68:69]
	s_mov_b32 m0, s48
	s_nop 0
	global_load_lds_dwordx4 v123, s[68:69]
	s_waitcnt vmcnt(8) lgkmcnt(0)
	s_setprio 1
	s_barrier
	v_mfma_f32_16x16x32_bf16 v[136:139], v[128:131], v[172:175], v[138:141]
	v_mfma_f32_16x16x32_bf16 v[132:135], v[146:149], v[172:175], v[132:135]
	v_mfma_f32_16x16x32_bf16 v[110:113], v[128:131], v[180:183], v[110:113]
	v_mfma_f32_16x16x32_bf16 v[106:109], v[146:149], v[180:183], v[106:109]
	v_mfma_f32_16x16x32_bf16 v[94:97], v[128:131], v[188:191], v[94:97]
	v_mfma_f32_16x16x32_bf16 v[90:93], v[146:149], v[188:191], v[90:93]
	v_mfma_f32_16x16x32_bf16 v[78:81], v[128:131], v[196:199], v[78:81]
	v_mfma_f32_16x16x32_bf16 v[74:77], v[146:149], v[196:199], v[74:77]
	v_mfma_f32_16x16x32_bf16 v[138:141], v[142:145], v[176:179], v[136:139]
	v_mfma_f32_16x16x32_bf16 v[134:137], v[150:153], v[176:179], v[132:135]
	v_mfma_f32_16x16x32_bf16 v[110:113], v[142:145], v[184:187], v[110:113]
	v_mfma_f32_16x16x32_bf16 v[106:109], v[150:153], v[184:187], v[106:109]
	v_mfma_f32_16x16x32_bf16 v[94:97], v[142:145], v[192:195], v[94:97]
	v_mfma_f32_16x16x32_bf16 v[90:93], v[150:153], v[192:195], v[90:93]
	v_mfma_f32_16x16x32_bf16 v[78:81], v[142:145], v[200:203], v[78:81]
	v_mfma_f32_16x16x32_bf16 v[74:77], v[150:153], v[200:203], v[74:77]
	s_setprio 0
	s_setprio 1
	v_mfma_f32_16x16x32_bf16 v[118:121], v[154:157], v[172:175], v[118:121]
	v_mfma_f32_16x16x32_bf16 v[114:117], v[164:167], v[172:175], v[114:117]
	v_mfma_f32_16x16x32_bf16 v[102:105], v[154:157], v[180:183], v[102:105]
	v_mfma_f32_16x16x32_bf16 v[98:101], v[164:167], v[180:183], v[98:101]
	v_mfma_f32_16x16x32_bf16 v[86:89], v[154:157], v[188:191], v[86:89]
	v_mfma_f32_16x16x32_bf16 v[82:85], v[164:167], v[188:191], v[82:85]
	v_mfma_f32_16x16x32_bf16 v[70:73], v[154:157], v[196:199], v[70:73]
	v_mfma_f32_16x16x32_bf16 v[66:69], v[164:167], v[196:199], v[66:69]
	v_mfma_f32_16x16x32_bf16 v[118:121], v[160:163], v[176:179], v[118:121]
	v_mfma_f32_16x16x32_bf16 v[114:117], v[168:171], v[176:179], v[114:117]
	v_mfma_f32_16x16x32_bf16 v[102:105], v[160:163], v[184:187], v[102:105]
	v_mfma_f32_16x16x32_bf16 v[98:101], v[168:171], v[184:187], v[98:101]
	v_mfma_f32_16x16x32_bf16 v[86:89], v[160:163], v[192:195], v[86:89]
	v_mfma_f32_16x16x32_bf16 v[82:85], v[168:171], v[192:195], v[82:85]
	v_mfma_f32_16x16x32_bf16 v[70:73], v[160:163], v[200:203], v[70:73]
	v_mfma_f32_16x16x32_bf16 v[66:69], v[168:171], v[200:203], v[66:69]
	s_setprio 0
	s_barrier
	ds_read_b128 v[172:175], v127 offset:49152
	ds_read_b128 v[176:179], v127 offset:50176
	ds_read_b128 v[180:183], v127 offset:51200
	ds_read_b128 v[184:187], v127 offset:52224
	ds_read_b128 v[188:191], v127 offset:53248
	ds_read_b128 v[192:195], v127 offset:54272
	ds_read_b128 v[196:199], v127 offset:55296
	ds_read_b128 v[200:203], v127 offset:56320
	s_add_i32 s67, s67, s42
	s_add_u32 s100, s22, s38
	s_addc_u32 s101, s23, s39
	s_mov_b32 m0, s67
	s_nop 0
	global_load_lds_dwordx4 v124, s[100:101]
	s_add_i32 m0, s67, 0x2000
	s_nop 0
	s_add_u32 s22, s22, 0x40080
	s_addc_u32 s23, s23, 0
	s_add_i32 s67, s70, s42
	global_load_lds_dwordx4 v125, s[100:101]
	s_mov_b32 m0, s67
	s_nop 0
	global_load_lds_dwordx4 v124, s[22:23]
	s_add_i32 m0, s67, 0x2000
	s_nop 0
	global_load_lds_dwordx4 v125, s[22:23]
	s_mov_b32 m0, s64
	s_add_u32 s100, s16, s38
	s_addc_u32 s101, s17, s39
	v_mov_b32_e32 v0, v123
	global_load_lds_dwordx4 v122, s[100:101]
	s_mov_b32 m0, s65
	s_nop 0
	global_load_lds_dwordx4 v123, s[100:101]
	s_waitcnt vmcnt(8) lgkmcnt(0)
	s_setprio 1
	s_barrier
	v_mfma_f32_16x16x32_bf16 v[62:65], v[128:131], v[172:175], v[62:65]
	v_mfma_f32_16x16x32_bf16 v[58:61], v[146:149], v[172:175], v[58:61]
	v_mfma_f32_16x16x32_bf16 v[46:49], v[128:131], v[180:183], v[46:49]
	v_mfma_f32_16x16x32_bf16 v[42:45], v[146:149], v[180:183], v[42:45]
	v_mfma_f32_16x16x32_bf16 v[30:33], v[128:131], v[188:191], v[30:33]
	v_mfma_f32_16x16x32_bf16 v[26:29], v[146:149], v[188:191], v[26:29]
	v_mfma_f32_16x16x32_bf16 v[14:17], v[128:131], v[196:199], v[14:17]
	v_mfma_f32_16x16x32_bf16 v[10:13], v[146:149], v[196:199], v[10:13]
	v_mfma_f32_16x16x32_bf16 v[62:65], v[142:145], v[176:179], v[62:65]
	v_mfma_f32_16x16x32_bf16 v[58:61], v[150:153], v[176:179], v[58:61]
	v_mfma_f32_16x16x32_bf16 v[46:49], v[142:145], v[184:187], v[46:49]
	v_mfma_f32_16x16x32_bf16 v[42:45], v[150:153], v[184:187], v[42:45]
	v_mfma_f32_16x16x32_bf16 v[30:33], v[142:145], v[192:195], v[30:33]
	v_mfma_f32_16x16x32_bf16 v[26:29], v[150:153], v[192:195], v[26:29]
	v_mfma_f32_16x16x32_bf16 v[14:17], v[142:145], v[200:203], v[14:17]
	v_mfma_f32_16x16x32_bf16 v[10:13], v[150:153], v[200:203], v[10:13]
	s_setprio 0
	s_setprio 1
	v_mfma_f32_16x16x32_bf16 v[54:57], v[154:157], v[172:175], v[54:57]
	v_mfma_f32_16x16x32_bf16 v[50:53], v[164:167], v[172:175], v[50:53]
	v_mfma_f32_16x16x32_bf16 v[38:41], v[154:157], v[180:183], v[38:41]
	v_mfma_f32_16x16x32_bf16 v[34:37], v[164:167], v[180:183], v[34:37]
	v_mfma_f32_16x16x32_bf16 v[22:25], v[154:157], v[188:191], v[22:25]
	v_mfma_f32_16x16x32_bf16 v[18:21], v[164:167], v[188:191], v[18:21]
	v_mfma_f32_16x16x32_bf16 v[6:9], v[154:157], v[196:199], v[6:9]
	v_mfma_f32_16x16x32_bf16 v[2:5], v[164:167], v[196:199], v[2:5]
	v_mfma_f32_16x16x32_bf16 v[54:57], v[160:163], v[176:179], v[54:57]
	v_mfma_f32_16x16x32_bf16 v[50:53], v[168:171], v[176:179], v[50:53]
	v_mfma_f32_16x16x32_bf16 v[38:41], v[160:163], v[184:187], v[38:41]
	v_mfma_f32_16x16x32_bf16 v[34:37], v[168:171], v[184:187], v[34:37]
	v_mfma_f32_16x16x32_bf16 v[22:25], v[160:163], v[192:195], v[22:25]
	v_mfma_f32_16x16x32_bf16 v[18:21], v[168:171], v[192:195], v[18:21]
	v_mfma_f32_16x16x32_bf16 v[6:9], v[160:163], v[200:203], v[6:9]
	v_mfma_f32_16x16x32_bf16 v[2:5], v[168:171], v[200:203], v[2:5]
	s_setprio 0
	s_barrier
	s_add_i32 s66, s66, 2
	s_add_u32 s14, s14, 0x100
	s_addc_u32 s15, s15, 0
	s_cmp_gt_u32 s66, 13
	s_cbranch_scc0 .LBB0_1807

.LBB0_1886:
	s_add_u32 s6, s4, 0xfffc0080
	s_addc_u32 s7, s5, -1
	s_add_i32 s47, 0, 0x10000
	s_cmp_eq_u32 s46, 12
	s_cselect_b32 s7, s3, s7
	s_cselect_b32 s6, s2, s6
	v_add_u32_e32 v0, s47, v127
	s_cselect_b32 s11, s40, s43
	s_cselect_b32 s10, s26, s37
	s_add_i32 s50, 0, 0x14000
	ds_read_b128 v[130:133], v0
	ds_read_b128 v[134:137], v0 offset:1024
	ds_read_b128 v[138:141], v0 offset:2048
	ds_read_b128 v[142:145], v0 offset:3072
	ds_read_b128 v[146:149], v0 offset:16384
	ds_read_b128 v[158:161], v0 offset:17408
	ds_read_b128 v[162:165], v0 offset:18432
	ds_read_b128 v[166:169], v0 offset:19456
	ds_read_b128 v[170:173], v128
	ds_read_b128 v[174:177], v128 offset:1024
	ds_read_b128 v[178:181], v128 offset:2048
	ds_read_b128 v[182:185], v128 offset:3072
	ds_read_b128 v[186:189], v128 offset:4096
	ds_read_b128 v[190:193], v128 offset:5120
	ds_read_b128 v[194:197], v128 offset:6144
	ds_read_b128 v[198:201], v128 offset:7168
	s_add_i32 m0, s17, 0xc000
	s_nop 0
	global_load_lds_dwordx4 v122, s[4:5]
	s_add_i32 m0, s17, 0xe000
	s_nop 0
	global_load_lds_dwordx4 v123, s[4:5]
	s_waitcnt vmcnt(8) lgkmcnt(0)
	s_setprio 1
	s_barrier
	v_mfma_f32_16x16x32_bf16 v[154:157], v[130:133], v[170:173], v[154:157]
	v_mfma_f32_16x16x32_bf16 v[150:153], v[138:141], v[170:173], v[150:153]
	v_mfma_f32_16x16x32_bf16 v[110:113], v[130:133], v[178:181], v[110:113]
	v_mfma_f32_16x16x32_bf16 v[106:109], v[138:141], v[178:181], v[106:109]
	v_mfma_f32_16x16x32_bf16 v[94:97], v[130:133], v[186:189], v[94:97]
	v_mfma_f32_16x16x32_bf16 v[90:93], v[138:141], v[186:189], v[90:93]
	v_mfma_f32_16x16x32_bf16 v[78:81], v[130:133], v[194:197], v[78:81]
	v_mfma_f32_16x16x32_bf16 v[74:77], v[138:141], v[194:197], v[74:77]
	v_mfma_f32_16x16x32_bf16 v[154:157], v[134:137], v[174:177], v[154:157]
	v_mfma_f32_16x16x32_bf16 v[150:153], v[142:145], v[174:177], v[150:153]
	v_mfma_f32_16x16x32_bf16 v[110:113], v[134:137], v[182:185], v[110:113]
	v_mfma_f32_16x16x32_bf16 v[106:109], v[142:145], v[182:185], v[106:109]
	v_mfma_f32_16x16x32_bf16 v[94:97], v[134:137], v[190:193], v[94:97]
	v_mfma_f32_16x16x32_bf16 v[90:93], v[142:145], v[190:193], v[90:93]
	v_mfma_f32_16x16x32_bf16 v[78:81], v[134:137], v[198:201], v[78:81]
	v_mfma_f32_16x16x32_bf16 v[74:77], v[142:145], v[198:201], v[74:77]
	s_setprio 0
	s_setprio 1
	v_mfma_f32_16x16x32_bf16 v[118:121], v[146:149], v[170:173], v[118:121]
	v_mfma_f32_16x16x32_bf16 v[114:117], v[162:165], v[170:173], v[114:117]
	v_mfma_f32_16x16x32_bf16 v[102:105], v[146:149], v[178:181], v[102:105]
	v_mfma_f32_16x16x32_bf16 v[98:101], v[162:165], v[178:181], v[98:101]
	v_mfma_f32_16x16x32_bf16 v[86:89], v[146:149], v[186:189], v[86:89]
	v_mfma_f32_16x16x32_bf16 v[82:85], v[162:165], v[186:189], v[82:85]
	v_mfma_f32_16x16x32_bf16 v[70:73], v[146:149], v[194:197], v[70:73]
	v_mfma_f32_16x16x32_bf16 v[66:69], v[162:165], v[194:197], v[66:69]
	v_mfma_f32_16x16x32_bf16 v[118:121], v[158:161], v[174:177], v[118:121]
	v_mfma_f32_16x16x32_bf16 v[114:117], v[166:169], v[174:177], v[114:117]
	v_mfma_f32_16x16x32_bf16 v[102:105], v[158:161], v[182:185], v[102:105]
	v_mfma_f32_16x16x32_bf16 v[98:101], v[166:169], v[182:185], v[98:101]
	v_mfma_f32_16x16x32_bf16 v[86:89], v[158:161], v[190:193], v[86:89]
	v_mfma_f32_16x16x32_bf16 v[82:85], v[166:169], v[190:193], v[82:85]
	v_mfma_f32_16x16x32_bf16 v[70:73], v[158:161], v[198:201], v[70:73]
	v_mfma_f32_16x16x32_bf16 v[66:69], v[166:169], v[198:201], v[66:69]
	s_setprio 0
	s_barrier
	s_add_i32 s47, s47, s16
	ds_read_b128 v[170:173], v128 offset:16384
	ds_read_b128 v[174:177], v128 offset:17408
	ds_read_b128 v[178:181], v128 offset:18432
	ds_read_b128 v[182:185], v128 offset:19456
	ds_read_b128 v[186:189], v128 offset:20480
	ds_read_b128 v[190:193], v128 offset:21504
	ds_read_b128 v[194:197], v128 offset:22528
	ds_read_b128 v[198:201], v128 offset:23552
	s_mov_b32 m0, s47
	s_nop 0
	global_load_lds_dwordx4 v125, s[10:11]
	s_add_i32 m0, s47, 0x2000
	s_add_u32 s48, s10, 0x40000
	global_load_lds_dwordx4 v126, s[10:11]
	s_addc_u32 s49, s11, 0
	s_add_i32 s47, s50, s16
	s_mov_b32 m0, s47
	s_nop 0
	global_load_lds_dwordx4 v125, s[48:49]
	s_add_i32 m0, s47, 0x2000
	s_nop 0
	global_load_lds_dwordx4 v126, s[48:49]
	s_mov_b32 m0, s17
	s_nop 0
	global_load_lds_dwordx4 v122, s[6:7]
	s_mov_b32 m0, s22
	s_nop 0
	global_load_lds_dwordx4 v123, s[6:7]
	s_waitcnt vmcnt(8) lgkmcnt(0)
	s_setprio 1
	s_barrier
	v_mfma_f32_16x16x32_bf16 v[62:65], v[130:133], v[170:173], v[62:65]
	v_mfma_f32_16x16x32_bf16 v[58:61], v[138:141], v[170:173], v[58:61]
	v_mfma_f32_16x16x32_bf16 v[46:49], v[130:133], v[178:181], v[46:49]
	v_mfma_f32_16x16x32_bf16 v[42:45], v[138:141], v[178:181], v[42:45]
	v_mfma_f32_16x16x32_bf16 v[30:33], v[130:133], v[186:189], v[30:33]
	v_mfma_f32_16x16x32_bf16 v[26:29], v[138:141], v[186:189], v[26:29]
	v_mfma_f32_16x16x32_bf16 v[14:17], v[130:133], v[194:197], v[14:17]
	v_mfma_f32_16x16x32_bf16 v[10:13], v[138:141], v[194:197], v[10:13]
	v_mfma_f32_16x16x32_bf16 v[62:65], v[134:137], v[174:177], v[62:65]
	v_mfma_f32_16x16x32_bf16 v[58:61], v[142:145], v[174:177], v[58:61]
	v_mfma_f32_16x16x32_bf16 v[46:49], v[134:137], v[182:185], v[46:49]
	v_mfma_f32_16x16x32_bf16 v[42:45], v[142:145], v[182:185], v[42:45]
	v_mfma_f32_16x16x32_bf16 v[30:33], v[134:137], v[190:193], v[30:33]
	v_mfma_f32_16x16x32_bf16 v[26:29], v[142:145], v[190:193], v[26:29]
	v_mfma_f32_16x16x32_bf16 v[14:17], v[134:137], v[198:201], v[14:17]
	v_mfma_f32_16x16x32_bf16 v[10:13], v[142:145], v[198:201], v[10:13]
	s_setprio 0
	s_setprio 1
	v_mfma_f32_16x16x32_bf16 v[54:57], v[146:149], v[170:173], v[54:57]
	v_mfma_f32_16x16x32_bf16 v[50:53], v[162:165], v[170:173], v[50:53]
	v_mfma_f32_16x16x32_bf16 v[38:41], v[146:149], v[178:181], v[38:41]
	v_mfma_f32_16x16x32_bf16 v[34:37], v[162:165], v[178:181], v[34:37]
	v_mfma_f32_16x16x32_bf16 v[22:25], v[146:149], v[186:189], v[22:25]
	v_mfma_f32_16x16x32_bf16 v[18:21], v[162:165], v[186:189], v[18:21]
	v_mfma_f32_16x16x32_bf16 v[6:9], v[146:149], v[194:197], v[6:9]
	v_mfma_f32_16x16x32_bf16 v[2:5], v[162:165], v[194:197], v[2:5]
	v_mfma_f32_16x16x32_bf16 v[54:57], v[158:161], v[174:177], v[54:57]
	v_mfma_f32_16x16x32_bf16 v[50:53], v[166:169], v[174:177], v[50:53]
	v_mfma_f32_16x16x32_bf16 v[38:41], v[158:161], v[182:185], v[38:41]
	v_mfma_f32_16x16x32_bf16 v[34:37], v[166:169], v[182:185], v[34:37]
	v_mfma_f32_16x16x32_bf16 v[22:25], v[158:161], v[190:193], v[22:25]
	v_mfma_f32_16x16x32_bf16 v[18:21], v[166:169], v[190:193], v[18:21]
	v_mfma_f32_16x16x32_bf16 v[6:9], v[158:161], v[198:201], v[6:9]
	v_mfma_f32_16x16x32_bf16 v[2:5], v[166:169], v[198:201], v[2:5]
	s_setprio 0
	s_barrier
	s_add_i32 s47, 0, 0x18000
	s_add_i32 s50, 0, 0x1c000
	ds_read_b128 v[130:133], v0 offset:32768
	ds_read_b128 v[134:137], v0 offset:33792
	ds_read_b128 v[138:141], v0 offset:34816
	ds_read_b128 v[142:145], v0 offset:35840
	ds_read_b128 v[146:149], v0 offset:49152
	ds_read_b128 v[158:161], v0 offset:50176
	ds_read_b128 v[162:165], v0 offset:51200
	ds_read_b128 v[166:169], v0 offset:52224
	s_add_u32 s48, s6, 0x40000
	s_mov_b32 m0, s23
	ds_read_b128 v[170:173], v128 offset:32768
	ds_read_b128 v[174:177], v128 offset:33792
	ds_read_b128 v[178:181], v128 offset:34816
	ds_read_b128 v[182:185], v128 offset:35840
	ds_read_b128 v[186:189], v128 offset:36864
	ds_read_b128 v[190:193], v128 offset:37888
	ds_read_b128 v[194:197], v128 offset:38912
	ds_read_b128 v[198:201], v128 offset:39936
	s_addc_u32 s49, s7, 0
	s_nop 0
	global_load_lds_dwordx4 v122, s[48:49]
	s_mov_b32 m0, s24
	s_nop 0
	global_load_lds_dwordx4 v123, s[48:49]
	s_waitcnt vmcnt(8) lgkmcnt(0)
	s_setprio 1
	s_barrier
	v_mfma_f32_16x16x32_bf16 v[154:157], v[130:133], v[170:173], v[154:157]
	v_mfma_f32_16x16x32_bf16 v[150:153], v[138:141], v[170:173], v[150:153]
	v_mfma_f32_16x16x32_bf16 v[110:113], v[130:133], v[178:181], v[110:113]
	v_mfma_f32_16x16x32_bf16 v[106:109], v[138:141], v[178:181], v[106:109]
	v_mfma_f32_16x16x32_bf16 v[94:97], v[130:133], v[186:189], v[94:97]
	v_mfma_f32_16x16x32_bf16 v[90:93], v[138:141], v[186:189], v[90:93]
	v_mfma_f32_16x16x32_bf16 v[78:81], v[130:133], v[194:197], v[78:81]
	v_mfma_f32_16x16x32_bf16 v[74:77], v[138:141], v[194:197], v[74:77]
	v_mfma_f32_16x16x32_bf16 v[154:157], v[134:137], v[174:177], v[154:157]
	v_mfma_f32_16x16x32_bf16 v[150:153], v[142:145], v[174:177], v[150:153]
	v_mfma_f32_16x16x32_bf16 v[110:113], v[134:137], v[182:185], v[110:113]
	v_mfma_f32_16x16x32_bf16 v[106:109], v[142:145], v[182:185], v[106:109]
	v_mfma_f32_16x16x32_bf16 v[94:97], v[134:137], v[190:193], v[94:97]
	v_mfma_f32_16x16x32_bf16 v[90:93], v[142:145], v[190:193], v[90:93]
	v_mfma_f32_16x16x32_bf16 v[78:81], v[134:137], v[198:201], v[78:81]
	v_mfma_f32_16x16x32_bf16 v[74:77], v[142:145], v[198:201], v[74:77]
	s_setprio 0
	s_setprio 1
	v_mfma_f32_16x16x32_bf16 v[118:121], v[146:149], v[170:173], v[118:121]
	v_mfma_f32_16x16x32_bf16 v[114:117], v[162:165], v[170:173], v[114:117]
	v_mfma_f32_16x16x32_bf16 v[102:105], v[146:149], v[178:181], v[102:105]
	v_mfma_f32_16x16x32_bf16 v[98:101], v[162:165], v[178:181], v[98:101]
	v_mfma_f32_16x16x32_bf16 v[86:89], v[146:149], v[186:189], v[86:89]
	v_mfma_f32_16x16x32_bf16 v[82:85], v[162:165], v[186:189], v[82:85]
	v_mfma_f32_16x16x32_bf16 v[70:73], v[146:149], v[194:197], v[70:73]
	v_mfma_f32_16x16x32_bf16 v[66:69], v[162:165], v[194:197], v[66:69]
	v_mfma_f32_16x16x32_bf16 v[118:121], v[158:161], v[174:177], v[118:121]
	v_mfma_f32_16x16x32_bf16 v[114:117], v[166:169], v[174:177], v[114:117]
	v_mfma_f32_16x16x32_bf16 v[102:105], v[158:161], v[182:185], v[102:105]
	v_mfma_f32_16x16x32_bf16 v[98:101], v[166:169], v[182:185], v[98:101]
	v_mfma_f32_16x16x32_bf16 v[86:89], v[158:161], v[190:193], v[86:89]
	v_mfma_f32_16x16x32_bf16 v[82:85], v[166:169], v[190:193], v[82:85]
	v_mfma_f32_16x16x32_bf16 v[70:73], v[158:161], v[198:201], v[70:73]
	v_mfma_f32_16x16x32_bf16 v[66:69], v[166:169], v[198:201], v[66:69]
	s_setprio 0
	s_barrier
	ds_read_b128 v[170:173], v128 offset:49152
	ds_read_b128 v[174:177], v128 offset:50176
	ds_read_b128 v[178:181], v128 offset:51200
	ds_read_b128 v[182:185], v128 offset:52224
	ds_read_b128 v[186:189], v128 offset:53248
	ds_read_b128 v[190:193], v128 offset:54272
	ds_read_b128 v[194:197], v128 offset:55296
	ds_read_b128 v[198:201], v128 offset:56320
	s_add_i32 s47, s47, s16
	s_add_u32 s100, s10, s38
	s_addc_u32 s101, s11, s39
	s_mov_b32 m0, s47
	s_nop 0
	global_load_lds_dwordx4 v125, s[100:101]
	s_add_i32 m0, s47, 0x2000
	s_nop 0
	s_add_u32 s10, s10, 0x40080
	s_addc_u32 s11, s11, 0
	s_add_i32 s47, s50, s16
	global_load_lds_dwordx4 v126, s[100:101]
	s_mov_b32 m0, s47
	s_nop 0
	global_load_lds_dwordx4 v125, s[10:11]
	s_add_i32 m0, s47, 0x2000
	s_nop 0
	global_load_lds_dwordx4 v126, s[10:11]
	s_mov_b32 m0, s41
	s_add_u32 s100, s6, s38
	s_addc_u32 s101, s7, s39
	v_mov_b32_e32 v0, v123
	global_load_lds_dwordx4 v122, s[100:101]
	s_mov_b32 m0, s42
	s_nop 0
	global_load_lds_dwordx4 v123, s[100:101]
	s_waitcnt vmcnt(8) lgkmcnt(0)
	s_setprio 1
	s_barrier
	v_mfma_f32_16x16x32_bf16 v[62:65], v[130:133], v[170:173], v[62:65]
	v_mfma_f32_16x16x32_bf16 v[58:61], v[138:141], v[170:173], v[58:61]
	v_mfma_f32_16x16x32_bf16 v[46:49], v[130:133], v[178:181], v[46:49]
	v_mfma_f32_16x16x32_bf16 v[42:45], v[138:141], v[178:181], v[42:45]
	v_mfma_f32_16x16x32_bf16 v[30:33], v[130:133], v[186:189], v[30:33]
	v_mfma_f32_16x16x32_bf16 v[26:29], v[138:141], v[186:189], v[26:29]
	v_mfma_f32_16x16x32_bf16 v[14:17], v[130:133], v[194:197], v[14:17]
	v_mfma_f32_16x16x32_bf16 v[10:13], v[138:141], v[194:197], v[10:13]
	v_mfma_f32_16x16x32_bf16 v[62:65], v[134:137], v[174:177], v[62:65]
	v_mfma_f32_16x16x32_bf16 v[58:61], v[142:145], v[174:177], v[58:61]
	v_mfma_f32_16x16x32_bf16 v[46:49], v[134:137], v[182:185], v[46:49]
	v_mfma_f32_16x16x32_bf16 v[42:45], v[142:145], v[182:185], v[42:45]
	v_mfma_f32_16x16x32_bf16 v[30:33], v[134:137], v[190:193], v[30:33]
	v_mfma_f32_16x16x32_bf16 v[26:29], v[142:145], v[190:193], v[26:29]
	v_mfma_f32_16x16x32_bf16 v[14:17], v[134:137], v[198:201], v[14:17]
	v_mfma_f32_16x16x32_bf16 v[10:13], v[142:145], v[198:201], v[10:13]
	s_setprio 0
	s_setprio 1
	v_mfma_f32_16x16x32_bf16 v[54:57], v[146:149], v[170:173], v[54:57]
	v_mfma_f32_16x16x32_bf16 v[50:53], v[162:165], v[170:173], v[50:53]
	v_mfma_f32_16x16x32_bf16 v[38:41], v[146:149], v[178:181], v[38:41]
	v_mfma_f32_16x16x32_bf16 v[34:37], v[162:165], v[178:181], v[34:37]
	v_mfma_f32_16x16x32_bf16 v[22:25], v[146:149], v[186:189], v[22:25]
	v_mfma_f32_16x16x32_bf16 v[18:21], v[162:165], v[186:189], v[18:21]
	v_mfma_f32_16x16x32_bf16 v[6:9], v[146:149], v[194:197], v[6:9]
	v_mfma_f32_16x16x32_bf16 v[2:5], v[162:165], v[194:197], v[2:5]
	v_mfma_f32_16x16x32_bf16 v[54:57], v[158:161], v[174:177], v[54:57]
	v_mfma_f32_16x16x32_bf16 v[50:53], v[166:169], v[174:177], v[50:53]
	v_mfma_f32_16x16x32_bf16 v[38:41], v[158:161], v[182:185], v[38:41]
	v_mfma_f32_16x16x32_bf16 v[34:37], v[166:169], v[182:185], v[34:37]
	v_mfma_f32_16x16x32_bf16 v[22:25], v[158:161], v[190:193], v[22:25]
	v_mfma_f32_16x16x32_bf16 v[18:21], v[166:169], v[190:193], v[18:21]
	v_mfma_f32_16x16x32_bf16 v[6:9], v[158:161], v[198:201], v[6:9]
	v_mfma_f32_16x16x32_bf16 v[2:5], v[166:169], v[198:201], v[2:5]
	s_setprio 0
	s_barrier
	s_add_i32 s46, s46, 2
	s_add_u32 s4, s4, 0x100
	s_addc_u32 s5, s5, 0
	s_add_u32 s37, s37, 0x100
	s_addc_u32 s43, s43, 0
	s_cmp_gt_u32 s46, 13
	s_cbranch_scc0 .LBB0_1886
	s_cmpk_lt_u32 s14, 0x100
	s_cbranch_scc0 .LBB0_1889
	s_barrier
